# GEMM K-loops: per-segment s_setprio flips deleted, one static s_setprio 1 for waves 4-7 per GEMM, reset at grid barriers
# baseline (speedup 1.0000x reference)
.LBB0_137:
	s_andn2_b64 vcc, exec, s[4:5]
	v_readlane_b32 s4, v252, 6
	s_mul_i32 s64, s4, 0x720
	s_cbranch_vccnz .LBB0_336
	v_bfe_i32 v3, v14, 27, 1
	v_lshlrev_b32_e32 v2, 4, v14
	v_lshrrev_b32_e32 v3, 22, v3
	v_add_u32_e32 v3, v2, v3
	v_and_b32_e32 v3, 0xfffffc00, v3
	v_sub_u32_e32 v3, v2, v3
	v_ashrrev_i32_e32 v0, 31, v14
	v_lshrrev_b32_e32 v4, 4, v3
	v_lshrrev_b32_e32 v0, 26, v0
	v_bitop3_b32 v3, v4, v3, 32 bitop3:0x6c
	v_add_u32_e32 v0, v14, v0
	v_ashrrev_i32_e32 v5, 31, v3
	v_ashrrev_i32_e32 v0, 6, v0
	v_lshrrev_b32_e32 v5, 26, v5
	v_lshlrev_b32_e32 v4, 3, v0
	v_add_u32_e32 v5, v3, v5
	v_and_b32_e32 v4, -16, v4
	v_ashrrev_i32_e32 v6, 6, v5
	v_lshlrev_b32_e32 v0, 5, v0
	s_add_u32 s16, s6, 0x4bf0000
	v_add_u32_e32 v4, v6, v4
	v_and_b32_e32 v15, 32, v0
	v_and_b32_e32 v0, 0xc0, v5
	s_addc_u32 s28, s1, 0
	v_sub_u32_e32 v0, v3, v0
	v_lshlrev_b32_e32 v3, 1, v4
	v_lshrrev_b32_e32 v5, 2, v4
	v_and_b32_e32 v6, 3, v6
	s_mov_b32 s1, 0x7fffffe0
	v_ashrrev_i16_sdwa v0, v201, sext(v0) dst_sel:DWORD dst_unused:UNUSED_PAD src0_sel:DWORD src1_sel:BYTE_0
	v_and_b32_e32 v3, 24, v3
	v_and_b32_e32 v5, 4, v5
	v_and_or_b32 v6, v4, s1, v6
	v_bfe_i32 v16, v0, 0, 16
	v_or3_b32 v3, v6, v5, v3
	v_add_u32_e32 v0, v15, v16
	v_mul_lo_u32 v17, v4, s2
	v_mul_lo_u32 v3, v3, s0
	v_add_u32_e32 v2, 0x2000, v2
	v_add_lshl_u32 v154, v0, v17, 1
	v_add_lshl_u32 v0, v3, v0, 1
	v_ashrrev_i32_e32 v3, 31, v2
	v_lshrrev_b32_e32 v3, 22, v3
	v_add_u32_e32 v3, v2, v3
	v_ashrrev_i32_e32 v3, 10, v3
	v_mul_i32_i24_e32 v4, 0x400, v3
	v_sub_u32_e32 v2, v2, v4
	v_lshrrev_b32_e32 v4, 4, v2
	v_bitop3_b32 v2, v4, v2, 32 bitop3:0x6c
	v_ashrrev_i32_e32 v5, 31, v2
	v_lshrrev_b32_e32 v5, 26, v5
	v_writelane_b32 v252, s50, 18
	s_add_u32 s29, s7, 0xa10000
	v_lshlrev_b32_e32 v4, 3, v3
	v_add_u32_e32 v5, v2, v5
	v_writelane_b32 v252, s51, 19
	s_addc_u32 s50, s3, 0
	v_and_b32_e32 v4, -16, v4
	v_ashrrev_i32_e32 v6, 6, v5
	s_ashr_i32 s3, s2, 31
	v_add_u32_e32 v4, v6, v4
	s_lshl_b64 s[22:23], s[2:3], 9
	s_ashr_i32 s4, s27, 31
	v_and_b32_e32 v6, 3, v6
	v_mul_lo_u32 v20, v4, s2
	s_lshl_b64 s[18:19], s[2:3], 8
	s_mul_i32 s4, s22, s4
	s_mul_hi_u32 s5, s22, s27
	s_lshr_b64 s[2:3], s[2:3], 23
	v_and_or_b32 v6, v4, s1, v6
	s_ashr_i32 s1, s0, 31
	s_add_i32 s4, s5, s4
	s_mul_i32 s2, s2, s27
	s_lshl_b64 s[24:25], s[0:1], 9
	s_add_i32 s7, s4, s2
	s_ashr_i32 s2, s8, 31
	s_mul_i32 s2, s24, s2
	s_mul_hi_u32 s3, s24, s8
	s_add_i32 s4, s3, s2
	s_lshr_b64 s[2:3], s[0:1], 23
	s_ashr_i32 s15, s13, 6
	s_mul_i32 s2, s2, s8
	s_ashr_i32 s44, s13, 8
	s_lshl_b64 s[20:21], s[0:1], 8
	s_lshl_b32 s26, s15, 10
	s_add_i32 s2, s4, s2
	s_mul_i32 s3, s24, s8
	s_add_u32 s4, s29, s3
	s_addc_u32 s5, s50, s2
	s_add_i32 s53, s9, 0x10000
	v_lshlrev_b32_e32 v3, 5, v3
	s_add_i32 s55, s53, s26
	v_and_b32_e32 v18, 32, v3
	v_and_b32_e32 v3, 0xc0, v5
	s_add_i32 s88, s55, 0x2000
	v_sub_u32_e32 v2, v2, v3
	v_lshlrev_b32_e32 v3, 1, v4
	v_lshrrev_b32_e32 v5, 2, v4
	s_add_u32 s2, s4, s20
	v_ashrrev_i16_sdwa v2, v201, sext(v2) dst_sel:DWORD dst_unused:UNUSED_PAD src0_sel:DWORD src1_sel:BYTE_0
	v_and_b32_e32 v3, 24, v3
	v_and_b32_e32 v5, 4, v5
	s_addc_u32 s3, s5, s21
	s_add_i32 s90, s9, 0x14000
	v_bfe_i32 v19, v2, 0, 16
	v_or3_b32 v3, v6, v5, v3
	s_add_i32 s93, s90, s26
	v_add_u32_e32 v2, v18, v19
	v_mul_lo_u32 v3, v3, s0
	s_mul_i32 s6, s22, s27
	s_mov_b32 m0, s55
	s_add_i32 s94, s93, 0x2000
	v_add_lshl_u32 v158, v3, v2, 1
	global_load_lds_dwordx4 v0, s[4:5]
	s_mov_b32 m0, s88
	s_add_u32 s6, s16, s6
	v_writelane_b32 v252, s29, 20
	global_load_lds_dwordx4 v158, s[4:5]
	s_mov_b32 m0, s93
	s_addc_u32 s7, s28, s7
	s_add_i32 s96, s9, s26
	global_load_lds_dwordx4 v0, s[2:3]
	s_mov_b32 m0, s94
	v_writelane_b32 v252, s16, 21
	s_add_i32 s66, s96, 0x2000
	global_load_lds_dwordx4 v158, s[2:3]
	v_writelane_b32 v252, s28, 23
	s_mov_b32 m0, s96
	s_add_u32 s28, s6, s18
	v_add_lshl_u32 v156, v2, v20, 1
	global_load_lds_dwordx4 v154, s[6:7]
	s_mov_b32 m0, s66
	s_addc_u32 s29, s7, s19
	s_add_i32 s67, s96, 0x4000
	global_load_lds_dwordx4 v156, s[6:7]
	s_mov_b32 m0, s67
	s_add_i32 s47, s96, 0x6000
	global_load_lds_dwordx4 v154, s[28:29]
	s_mov_b32 m0, s47
	v_mov_b32_e32 v159, v1
	global_load_lds_dwordx4 v156, s[28:29]
	s_cmp_eq_u32 s44, 1
	v_lshl_add_u64 v[4:5], s[2:3], 0, v[0:1]
	v_lshl_add_u64 v[2:3], s[2:3], 0, v[158:159]
	v_mov_b32_e32 v155, v1
	v_mov_b32_e32 v157, v1
	s_cselect_b64 s[2:3], -1, 0
	s_mov_b32 s34, s64
	v_lshl_add_u64 v[10:11], s[4:5], 0, v[0:1]
	v_lshl_add_u64 v[6:7], s[4:5], 0, v[158:159]
	v_lshl_add_u64 v[8:9], s[6:7], 0, v[154:155]
	v_writelane_b32 v252, s2, 24
	s_cmp_lg_u32 s44, 1
	v_lshl_add_u64 v[12:13], s[6:7], 0, v[156:157]
	v_writelane_b32 v252, s3, 25
	s_cbranch_scc1 .LBB0_140
	s_barrier
	s_setprio 1

.LBB0_151:
	v_add_u32_e32 v14, s53, v189
	v_add_u32_e32 v168, s90, v189
	ds_read_b128 v[2:5], v14
	ds_read_b128 v[6:9], v14 offset:1024
	ds_read_b128 v[10:13], v14 offset:2048
	ds_read_b128 v[14:17], v14 offset:3072
	ds_read_b128 v[146:149], v168
	ds_read_b128 v[150:153], v168 offset:1024
	ds_read_b128 v[164:167], v168 offset:2048
	ds_read_b128 v[168:171], v168 offset:3072
	s_add_i32 s11, s6, 2
	s_add_u32 s15, s4, 0x80
	s_addc_u32 s7, s5, 0
	s_cmp_eq_u32 s46, s6
	s_cselect_b32 s6, s0, s15
	s_cselect_b32 s7, s1, s7
	s_cselect_b32 s73, s69, s10
	s_cselect_b32 s72, s68, s9
	v_lshl_add_u64 v[176:177], s[4:5], 0, v[162:163]
	s_add_i32 m0, s96, 0xc000
	ds_read_b128 v[172:175], v190
	ds_read_b128 v[182:185], v190 offset:1024
	ds_read_b128 v[192:195], v190 offset:2048
	ds_read_b128 v[196:199], v190 offset:3072
	ds_read_b128 v[218:221], v190 offset:4096
	ds_read_b128 v[222:225], v190 offset:5120
	ds_read_b128 v[230:233], v190 offset:6144
	ds_read_b128 v[234:237], v190 offset:7168
	global_load_lds_dwordx4 v[176:177], off
	v_lshl_add_u64 v[176:177], s[4:5], 0, v[160:161]
	s_add_i32 m0, s96, 0xe000
	s_nop 0
	global_load_lds_dwordx4 v[176:177], off
	s_waitcnt vmcnt(8)
	s_waitcnt lgkmcnt(0)
	s_barrier
	s_waitcnt lgkmcnt(0)
	v_mfma_f32_16x16x32_bf16 v[138:141], v[2:5], v[172:175], v[138:141]
	v_mfma_f32_16x16x32_bf16 v[142:145], v[10:13], v[172:175], v[142:145]
	v_mfma_f32_16x16x32_bf16 v[126:129], v[2:5], v[192:195], v[126:129]
	v_mfma_f32_16x16x32_bf16 v[122:125], v[10:13], v[192:195], v[122:125]
	v_mfma_f32_16x16x32_bf16 v[110:113], v[2:5], v[218:221], v[110:113]
	v_mfma_f32_16x16x32_bf16 v[106:109], v[10:13], v[218:221], v[106:109]
	v_mfma_f32_16x16x32_bf16 v[94:97], v[2:5], v[230:233], v[94:97]
	v_mfma_f32_16x16x32_bf16 v[90:93], v[10:13], v[230:233], v[90:93]
	v_mfma_f32_16x16x32_bf16 v[138:141], v[6:9], v[182:185], v[138:141]
	v_mfma_f32_16x16x32_bf16 v[142:145], v[14:17], v[182:185], v[142:145]
	v_mfma_f32_16x16x32_bf16 v[126:129], v[6:9], v[196:199], v[126:129]
	v_mfma_f32_16x16x32_bf16 v[122:125], v[14:17], v[196:199], v[122:125]
	v_mfma_f32_16x16x32_bf16 v[110:113], v[6:9], v[222:225], v[110:113]
	v_mfma_f32_16x16x32_bf16 v[106:109], v[14:17], v[222:225], v[106:109]
	v_mfma_f32_16x16x32_bf16 v[94:97], v[6:9], v[234:237], v[94:97]
	v_mfma_f32_16x16x32_bf16 v[90:93], v[14:17], v[234:237], v[90:93]
	v_mfma_f32_16x16x32_bf16 v[134:137], v[146:149], v[172:175], v[134:137]
	v_mfma_f32_16x16x32_bf16 v[130:133], v[164:167], v[172:175], v[130:133]
	v_mfma_f32_16x16x32_bf16 v[118:121], v[146:149], v[192:195], v[118:121]
	v_mfma_f32_16x16x32_bf16 v[114:117], v[164:167], v[192:195], v[114:117]
	v_mfma_f32_16x16x32_bf16 v[102:105], v[146:149], v[218:221], v[102:105]
	v_mfma_f32_16x16x32_bf16 v[98:101], v[164:167], v[218:221], v[98:101]
	v_mfma_f32_16x16x32_bf16 v[86:89], v[146:149], v[230:233], v[86:89]
	v_mfma_f32_16x16x32_bf16 v[82:85], v[164:167], v[230:233], v[82:85]
	v_mfma_f32_16x16x32_bf16 v[134:137], v[150:153], v[182:185], v[134:137]
	v_mfma_f32_16x16x32_bf16 v[130:133], v[168:171], v[182:185], v[130:133]
	v_mfma_f32_16x16x32_bf16 v[118:121], v[150:153], v[196:199], v[118:121]
	v_mfma_f32_16x16x32_bf16 v[114:117], v[168:171], v[196:199], v[114:117]
	v_mfma_f32_16x16x32_bf16 v[102:105], v[150:153], v[222:225], v[102:105]
	v_mfma_f32_16x16x32_bf16 v[98:101], v[168:171], v[222:225], v[98:101]
	v_mfma_f32_16x16x32_bf16 v[86:89], v[150:153], v[234:237], v[86:89]
	v_mfma_f32_16x16x32_bf16 v[82:85], v[168:171], v[234:237], v[82:85]
	s_barrier
	s_mov_b32 m0, s55
	v_lshl_add_u64 v[176:177], s[72:73], 0, v[0:1]
	v_lshl_add_u64 v[186:187], s[72:73], 0, v[158:159]
	s_add_u32 s72, s72, s20
	ds_read_b128 v[172:175], v190 offset:16384
	ds_read_b128 v[182:185], v190 offset:17408
	ds_read_b128 v[192:195], v190 offset:18432
	ds_read_b128 v[196:199], v190 offset:19456
	ds_read_b128 v[218:221], v190 offset:20480
	ds_read_b128 v[222:225], v190 offset:21504
	ds_read_b128 v[230:233], v190 offset:22528
	ds_read_b128 v[234:237], v190 offset:23552
	global_load_lds_dwordx4 v[176:177], off
	s_mov_b32 m0, s88
	s_addc_u32 s73, s73, s21
	global_load_lds_dwordx4 v[186:187], off
	v_lshl_add_u64 v[238:239], s[72:73], 0, v[0:1]
	s_mov_b32 m0, s93
	v_lshl_add_u64 v[240:241], s[72:73], 0, v[158:159]
	global_load_lds_dwordx4 v[238:239], off
	s_mov_b32 m0, s94
	v_lshl_add_u64 v[242:243], s[6:7], 0, v[154:155]
	global_load_lds_dwordx4 v[240:241], off
	s_mov_b32 m0, s96
	v_lshl_add_u64 v[244:245], s[6:7], 0, v[156:157]
	global_load_lds_dwordx4 v[242:243], off
	s_mov_b32 m0, s66
	s_nop 0
	global_load_lds_dwordx4 v[244:245], off
	s_waitcnt vmcnt(8)
	s_waitcnt lgkmcnt(0)
	s_barrier
	s_waitcnt lgkmcnt(0)
	v_mfma_f32_16x16x32_bf16 v[78:81], v[2:5], v[172:175], v[78:81]
	v_mfma_f32_16x16x32_bf16 v[74:77], v[10:13], v[172:175], v[74:77]
	v_mfma_f32_16x16x32_bf16 v[62:65], v[2:5], v[192:195], v[62:65]
	v_mfma_f32_16x16x32_bf16 v[58:61], v[10:13], v[192:195], v[58:61]
	v_mfma_f32_16x16x32_bf16 v[46:49], v[2:5], v[218:221], v[46:49]
	v_mfma_f32_16x16x32_bf16 v[42:45], v[10:13], v[218:221], v[42:45]
	v_mfma_f32_16x16x32_bf16 v[2:5], v[2:5], v[230:233], v[30:33]
	v_mfma_f32_16x16x32_bf16 v[78:81], v[6:9], v[182:185], v[78:81]
	v_mfma_f32_16x16x32_bf16 v[74:77], v[14:17], v[182:185], v[74:77]
	v_mfma_f32_16x16x32_bf16 v[62:65], v[6:9], v[196:199], v[62:65]
	v_mfma_f32_16x16x32_bf16 v[58:61], v[14:17], v[196:199], v[58:61]
	v_mfma_f32_16x16x32_bf16 v[46:49], v[6:9], v[222:225], v[46:49]
	v_mfma_f32_16x16x32_bf16 v[42:45], v[14:17], v[222:225], v[42:45]
	v_mfma_f32_16x16x32_bf16 v[2:5], v[6:9], v[234:237], v[2:5]
	v_mfma_f32_16x16x32_bf16 v[6:9], v[10:13], v[230:233], v[26:29]
	v_mfma_f32_16x16x32_bf16 v[6:9], v[14:17], v[234:237], v[6:9]
	v_mfma_f32_16x16x32_bf16 v[26:29], v[146:149], v[192:195], v[54:57]
	v_mfma_f32_16x16x32_bf16 v[54:57], v[150:153], v[196:199], v[26:29]
	v_mfma_f32_16x16x32_bf16 v[26:29], v[164:167], v[192:195], v[50:53]
	v_mfma_f32_16x16x32_bf16 v[50:53], v[168:171], v[196:199], v[26:29]
	v_mfma_f32_16x16x32_bf16 v[26:29], v[146:149], v[218:221], v[38:41]
	v_mfma_f32_16x16x32_bf16 v[38:41], v[150:153], v[222:225], v[26:29]
	v_mfma_f32_16x16x32_bf16 v[26:29], v[164:167], v[218:221], v[34:37]
	v_mfma_f32_16x16x32_bf16 v[22:25], v[146:149], v[230:233], v[22:25]
	v_mfma_f32_16x16x32_bf16 v[18:21], v[164:167], v[230:233], v[18:21]
	v_mfma_f32_16x16x32_bf16 v[10:13], v[146:149], v[172:175], v[70:73]
	v_mfma_f32_16x16x32_bf16 v[14:17], v[164:167], v[172:175], v[66:69]
	v_mfma_f32_16x16x32_bf16 v[34:37], v[168:171], v[222:225], v[26:29]
	v_mfma_f32_16x16x32_bf16 v[22:25], v[150:153], v[234:237], v[22:25]
	v_mfma_f32_16x16x32_bf16 v[18:21], v[168:171], v[234:237], v[18:21]
	v_mfma_f32_16x16x32_bf16 v[10:13], v[150:153], v[182:185], v[10:13]
	v_mfma_f32_16x16x32_bf16 v[14:17], v[168:171], v[182:185], v[14:17]
	s_barrier
	v_add_u32_e32 v70, s16, v189
	v_add_u32_e32 v168, s52, v189
	ds_read_b128 v[26:29], v70
	ds_read_b128 v[30:33], v70 offset:1024
	ds_read_b128 v[66:69], v70 offset:2048
	ds_read_b128 v[70:73], v70 offset:3072
	ds_read_b128 v[146:149], v168
	ds_read_b128 v[150:153], v168 offset:1024
	ds_read_b128 v[164:167], v168 offset:2048
	ds_read_b128 v[168:171], v168 offset:3072
	s_add_u32 s6, s6, s18
	s_addc_u32 s7, s7, s19
	s_mov_b32 m0, s67
	v_lshl_add_u64 v[246:247], s[6:7], 0, v[154:155]
	ds_read_b128 v[172:175], v190 offset:32768
	ds_read_b128 v[182:185], v190 offset:33792
	ds_read_b128 v[192:195], v190 offset:34816
	ds_read_b128 v[196:199], v190 offset:35840
	ds_read_b128 v[218:221], v190 offset:36864
	ds_read_b128 v[222:225], v190 offset:37888
	ds_read_b128 v[230:233], v190 offset:38912
	ds_read_b128 v[234:237], v190 offset:39936
	global_load_lds_dwordx4 v[246:247], off
	v_lshl_add_u64 v[246:247], s[6:7], 0, v[156:157]
	s_mov_b32 m0, s47
	s_nop 0
	global_load_lds_dwordx4 v[246:247], off
	s_waitcnt vmcnt(8)
	s_waitcnt lgkmcnt(0)
	s_barrier
	s_waitcnt lgkmcnt(0)
	v_mfma_f32_16x16x32_bf16 v[138:141], v[26:29], v[172:175], v[138:141]
	v_mfma_f32_16x16x32_bf16 v[142:145], v[66:69], v[172:175], v[142:145]
	v_mfma_f32_16x16x32_bf16 v[126:129], v[26:29], v[192:195], v[126:129]
	v_mfma_f32_16x16x32_bf16 v[122:125], v[66:69], v[192:195], v[122:125]
	v_mfma_f32_16x16x32_bf16 v[110:113], v[26:29], v[218:221], v[110:113]
	v_mfma_f32_16x16x32_bf16 v[106:109], v[66:69], v[218:221], v[106:109]
	v_mfma_f32_16x16x32_bf16 v[94:97], v[26:29], v[230:233], v[94:97]
	v_mfma_f32_16x16x32_bf16 v[90:93], v[66:69], v[230:233], v[90:93]
	v_mfma_f32_16x16x32_bf16 v[138:141], v[30:33], v[182:185], v[138:141]
	v_mfma_f32_16x16x32_bf16 v[142:145], v[70:73], v[182:185], v[142:145]
	v_mfma_f32_16x16x32_bf16 v[126:129], v[30:33], v[196:199], v[126:129]
	v_mfma_f32_16x16x32_bf16 v[122:125], v[70:73], v[196:199], v[122:125]
	v_mfma_f32_16x16x32_bf16 v[110:113], v[30:33], v[222:225], v[110:113]
	v_mfma_f32_16x16x32_bf16 v[106:109], v[70:73], v[222:225], v[106:109]
	v_mfma_f32_16x16x32_bf16 v[94:97], v[30:33], v[234:237], v[94:97]
	v_mfma_f32_16x16x32_bf16 v[90:93], v[70:73], v[234:237], v[90:93]
	v_mfma_f32_16x16x32_bf16 v[134:137], v[146:149], v[172:175], v[134:137]
	v_mfma_f32_16x16x32_bf16 v[130:133], v[164:167], v[172:175], v[130:133]
	v_mfma_f32_16x16x32_bf16 v[118:121], v[146:149], v[192:195], v[118:121]
	v_mfma_f32_16x16x32_bf16 v[114:117], v[164:167], v[192:195], v[114:117]
	v_mfma_f32_16x16x32_bf16 v[102:105], v[146:149], v[218:221], v[102:105]
	v_mfma_f32_16x16x32_bf16 v[98:101], v[164:167], v[218:221], v[98:101]
	v_mfma_f32_16x16x32_bf16 v[86:89], v[146:149], v[230:233], v[86:89]
	v_mfma_f32_16x16x32_bf16 v[82:85], v[164:167], v[230:233], v[82:85]
	v_mfma_f32_16x16x32_bf16 v[134:137], v[150:153], v[182:185], v[134:137]
	v_mfma_f32_16x16x32_bf16 v[130:133], v[168:171], v[182:185], v[130:133]
	v_mfma_f32_16x16x32_bf16 v[118:121], v[150:153], v[196:199], v[118:121]
	v_mfma_f32_16x16x32_bf16 v[114:117], v[168:171], v[196:199], v[114:117]
	v_mfma_f32_16x16x32_bf16 v[102:105], v[150:153], v[222:225], v[102:105]
	v_mfma_f32_16x16x32_bf16 v[98:101], v[168:171], v[222:225], v[98:101]
	v_mfma_f32_16x16x32_bf16 v[86:89], v[150:153], v[234:237], v[86:89]
	v_mfma_f32_16x16x32_bf16 v[82:85], v[168:171], v[234:237], v[82:85]
	s_barrier
	s_mov_b32 m0, s91
	v_lshl_add_u64 v[176:177], v[176:177], 0, s[48:49]
	ds_read_b128 v[172:175], v190 offset:49152
	ds_read_b128 v[182:185], v190 offset:50176
	ds_read_b128 v[192:195], v190 offset:51200
	ds_read_b128 v[196:199], v190 offset:52224
	ds_read_b128 v[218:221], v190 offset:53248
	ds_read_b128 v[222:225], v190 offset:54272
	ds_read_b128 v[230:233], v190 offset:55296
	ds_read_b128 v[234:237], v190 offset:56320
	global_load_lds_dwordx4 v[176:177], off
	v_lshl_add_u64 v[176:177], v[186:187], 0, s[48:49]
	s_mov_b32 m0, s64
	s_nop 0
	global_load_lds_dwordx4 v[176:177], off
	v_lshl_add_u64 v[176:177], v[238:239], 0, s[48:49]
	s_mov_b32 m0, s89
	s_nop 0
	global_load_lds_dwordx4 v[176:177], off
	v_lshl_add_u64 v[176:177], v[240:241], 0, s[48:49]
	s_mov_b32 m0, s70
	s_nop 0
	global_load_lds_dwordx4 v[176:177], off
	v_lshl_add_u64 v[176:177], v[242:243], 0, s[48:49]
	s_mov_b32 m0, s65
	s_nop 0
	global_load_lds_dwordx4 v[176:177], off
	v_lshl_add_u64 v[176:177], v[244:245], 0, s[48:49]
	s_mov_b32 m0, s87
	s_nop 0
	global_load_lds_dwordx4 v[176:177], off
	s_waitcnt vmcnt(8)
	s_waitcnt lgkmcnt(0)
	s_barrier
	s_waitcnt lgkmcnt(0)
	v_mfma_f32_16x16x32_bf16 v[78:81], v[26:29], v[172:175], v[78:81]
	v_mfma_f32_16x16x32_bf16 v[62:65], v[26:29], v[192:195], v[62:65]
	v_mfma_f32_16x16x32_bf16 v[46:49], v[26:29], v[218:221], v[46:49]
	v_mfma_f32_16x16x32_bf16 v[2:5], v[26:29], v[230:233], v[2:5]
	v_mfma_f32_16x16x32_bf16 v[78:81], v[30:33], v[182:185], v[78:81]
	v_mfma_f32_16x16x32_bf16 v[74:77], v[66:69], v[172:175], v[74:77]
	v_mfma_f32_16x16x32_bf16 v[62:65], v[30:33], v[196:199], v[62:65]
	v_mfma_f32_16x16x32_bf16 v[58:61], v[66:69], v[192:195], v[58:61]
	v_mfma_f32_16x16x32_bf16 v[46:49], v[30:33], v[222:225], v[46:49]
	v_mfma_f32_16x16x32_bf16 v[42:45], v[66:69], v[218:221], v[42:45]
	v_mfma_f32_16x16x32_bf16 v[30:33], v[30:33], v[234:237], v[2:5]
	v_mfma_f32_16x16x32_bf16 v[2:5], v[66:69], v[230:233], v[6:9]
	v_mfma_f32_16x16x32_bf16 v[74:77], v[70:73], v[182:185], v[74:77]
	v_mfma_f32_16x16x32_bf16 v[58:61], v[70:73], v[196:199], v[58:61]
	v_mfma_f32_16x16x32_bf16 v[42:45], v[70:73], v[222:225], v[42:45]
	v_mfma_f32_16x16x32_bf16 v[26:29], v[70:73], v[234:237], v[2:5]
	v_mfma_f32_16x16x32_bf16 v[2:5], v[146:149], v[172:175], v[10:13]
	v_mfma_f32_16x16x32_bf16 v[70:73], v[150:153], v[182:185], v[2:5]
	v_mfma_f32_16x16x32_bf16 v[2:5], v[164:167], v[172:175], v[14:17]
	v_mfma_f32_16x16x32_bf16 v[66:69], v[168:171], v[182:185], v[2:5]
	v_mfma_f32_16x16x32_bf16 v[2:5], v[146:149], v[192:195], v[54:57]
	v_mfma_f32_16x16x32_bf16 v[54:57], v[150:153], v[196:199], v[2:5]
	v_mfma_f32_16x16x32_bf16 v[2:5], v[164:167], v[192:195], v[50:53]
	v_mfma_f32_16x16x32_bf16 v[50:53], v[168:171], v[196:199], v[2:5]
	v_mfma_f32_16x16x32_bf16 v[2:5], v[146:149], v[218:221], v[38:41]
	v_mfma_f32_16x16x32_bf16 v[38:41], v[150:153], v[222:225], v[2:5]
	v_mfma_f32_16x16x32_bf16 v[2:5], v[164:167], v[218:221], v[34:37]
	v_mfma_f32_16x16x32_bf16 v[34:37], v[168:171], v[222:225], v[2:5]
	v_mfma_f32_16x16x32_bf16 v[2:5], v[146:149], v[230:233], v[22:25]
	v_mfma_f32_16x16x32_bf16 v[22:25], v[150:153], v[234:237], v[2:5]
	v_mfma_f32_16x16x32_bf16 v[2:5], v[164:167], v[230:233], v[18:21]
	v_mfma_f32_16x16x32_bf16 v[18:21], v[168:171], v[234:237], v[2:5]
	s_barrier
	s_add_u32 s9, s9, 0x100
	s_addc_u32 s10, s10, 0
	s_add_u32 s4, s4, 0x100
	s_addc_u32 s5, s5, 0
	s_cmp_ge_i32 s11, s86
	s_mov_b32 s6, s11
	s_cbranch_scc0 .LBB0_151

.LBB0_336:
	s_mov_b32 s0, s45
	s_add_i32 s0, s0, 0x200e8
	v_mov_b32_e32 v0, s0
	ds_read_b64 v[2:3], v0
	s_mov_b32 s16, 0
	s_setprio 0
	s_getreg_b32 s0, hwreg(HW_REG_XCC_ID, 0, 4)
	s_waitcnt vmcnt(0)
	s_waitcnt lgkmcnt(0)
	v_readfirstlane_b32 s73, v3
	v_readfirstlane_b32 s72, v2
	s_waitcnt vmcnt(0)
	s_barrier
	s_mov_b64 s[68:69], exec
	v_readlane_b32 s2, v252, 1
	v_readlane_b32 s3, v252, 2
	s_and_b64 s[2:3], s[68:69], s[2:3]
	s_mov_b64 exec, s[2:3]
	s_cbranch_execz .LBB0_380
	s_add_i32 s15, s16, 0x20200
	v_mov_b32_e32 v0, s15
	s_waitcnt vmcnt(0) expcnt(0) lgkmcnt(0)
	ds_read_b32 v2, v0
	s_add_i32 s16, s16, 0x20204
	v_mov_b32_e32 v0, s16
	ds_read_b32 v0, v0
	s_and_b32 s14, s0, 15
	s_waitcnt lgkmcnt(1)
	v_cmp_ne_u32_e32 vcc, 0, v2
	s_cbranch_vccnz .LBB0_351
	s_add_u32 s0, s72, 0x1000
	s_addc_u32 s1, s73, 0
	s_add_u32 s2, s72, 0x1100
	s_addc_u32 s3, s73, 0
	s_add_u32 s4, s72, 0x1200
	s_addc_u32 s5, s73, 0
	s_add_u32 s6, s72, 0x1300
	s_addc_u32 s7, s73, 0
	s_mov_b32 s30, 1
	s_mov_b64 s[8:9], 0
	s_branch .LBB0_341

.LBB0_385:
	s_mov_b32 s0, s45
	s_waitcnt lgkmcnt(0)
	s_barrier
	s_add_i32 s0, s0, 0x200e8
	v_mov_b32_e32 v0, s0
	s_waitcnt vmcnt(0)
	ds_read_b64 v[2:3], v0
	s_mov_b32 s16, 0
	s_setprio 0
	s_getreg_b32 s0, hwreg(HW_REG_XCC_ID, 0, 4)
	s_waitcnt vmcnt(0)
	s_waitcnt lgkmcnt(0)
	v_readfirstlane_b32 s75, v3
	v_readfirstlane_b32 s74, v2
	s_barrier
	s_mov_b64 s[72:73], exec
	v_readlane_b32 s2, v252, 1
	v_readlane_b32 s3, v252, 2
	s_and_b64 s[2:3], s[72:73], s[2:3]
	s_mov_b64 exec, s[2:3]
	s_cbranch_execz .LBB0_429
	s_add_i32 s15, s16, 0x20200
	v_mov_b32_e32 v0, s15
	s_waitcnt vmcnt(0) expcnt(0) lgkmcnt(0)
	ds_read_b32 v2, v0
	s_add_i32 s16, s16, 0x20204
	v_mov_b32_e32 v0, s16
	ds_read_b32 v0, v0
	s_and_b32 s14, s0, 15
	s_waitcnt lgkmcnt(1)
	v_cmp_ne_u32_e32 vcc, 0, v2
	s_cbranch_vccnz .LBB0_400
	s_add_u32 s0, s74, 0x1000
	s_addc_u32 s1, s75, 0
	s_add_u32 s2, s74, 0x1100
	s_addc_u32 s3, s75, 0
	s_add_u32 s4, s74, 0x1200
	s_addc_u32 s5, s75, 0
	s_add_u32 s6, s74, 0x1300
	s_addc_u32 s7, s75, 0
	s_mov_b32 s30, 1
	s_mov_b64 s[8:9], 0
	s_branch .LBB0_390

.LBB0_519:
	s_or_b64 exec, exec, s[4:5]
	s_mov_b32 s0, s45
	s_add_i32 s0, s0, 0x200e8
	v_mov_b32_e32 v0, s0
	ds_read_b64 v[2:3], v0
	s_mov_b32 s16, 0
	s_setprio 0
	s_getreg_b32 s0, hwreg(HW_REG_XCC_ID, 0, 4)
	s_waitcnt vmcnt(0)
	s_waitcnt lgkmcnt(0)
	v_readfirstlane_b32 s73, v3
	v_readfirstlane_b32 s72, v2
	s_barrier
	s_mov_b64 s[70:71], exec
	v_readlane_b32 s2, v252, 1
	v_readlane_b32 s3, v252, 2
	s_and_b64 s[2:3], s[70:71], s[2:3]
	s_mov_b64 exec, s[2:3]
	s_cbranch_execz .LBB0_563
	s_add_i32 s15, s16, 0x20200
	v_mov_b32_e32 v0, s15
	s_waitcnt vmcnt(0) expcnt(0) lgkmcnt(0)
	ds_read_b32 v2, v0
	s_add_i32 s16, s16, 0x20204
	v_mov_b32_e32 v0, s16
	ds_read_b32 v0, v0
	s_and_b32 s14, s0, 15
	s_waitcnt lgkmcnt(1)
	v_cmp_ne_u32_e32 vcc, 0, v2
	s_cbranch_vccnz .LBB0_534
	s_add_u32 s0, s72, 0x1000
	s_addc_u32 s1, s73, 0
	s_add_u32 s2, s72, 0x1100
	s_addc_u32 s3, s73, 0
	s_add_u32 s4, s72, 0x1200
	s_addc_u32 s5, s73, 0
	s_add_u32 s6, s72, 0x1300
	s_addc_u32 s7, s73, 0
	s_mov_b32 s30, 1
	s_mov_b64 s[8:9], 0
	s_branch .LBB0_524

.LBB0_602:
	s_mov_b32 s0, s45
	s_waitcnt lgkmcnt(0)
	s_barrier
	s_add_i32 s0, s0, 0x200e8
	v_mov_b32_e32 v0, s0
	s_waitcnt vmcnt(0)
	ds_read_b64 v[2:3], v0
	s_mov_b32 s16, 0
	s_setprio 0
	s_getreg_b32 s0, hwreg(HW_REG_XCC_ID, 0, 4)
	s_waitcnt vmcnt(0)
	s_waitcnt lgkmcnt(0)
	v_readfirstlane_b32 s73, v3
	v_readfirstlane_b32 s72, v2
	s_barrier
	s_mov_b64 s[70:71], exec
	v_readlane_b32 s2, v252, 1
	v_readlane_b32 s3, v252, 2
	s_and_b64 s[2:3], s[70:71], s[2:3]
	s_mov_b64 exec, s[2:3]
	s_cbranch_execz .LBB0_646
	s_add_i32 s15, s16, 0x20200
	v_mov_b32_e32 v0, s15
	s_waitcnt vmcnt(0) expcnt(0) lgkmcnt(0)
	ds_read_b32 v2, v0
	s_add_i32 s16, s16, 0x20204
	v_mov_b32_e32 v0, s16
	ds_read_b32 v0, v0
	s_and_b32 s14, s0, 15
	s_waitcnt lgkmcnt(1)
	v_cmp_ne_u32_e32 vcc, 0, v2
	s_cbranch_vccnz .LBB0_617
	s_add_u32 s0, s72, 0x1000
	s_addc_u32 s1, s73, 0
	s_add_u32 s2, s72, 0x1100
	s_addc_u32 s3, s73, 0
	s_add_u32 s4, s72, 0x1200
	s_addc_u32 s5, s73, 0
	s_add_u32 s6, s72, 0x1300
	s_addc_u32 s7, s73, 0
	s_mov_b32 s30, 1
	s_mov_b64 s[8:9], 0
	s_branch .LBB0_607

.LBB0_648:
	s_andn2_b64 vcc, exec, s[4:5]
	s_cbranch_vccnz .LBB0_747
	v_bfe_i32 v3, v20, 27, 1
	v_lshlrev_b32_e32 v2, 4, v20
	v_lshrrev_b32_e32 v3, 22, v3
	v_add_u32_e32 v3, v2, v3
	v_and_b32_e32 v3, 0xfffffc00, v3
	v_sub_u32_e32 v3, v2, v3
	v_ashrrev_i32_e32 v0, 31, v20
	v_lshrrev_b32_e32 v4, 4, v3
	v_lshrrev_b32_e32 v0, 26, v0
	v_bitop3_b32 v3, v4, v3, 32 bitop3:0x6c
	v_add_u32_e32 v0, v20, v0
	v_ashrrev_i32_e32 v5, 31, v3
	v_ashrrev_i32_e32 v0, 6, v0
	v_lshrrev_b32_e32 v5, 26, v5
	v_lshlrev_b32_e32 v4, 3, v0
	v_add_u32_e32 v5, v3, v5
	v_and_b32_e32 v4, -16, v4
	v_ashrrev_i32_e32 v6, 6, v5
	v_lshlrev_b32_e32 v0, 5, v0
	s_add_u32 s15, s3, 0x8bf1c00
	v_add_u32_e32 v4, v6, v4
	v_and_b32_e32 v14, 32, v0
	v_and_b32_e32 v0, 0xc0, v5
	s_addc_u32 s16, s1, 0
	v_sub_u32_e32 v0, v3, v0
	v_lshlrev_b32_e32 v3, 1, v4
	v_lshrrev_b32_e32 v5, 2, v4
	v_and_b32_e32 v6, 3, v6
	s_mov_b32 s1, 0x7fffffe0
	v_ashrrev_i16_sdwa v0, v201, sext(v0) dst_sel:DWORD dst_unused:UNUSED_PAD src0_sel:DWORD src1_sel:BYTE_0
	v_and_b32_e32 v3, 24, v3
	v_and_b32_e32 v5, 4, v5
	v_and_or_b32 v6, v4, s1, v6
	v_bfe_i32 v15, v0, 0, 16
	v_or3_b32 v3, v6, v5, v3
	v_add_u32_e32 v0, v14, v15
	v_mul_lo_u32 v16, v4, s2
	v_mul_lo_u32 v3, v3, s0
	v_add_u32_e32 v2, 0x2000, v2
	v_add_lshl_u32 v138, v0, v16, 1
	v_add_lshl_u32 v0, v3, v0, 1
	v_ashrrev_i32_e32 v3, 31, v2
	v_lshrrev_b32_e32 v3, 22, v3
	v_add_u32_e32 v3, v2, v3
	v_ashrrev_i32_e32 v3, 10, v3
	v_mul_i32_i24_e32 v4, 0x400, v3
	v_sub_u32_e32 v2, v2, v4
	v_lshrrev_b32_e32 v4, 4, v2
	v_bitop3_b32 v2, v4, v2, 32 bitop3:0x6c
	v_ashrrev_i32_e32 v5, 31, v2
	v_lshrrev_b32_e32 v5, 26, v5
	s_add_u32 s33, s9, 0x1610000
	v_lshlrev_b32_e32 v4, 3, v3
	v_add_u32_e32 v5, v2, v5
	s_addc_u32 s37, s8, 0
	v_and_b32_e32 v4, -16, v4
	v_ashrrev_i32_e32 v6, 6, v5
	s_ashr_i32 s3, s2, 31
	v_add_u32_e32 v4, v6, v4
	s_lshl_b64 s[12:13], s[2:3], 9
	s_ashr_i32 s4, s89, 31
	v_and_b32_e32 v6, 3, v6
	v_mul_lo_u32 v19, v4, s2
	s_lshl_b64 s[8:9], s[2:3], 8
	s_mul_i32 s4, s12, s4
	s_mul_hi_u32 s5, s12, s89
	s_lshr_b64 s[2:3], s[2:3], 23
	v_and_or_b32 v6, v4, s1, v6
	s_ashr_i32 s1, s0, 31
	s_add_i32 s4, s5, s4
	s_mul_i32 s2, s2, s89
	s_lshl_b64 s[18:19], s[0:1], 9
	s_add_i32 s20, s4, s2
	s_ashr_i32 s2, s90, 31
	s_mul_i32 s2, s18, s2
	s_mul_hi_u32 s3, s18, s90
	s_add_i32 s4, s3, s2
	s_lshr_b64 s[2:3], s[0:1], 23
	s_ashr_i32 s23, s7, 6
	s_mul_i32 s2, s2, s90
	s_ashr_i32 s46, s7, 8
	s_lshl_b64 s[10:11], s[0:1], 8
	s_lshl_b32 s22, s23, 10
	s_add_i32 s2, s4, s2
	s_mul_i32 s3, s18, s90
	s_add_u32 s4, s33, s3
	s_addc_u32 s5, s37, s2
	s_add_i32 s47, s26, 0x10000
	v_lshlrev_b32_e32 v3, 5, v3
	s_add_i32 s50, s47, s22
	v_and_b32_e32 v17, 32, v3
	v_and_b32_e32 v3, 0xc0, v5
	s_add_i32 s51, s50, 0x2000
	v_sub_u32_e32 v2, v2, v3
	v_lshlrev_b32_e32 v3, 1, v4
	v_lshrrev_b32_e32 v5, 2, v4
	s_add_u32 s2, s4, s10
	v_ashrrev_i16_sdwa v2, v201, sext(v2) dst_sel:DWORD dst_unused:UNUSED_PAD src0_sel:DWORD src1_sel:BYTE_0
	v_and_b32_e32 v3, 24, v3
	v_and_b32_e32 v5, 4, v5
	s_addc_u32 s3, s5, s11
	s_add_i32 s52, s26, 0x14000
	v_bfe_i32 v18, v2, 0, 16
	v_or3_b32 v3, v6, v5, v3
	s_add_i32 s53, s52, s22
	v_add_u32_e32 v2, v17, v18
	v_mul_lo_u32 v3, v3, s0
	s_mul_i32 s21, s12, s89
	s_mov_b32 m0, s50
	s_add_i32 s54, s53, 0x2000
	v_add_lshl_u32 v142, v3, v2, 1
	global_load_lds_dwordx4 v0, s[4:5]
	s_mov_b32 m0, s51
	s_add_u32 s28, s15, s21
	global_load_lds_dwordx4 v142, s[4:5]
	s_mov_b32 m0, s53
	s_addc_u32 s29, s16, s20
	s_add_i32 s55, s26, s22
	v_mov_b32_e32 v143, v1
	global_load_lds_dwordx4 v0, s[2:3]
	s_mov_b32 m0, s54
	s_add_i32 s58, s55, 0x2000
	v_lshl_add_u64 v[6:7], s[2:3], 0, v[0:1]
	v_lshl_add_u64 v[8:9], s[2:3], 0, v[142:143]
	global_load_lds_dwordx4 v142, s[2:3]
	s_mov_b32 m0, s55
	s_add_u32 s2, s28, s8
	v_add_lshl_u32 v140, v2, v19, 1
	global_load_lds_dwordx4 v138, s[28:29]
	s_mov_b32 m0, s58
	s_addc_u32 s3, s29, s9
	s_add_i32 s59, s55, 0x4000
	global_load_lds_dwordx4 v140, s[28:29]
	s_mov_b32 m0, s59
	s_add_i32 s60, s55, 0x6000
	global_load_lds_dwordx4 v138, s[2:3]
	s_mov_b32 m0, s60
	v_mov_b32_e32 v139, v1
	global_load_lds_dwordx4 v140, s[2:3]
	v_mov_b32_e32 v141, v1
	s_cmp_eq_u32 s46, 1
	v_lshl_add_u64 v[2:3], s[4:5], 0, v[0:1]
	v_lshl_add_u64 v[4:5], s[4:5], 0, v[142:143]
	v_lshl_add_u64 v[10:11], s[28:29], 0, v[138:139]
	v_lshl_add_u64 v[12:13], s[28:29], 0, v[140:141]
	s_cselect_b64 s[20:21], -1, 0
	s_cmp_lg_u32 s46, 1
	s_cbranch_scc1 .LBB0_651
	s_barrier
	s_setprio 1

.LBB0_662:
	v_add_u32_e32 v152, s47, v156
	ds_read_b128 v[130:133], v152
	ds_read_b128 v[134:137], v152 offset:1024
	ds_read_b128 v[148:151], v152 offset:2048
	ds_read_b128 v[158:161], v152 offset:3072
	v_add_u32_e32 v152, s52, v156
	ds_read_b128 v[162:165], v152
	ds_read_b128 v[166:169], v152 offset:1024
	ds_read_b128 v[170:173], v152 offset:2048
	ds_read_b128 v[174:177], v152 offset:3072
	s_add_i32 s34, s28, 2
	s_add_u32 s35, s4, 0x80
	s_addc_u32 s29, s5, 0
	s_cmp_eq_u32 s75, s28
	s_cselect_b32 s28, s0, s35
	s_cselect_b32 s29, s1, s29
	s_cselect_b32 s71, s27, s31
	s_cselect_b32 s70, s26, s30
	v_lshl_add_u64 v[152:153], s[4:5], 0, v[146:147]
	s_add_i32 m0, s55, 0xc000
	ds_read_b128 v[182:185], v157
	ds_read_b128 v[186:189], v157 offset:1024
	ds_read_b128 v[190:193], v157 offset:2048
	ds_read_b128 v[194:197], v157 offset:3072
	ds_read_b128 v[218:221], v157 offset:4096
	ds_read_b128 v[222:225], v157 offset:5120
	ds_read_b128 v[230:233], v157 offset:6144
	ds_read_b128 v[234:237], v157 offset:7168
	global_load_lds_dwordx4 v[152:153], off
	v_lshl_add_u64 v[152:153], s[4:5], 0, v[144:145]
	s_add_i32 m0, s55, 0xe000
	s_nop 0
	global_load_lds_dwordx4 v[152:153], off
	s_waitcnt vmcnt(8)
	s_waitcnt lgkmcnt(0)
	s_barrier
	s_waitcnt lgkmcnt(0)
	v_mfma_f32_16x16x32_bf16 v[6:9], v[130:133], v[182:185], v[6:9]
	v_mfma_f32_16x16x32_bf16 v[2:5], v[148:151], v[182:185], v[2:5]
	v_mfma_f32_16x16x32_bf16 v[126:129], v[130:133], v[190:193], v[126:129]
	v_mfma_f32_16x16x32_bf16 v[122:125], v[148:151], v[190:193], v[122:125]
	v_mfma_f32_16x16x32_bf16 v[118:121], v[130:133], v[218:221], v[118:121]
	v_mfma_f32_16x16x32_bf16 v[114:117], v[148:151], v[218:221], v[114:117]
	v_mfma_f32_16x16x32_bf16 v[110:113], v[130:133], v[230:233], v[110:113]
	v_mfma_f32_16x16x32_bf16 v[106:109], v[148:151], v[230:233], v[106:109]
	v_mfma_f32_16x16x32_bf16 v[6:9], v[134:137], v[186:189], v[6:9]
	v_mfma_f32_16x16x32_bf16 v[2:5], v[158:161], v[186:189], v[2:5]
	v_mfma_f32_16x16x32_bf16 v[126:129], v[134:137], v[194:197], v[126:129]
	v_mfma_f32_16x16x32_bf16 v[122:125], v[158:161], v[194:197], v[122:125]
	v_mfma_f32_16x16x32_bf16 v[118:121], v[134:137], v[222:225], v[118:121]
	v_mfma_f32_16x16x32_bf16 v[114:117], v[158:161], v[222:225], v[114:117]
	v_mfma_f32_16x16x32_bf16 v[110:113], v[134:137], v[234:237], v[110:113]
	v_mfma_f32_16x16x32_bf16 v[106:109], v[158:161], v[234:237], v[106:109]
	v_mfma_f32_16x16x32_bf16 v[70:73], v[162:165], v[182:185], v[70:73]
	v_mfma_f32_16x16x32_bf16 v[66:69], v[170:173], v[182:185], v[66:69]
	v_mfma_f32_16x16x32_bf16 v[62:65], v[162:165], v[190:193], v[62:65]
	v_mfma_f32_16x16x32_bf16 v[58:61], v[170:173], v[190:193], v[58:61]
	v_mfma_f32_16x16x32_bf16 v[54:57], v[162:165], v[218:221], v[54:57]
	v_mfma_f32_16x16x32_bf16 v[50:53], v[170:173], v[218:221], v[50:53]
	v_mfma_f32_16x16x32_bf16 v[46:49], v[162:165], v[230:233], v[46:49]
	v_mfma_f32_16x16x32_bf16 v[42:45], v[170:173], v[230:233], v[42:45]
	v_mfma_f32_16x16x32_bf16 v[70:73], v[166:169], v[186:189], v[70:73]
	v_mfma_f32_16x16x32_bf16 v[66:69], v[174:177], v[186:189], v[66:69]
	v_mfma_f32_16x16x32_bf16 v[62:65], v[166:169], v[194:197], v[62:65]
	v_mfma_f32_16x16x32_bf16 v[58:61], v[174:177], v[194:197], v[58:61]
	v_mfma_f32_16x16x32_bf16 v[54:57], v[166:169], v[222:225], v[54:57]
	v_mfma_f32_16x16x32_bf16 v[50:53], v[174:177], v[222:225], v[50:53]
	v_mfma_f32_16x16x32_bf16 v[46:49], v[166:169], v[234:237], v[46:49]
	v_mfma_f32_16x16x32_bf16 v[42:45], v[174:177], v[234:237], v[42:45]
	s_barrier
	s_mov_b32 m0, s50
	v_lshl_add_u64 v[152:153], s[70:71], 0, v[0:1]
	v_lshl_add_u64 v[198:199], s[70:71], 0, v[142:143]
	s_add_u32 s70, s70, s10
	ds_read_b128 v[182:185], v157 offset:16384
	ds_read_b128 v[186:189], v157 offset:17408
	ds_read_b128 v[190:193], v157 offset:18432
	ds_read_b128 v[194:197], v157 offset:19456
	ds_read_b128 v[218:221], v157 offset:20480
	ds_read_b128 v[222:225], v157 offset:21504
	ds_read_b128 v[230:233], v157 offset:22528
	ds_read_b128 v[234:237], v157 offset:23552
	global_load_lds_dwordx4 v[152:153], off
	s_mov_b32 m0, s51
	s_addc_u32 s71, s71, s11
	global_load_lds_dwordx4 v[198:199], off
	v_lshl_add_u64 v[238:239], s[70:71], 0, v[0:1]
	s_mov_b32 m0, s53
	v_lshl_add_u64 v[240:241], s[70:71], 0, v[142:143]
	global_load_lds_dwordx4 v[238:239], off
	s_mov_b32 m0, s54
	v_lshl_add_u64 v[242:243], s[28:29], 0, v[138:139]
	global_load_lds_dwordx4 v[240:241], off
	s_mov_b32 m0, s55
	v_lshl_add_u64 v[244:245], s[28:29], 0, v[140:141]
	global_load_lds_dwordx4 v[242:243], off
	s_mov_b32 m0, s58
	s_nop 0
	global_load_lds_dwordx4 v[244:245], off
	s_waitcnt vmcnt(8)
	s_waitcnt lgkmcnt(0)
	s_barrier
	s_waitcnt lgkmcnt(0)
	v_mfma_f32_16x16x32_bf16 v[102:105], v[130:133], v[182:185], v[102:105]
	v_mfma_f32_16x16x32_bf16 v[98:101], v[148:151], v[182:185], v[98:101]
	v_mfma_f32_16x16x32_bf16 v[94:97], v[130:133], v[190:193], v[94:97]
	v_mfma_f32_16x16x32_bf16 v[90:93], v[148:151], v[190:193], v[90:93]
	v_mfma_f32_16x16x32_bf16 v[86:89], v[130:133], v[218:221], v[86:89]
	v_mfma_f32_16x16x32_bf16 v[82:85], v[148:151], v[218:221], v[82:85]
	v_mfma_f32_16x16x32_bf16 v[78:81], v[130:133], v[230:233], v[78:81]
	v_mfma_f32_16x16x32_bf16 v[74:77], v[148:151], v[230:233], v[74:77]
	v_mfma_f32_16x16x32_bf16 v[102:105], v[134:137], v[186:189], v[102:105]
	v_mfma_f32_16x16x32_bf16 v[98:101], v[158:161], v[186:189], v[98:101]
	v_mfma_f32_16x16x32_bf16 v[94:97], v[134:137], v[194:197], v[94:97]
	v_mfma_f32_16x16x32_bf16 v[90:93], v[158:161], v[194:197], v[90:93]
	v_mfma_f32_16x16x32_bf16 v[86:89], v[134:137], v[222:225], v[86:89]
	v_mfma_f32_16x16x32_bf16 v[82:85], v[158:161], v[222:225], v[82:85]
	v_mfma_f32_16x16x32_bf16 v[78:81], v[134:137], v[234:237], v[78:81]
	v_mfma_f32_16x16x32_bf16 v[74:77], v[158:161], v[234:237], v[74:77]
	v_mfma_f32_16x16x32_bf16 v[38:41], v[162:165], v[182:185], v[38:41]
	v_mfma_f32_16x16x32_bf16 v[34:37], v[170:173], v[182:185], v[34:37]
	v_mfma_f32_16x16x32_bf16 v[30:33], v[162:165], v[190:193], v[30:33]
	v_mfma_f32_16x16x32_bf16 v[26:29], v[170:173], v[190:193], v[26:29]
	v_mfma_f32_16x16x32_bf16 v[22:25], v[162:165], v[218:221], v[22:25]
	v_mfma_f32_16x16x32_bf16 v[18:21], v[170:173], v[218:221], v[18:21]
	v_mfma_f32_16x16x32_bf16 v[14:17], v[162:165], v[230:233], v[14:17]
	v_mfma_f32_16x16x32_bf16 v[10:13], v[170:173], v[230:233], v[10:13]
	v_mfma_f32_16x16x32_bf16 v[38:41], v[166:169], v[186:189], v[38:41]
	v_mfma_f32_16x16x32_bf16 v[34:37], v[174:177], v[186:189], v[34:37]
	v_mfma_f32_16x16x32_bf16 v[30:33], v[166:169], v[194:197], v[30:33]
	v_mfma_f32_16x16x32_bf16 v[26:29], v[174:177], v[194:197], v[26:29]
	v_mfma_f32_16x16x32_bf16 v[22:25], v[166:169], v[222:225], v[22:25]
	v_mfma_f32_16x16x32_bf16 v[18:21], v[174:177], v[222:225], v[18:21]
	v_mfma_f32_16x16x32_bf16 v[14:17], v[166:169], v[234:237], v[14:17]
	v_mfma_f32_16x16x32_bf16 v[10:13], v[174:177], v[234:237], v[10:13]
	s_barrier
	v_add_u32_e32 v158, s63, v156
	v_add_u32_e32 v174, s72, v156
	ds_read_b128 v[130:133], v158
	ds_read_b128 v[134:137], v158 offset:1024
	ds_read_b128 v[148:151], v158 offset:2048
	ds_read_b128 v[158:161], v158 offset:3072
	ds_read_b128 v[162:165], v174
	ds_read_b128 v[166:169], v174 offset:1024
	ds_read_b128 v[170:173], v174 offset:2048
	ds_read_b128 v[174:177], v174 offset:3072
	s_add_u32 s28, s28, s8
	s_addc_u32 s29, s29, s9
	s_mov_b32 m0, s59
	v_lshl_add_u64 v[246:247], s[28:29], 0, v[138:139]
	ds_read_b128 v[182:185], v157 offset:32768
	ds_read_b128 v[186:189], v157 offset:33792
	ds_read_b128 v[190:193], v157 offset:34816
	ds_read_b128 v[194:197], v157 offset:35840
	ds_read_b128 v[218:221], v157 offset:36864
	ds_read_b128 v[222:225], v157 offset:37888
	ds_read_b128 v[230:233], v157 offset:38912
	ds_read_b128 v[234:237], v157 offset:39936
	global_load_lds_dwordx4 v[246:247], off
	v_lshl_add_u64 v[246:247], s[28:29], 0, v[140:141]
	s_mov_b32 m0, s60
	s_nop 0
	global_load_lds_dwordx4 v[246:247], off
	s_waitcnt vmcnt(8)
	s_waitcnt lgkmcnt(0)
	s_barrier
	s_waitcnt lgkmcnt(0)
	v_mfma_f32_16x16x32_bf16 v[6:9], v[130:133], v[182:185], v[6:9]
	v_mfma_f32_16x16x32_bf16 v[2:5], v[148:151], v[182:185], v[2:5]
	v_mfma_f32_16x16x32_bf16 v[126:129], v[130:133], v[190:193], v[126:129]
	v_mfma_f32_16x16x32_bf16 v[122:125], v[148:151], v[190:193], v[122:125]
	v_mfma_f32_16x16x32_bf16 v[118:121], v[130:133], v[218:221], v[118:121]
	v_mfma_f32_16x16x32_bf16 v[114:117], v[148:151], v[218:221], v[114:117]
	v_mfma_f32_16x16x32_bf16 v[110:113], v[130:133], v[230:233], v[110:113]
	v_mfma_f32_16x16x32_bf16 v[106:109], v[148:151], v[230:233], v[106:109]
	v_mfma_f32_16x16x32_bf16 v[6:9], v[134:137], v[186:189], v[6:9]
	v_mfma_f32_16x16x32_bf16 v[2:5], v[158:161], v[186:189], v[2:5]
	v_mfma_f32_16x16x32_bf16 v[126:129], v[134:137], v[194:197], v[126:129]
	v_mfma_f32_16x16x32_bf16 v[122:125], v[158:161], v[194:197], v[122:125]
	v_mfma_f32_16x16x32_bf16 v[118:121], v[134:137], v[222:225], v[118:121]
	v_mfma_f32_16x16x32_bf16 v[114:117], v[158:161], v[222:225], v[114:117]
	v_mfma_f32_16x16x32_bf16 v[110:113], v[134:137], v[234:237], v[110:113]
	v_mfma_f32_16x16x32_bf16 v[106:109], v[158:161], v[234:237], v[106:109]
	v_mfma_f32_16x16x32_bf16 v[70:73], v[162:165], v[182:185], v[70:73]
	v_mfma_f32_16x16x32_bf16 v[66:69], v[170:173], v[182:185], v[66:69]
	v_mfma_f32_16x16x32_bf16 v[62:65], v[162:165], v[190:193], v[62:65]
	v_mfma_f32_16x16x32_bf16 v[58:61], v[170:173], v[190:193], v[58:61]
	v_mfma_f32_16x16x32_bf16 v[54:57], v[162:165], v[218:221], v[54:57]
	v_mfma_f32_16x16x32_bf16 v[50:53], v[170:173], v[218:221], v[50:53]
	v_mfma_f32_16x16x32_bf16 v[46:49], v[162:165], v[230:233], v[46:49]
	v_mfma_f32_16x16x32_bf16 v[42:45], v[170:173], v[230:233], v[42:45]
	v_mfma_f32_16x16x32_bf16 v[70:73], v[166:169], v[186:189], v[70:73]
	v_mfma_f32_16x16x32_bf16 v[66:69], v[174:177], v[186:189], v[66:69]
	v_mfma_f32_16x16x32_bf16 v[62:65], v[166:169], v[194:197], v[62:65]
	v_mfma_f32_16x16x32_bf16 v[58:61], v[174:177], v[194:197], v[58:61]
	v_mfma_f32_16x16x32_bf16 v[54:57], v[166:169], v[222:225], v[54:57]
	v_mfma_f32_16x16x32_bf16 v[50:53], v[174:177], v[222:225], v[50:53]
	v_mfma_f32_16x16x32_bf16 v[46:49], v[166:169], v[234:237], v[46:49]
	v_mfma_f32_16x16x32_bf16 v[42:45], v[174:177], v[234:237], v[42:45]
	s_barrier
	s_mov_b32 m0, s64
	v_lshl_add_u64 v[152:153], v[152:153], 0, s[48:49]
	ds_read_b128 v[182:185], v157 offset:49152
	ds_read_b128 v[186:189], v157 offset:50176
	ds_read_b128 v[190:193], v157 offset:51200
	ds_read_b128 v[194:197], v157 offset:52224
	ds_read_b128 v[218:221], v157 offset:53248
	ds_read_b128 v[222:225], v157 offset:54272
	ds_read_b128 v[230:233], v157 offset:55296
	ds_read_b128 v[234:237], v157 offset:56320
	global_load_lds_dwordx4 v[152:153], off
	v_lshl_add_u64 v[152:153], v[198:199], 0, s[48:49]
	s_mov_b32 m0, s65
	s_nop 0
	global_load_lds_dwordx4 v[152:153], off
	v_lshl_add_u64 v[152:153], v[238:239], 0, s[48:49]
	s_mov_b32 m0, s73
	s_nop 0
	global_load_lds_dwordx4 v[152:153], off
	v_lshl_add_u64 v[152:153], v[240:241], 0, s[48:49]
	s_mov_b32 m0, s74
	s_nop 0
	global_load_lds_dwordx4 v[152:153], off
	v_lshl_add_u64 v[152:153], v[242:243], 0, s[48:49]
	s_mov_b32 m0, s66
	s_nop 0
	global_load_lds_dwordx4 v[152:153], off
	v_lshl_add_u64 v[152:153], v[244:245], 0, s[48:49]
	s_mov_b32 m0, s67
	s_nop 0
	global_load_lds_dwordx4 v[152:153], off
	s_waitcnt vmcnt(8)
	s_waitcnt lgkmcnt(0)
	s_barrier
	s_waitcnt lgkmcnt(0)
	v_mfma_f32_16x16x32_bf16 v[102:105], v[130:133], v[182:185], v[102:105]
	v_mfma_f32_16x16x32_bf16 v[98:101], v[148:151], v[182:185], v[98:101]
	v_mfma_f32_16x16x32_bf16 v[94:97], v[130:133], v[190:193], v[94:97]
	v_mfma_f32_16x16x32_bf16 v[90:93], v[148:151], v[190:193], v[90:93]
	v_mfma_f32_16x16x32_bf16 v[86:89], v[130:133], v[218:221], v[86:89]
	v_mfma_f32_16x16x32_bf16 v[82:85], v[148:151], v[218:221], v[82:85]
	v_mfma_f32_16x16x32_bf16 v[78:81], v[130:133], v[230:233], v[78:81]
	v_mfma_f32_16x16x32_bf16 v[74:77], v[148:151], v[230:233], v[74:77]
	v_mfma_f32_16x16x32_bf16 v[102:105], v[134:137], v[186:189], v[102:105]
	v_mfma_f32_16x16x32_bf16 v[98:101], v[158:161], v[186:189], v[98:101]
	v_mfma_f32_16x16x32_bf16 v[94:97], v[134:137], v[194:197], v[94:97]
	v_mfma_f32_16x16x32_bf16 v[90:93], v[158:161], v[194:197], v[90:93]
	v_mfma_f32_16x16x32_bf16 v[86:89], v[134:137], v[222:225], v[86:89]
	v_mfma_f32_16x16x32_bf16 v[82:85], v[158:161], v[222:225], v[82:85]
	v_mfma_f32_16x16x32_bf16 v[78:81], v[134:137], v[234:237], v[78:81]
	v_mfma_f32_16x16x32_bf16 v[74:77], v[158:161], v[234:237], v[74:77]
	v_mfma_f32_16x16x32_bf16 v[38:41], v[162:165], v[182:185], v[38:41]
	v_mfma_f32_16x16x32_bf16 v[34:37], v[170:173], v[182:185], v[34:37]
	v_mfma_f32_16x16x32_bf16 v[30:33], v[162:165], v[190:193], v[30:33]
	v_mfma_f32_16x16x32_bf16 v[26:29], v[170:173], v[190:193], v[26:29]
	v_mfma_f32_16x16x32_bf16 v[22:25], v[162:165], v[218:221], v[22:25]
	v_mfma_f32_16x16x32_bf16 v[18:21], v[170:173], v[218:221], v[18:21]
	v_mfma_f32_16x16x32_bf16 v[14:17], v[162:165], v[230:233], v[14:17]
	v_mfma_f32_16x16x32_bf16 v[10:13], v[170:173], v[230:233], v[10:13]
	v_mfma_f32_16x16x32_bf16 v[38:41], v[166:169], v[186:189], v[38:41]
	v_mfma_f32_16x16x32_bf16 v[34:37], v[174:177], v[186:189], v[34:37]
	v_mfma_f32_16x16x32_bf16 v[30:33], v[166:169], v[194:197], v[30:33]
	v_mfma_f32_16x16x32_bf16 v[26:29], v[174:177], v[194:197], v[26:29]
	v_mfma_f32_16x16x32_bf16 v[22:25], v[166:169], v[222:225], v[22:25]
	v_mfma_f32_16x16x32_bf16 v[18:21], v[174:177], v[222:225], v[18:21]
	v_mfma_f32_16x16x32_bf16 v[14:17], v[166:169], v[234:237], v[14:17]
	v_mfma_f32_16x16x32_bf16 v[10:13], v[174:177], v[234:237], v[10:13]
	s_barrier
	s_add_u32 s30, s30, 0x100
	s_addc_u32 s31, s31, 0
	s_add_u32 s4, s4, 0x100
	s_addc_u32 s5, s5, 0
	s_cmp_ge_i32 s34, s62
	s_mov_b32 s28, s34
	s_cbranch_scc0 .LBB0_662

.LBB0_749:
	s_andn2_b64 vcc, exec, s[4:5]
	s_cbranch_vccnz .LBB0_802
	v_bfe_i32 v3, v20, 27, 1
	v_lshlrev_b32_e32 v2, 4, v20
	v_lshrrev_b32_e32 v3, 22, v3
	v_add_u32_e32 v3, v2, v3
	v_and_b32_e32 v3, 0xfffffc00, v3
	v_sub_u32_e32 v3, v2, v3
	v_ashrrev_i32_e32 v0, 31, v20
	v_lshrrev_b32_e32 v4, 4, v3
	v_lshrrev_b32_e32 v0, 26, v0
	v_bitop3_b32 v3, v4, v3, 32 bitop3:0x6c
	v_add_u32_e32 v0, v20, v0
	v_ashrrev_i32_e32 v5, 31, v3
	v_ashrrev_i32_e32 v0, 6, v0
	v_lshrrev_b32_e32 v5, 26, v5
	v_lshlrev_b32_e32 v4, 3, v0
	v_add_u32_e32 v5, v3, v5
	v_and_b32_e32 v4, -16, v4
	v_ashrrev_i32_e32 v6, 6, v5
	v_lshlrev_b32_e32 v0, 5, v0
	s_add_u32 s15, s3, 0x8bf1d00
	v_add_u32_e32 v4, v6, v4
	v_and_b32_e32 v14, 32, v0
	v_and_b32_e32 v0, 0xc0, v5
	s_addc_u32 s16, s1, 0
	v_sub_u32_e32 v0, v3, v0
	v_lshlrev_b32_e32 v3, 1, v4
	v_lshrrev_b32_e32 v5, 2, v4
	v_and_b32_e32 v6, 3, v6
	s_mov_b32 s1, 0x7fffffe0
	v_ashrrev_i16_sdwa v0, v201, sext(v0) dst_sel:DWORD dst_unused:UNUSED_PAD src0_sel:DWORD src1_sel:BYTE_0
	v_and_b32_e32 v3, 24, v3
	v_and_b32_e32 v5, 4, v5
	v_and_or_b32 v6, v4, s1, v6
	v_bfe_i32 v15, v0, 0, 16
	v_or3_b32 v3, v6, v5, v3
	v_add_u32_e32 v0, v14, v15
	v_mul_lo_u32 v16, v4, s2
	v_mul_lo_u32 v3, v3, s0
	v_add_u32_e32 v2, 0x2000, v2
	v_add_lshl_u32 v130, v0, v16, 1
	v_add_lshl_u32 v0, v3, v0, 1
	v_ashrrev_i32_e32 v3, 31, v2
	v_lshrrev_b32_e32 v3, 22, v3
	v_add_u32_e32 v3, v2, v3
	v_ashrrev_i32_e32 v3, 10, v3
	v_mul_i32_i24_e32 v4, 0x400, v3
	v_sub_u32_e32 v2, v2, v4
	v_lshrrev_b32_e32 v4, 4, v2
	v_bitop3_b32 v2, v4, v2, 32 bitop3:0x6c
	v_ashrrev_i32_e32 v5, 31, v2
	v_lshrrev_b32_e32 v5, 26, v5
	s_add_u32 s30, s9, 0x1730000
	v_lshlrev_b32_e32 v4, 3, v3
	v_add_u32_e32 v5, v2, v5
	s_addc_u32 s31, s8, 0
	v_and_b32_e32 v4, -16, v4
	v_ashrrev_i32_e32 v6, 6, v5
	s_ashr_i32 s3, s2, 31
	v_add_u32_e32 v4, v6, v4
	s_lshl_b64 s[12:13], s[2:3], 9
	s_ashr_i32 s4, s67, 31
	v_and_b32_e32 v6, 3, v6
	v_mul_lo_u32 v19, v4, s2
	s_lshl_b64 s[8:9], s[2:3], 8
	s_mul_i32 s4, s12, s4
	s_mul_hi_u32 s5, s12, s67
	s_lshr_b64 s[2:3], s[2:3], 23
	v_and_or_b32 v6, v4, s1, v6
	s_ashr_i32 s1, s0, 31
	s_add_i32 s4, s5, s4
	s_mul_i32 s2, s2, s67
	s_lshl_b64 s[18:19], s[0:1], 9
	s_add_i32 s20, s4, s2
	s_ashr_i32 s2, s66, 31
	s_mul_i32 s2, s18, s2
	s_mul_hi_u32 s3, s18, s66
	s_add_i32 s4, s3, s2
	s_lshr_b64 s[2:3], s[0:1], 23
	s_ashr_i32 s23, s7, 6
	s_mul_i32 s2, s2, s66
	s_ashr_i32 s33, s7, 8
	s_lshl_b64 s[10:11], s[0:1], 8
	s_lshl_b32 s22, s23, 10
	s_add_i32 s2, s4, s2
	s_mul_i32 s3, s18, s66
	s_add_u32 s4, s30, s3
	s_addc_u32 s5, s31, s2
	s_add_i32 s34, s26, 0x10000
	v_lshlrev_b32_e32 v3, 5, v3
	s_add_i32 s35, s34, s22
	v_and_b32_e32 v17, 32, v3
	v_and_b32_e32 v3, 0xc0, v5
	s_add_i32 s37, s35, 0x2000
	v_sub_u32_e32 v2, v2, v3
	v_lshlrev_b32_e32 v3, 1, v4
	v_lshrrev_b32_e32 v5, 2, v4
	s_add_u32 s2, s4, s10
	v_ashrrev_i16_sdwa v2, v201, sext(v2) dst_sel:DWORD dst_unused:UNUSED_PAD src0_sel:DWORD src1_sel:BYTE_0
	v_and_b32_e32 v3, 24, v3
	v_and_b32_e32 v5, 4, v5
	s_addc_u32 s3, s5, s11
	s_add_i32 s44, s26, 0x14000
	v_bfe_i32 v18, v2, 0, 16
	v_or3_b32 v3, v6, v5, v3
	s_add_i32 s46, s44, s22
	v_add_u32_e32 v2, v17, v18
	v_mul_lo_u32 v3, v3, s0
	s_mul_i32 s21, s12, s67
	s_mov_b32 m0, s35
	s_add_i32 s47, s46, 0x2000
	v_add_lshl_u32 v134, v3, v2, 1
	global_load_lds_dwordx4 v0, s[4:5]
	s_mov_b32 m0, s37
	s_add_u32 s28, s15, s21
	global_load_lds_dwordx4 v134, s[4:5]
	s_mov_b32 m0, s46
	s_addc_u32 s29, s16, s20
	s_add_i32 s50, s26, s22
	v_mov_b32_e32 v135, v1
	global_load_lds_dwordx4 v0, s[2:3]
	s_mov_b32 m0, s47
	s_add_i32 s51, s50, 0x2000
	v_lshl_add_u64 v[6:7], s[2:3], 0, v[0:1]
	v_lshl_add_u64 v[8:9], s[2:3], 0, v[134:135]
	global_load_lds_dwordx4 v134, s[2:3]
	s_mov_b32 m0, s50
	s_add_u32 s2, s28, s8
	v_add_lshl_u32 v132, v2, v19, 1
	global_load_lds_dwordx4 v130, s[28:29]
	s_mov_b32 m0, s51
	s_addc_u32 s3, s29, s9
	s_add_i32 s52, s50, 0x4000
	global_load_lds_dwordx4 v132, s[28:29]
	s_mov_b32 m0, s52
	s_add_i32 s53, s50, 0x6000
	global_load_lds_dwordx4 v130, s[2:3]
	s_mov_b32 m0, s53
	v_mov_b32_e32 v131, v1
	global_load_lds_dwordx4 v132, s[2:3]
	v_mov_b32_e32 v133, v1
	s_cmp_eq_u32 s33, 1
	v_lshl_add_u64 v[2:3], s[4:5], 0, v[0:1]
	v_lshl_add_u64 v[4:5], s[4:5], 0, v[134:135]
	v_lshl_add_u64 v[10:11], s[28:29], 0, v[130:131]
	v_lshl_add_u64 v[12:13], s[28:29], 0, v[132:133]
	s_cselect_b64 s[20:21], -1, 0
	s_cmp_lg_u32 s33, 1
	s_cbranch_scc1 .LBB0_752
	s_barrier
	s_setprio 1

.LBB0_763:
	v_add_u32_e32 v156, s34, v150
	v_add_u32_e32 v172, s44, v150
	ds_read_b128 v[140:143], v156
	ds_read_b128 v[144:147], v156 offset:1024
	ds_read_b128 v[152:155], v156 offset:2048
	ds_read_b128 v[156:159], v156 offset:3072
	ds_read_b128 v[160:163], v172
	ds_read_b128 v[164:167], v172 offset:1024
	ds_read_b128 v[168:171], v172 offset:2048
	ds_read_b128 v[172:175], v172 offset:3072
	s_add_i32 s83, s28, 2
	s_add_u32 s84, s4, 0x80
	s_addc_u32 s29, s5, 0
	s_cmp_eq_u32 s70, s28
	s_cselect_b32 s28, s0, s84
	s_cselect_b32 s29, s1, s29
	s_cselect_b32 s85, s27, s82
	s_cselect_b32 s84, s26, s81
	v_lshl_add_u64 v[176:177], s[4:5], 0, v[138:139]
	s_add_i32 m0, s50, 0xc000
	ds_read_b128 v[182:185], v151
	ds_read_b128 v[186:189], v151 offset:1024
	ds_read_b128 v[190:193], v151 offset:2048
	ds_read_b128 v[194:197], v151 offset:3072
	ds_read_b128 v[218:221], v151 offset:4096
	ds_read_b128 v[222:225], v151 offset:5120
	ds_read_b128 v[230:233], v151 offset:6144
	ds_read_b128 v[234:237], v151 offset:7168
	global_load_lds_dwordx4 v[176:177], off
	v_lshl_add_u64 v[176:177], s[4:5], 0, v[136:137]
	s_add_i32 m0, s50, 0xe000
	s_nop 0
	global_load_lds_dwordx4 v[176:177], off
	s_waitcnt vmcnt(8)
	s_waitcnt lgkmcnt(0)
	s_barrier
	s_waitcnt lgkmcnt(0)
	v_mfma_f32_16x16x32_bf16 v[122:125], v[140:143], v[182:185], v[122:125]
	v_mfma_f32_16x16x32_bf16 v[126:129], v[152:155], v[182:185], v[126:129]
	v_mfma_f32_16x16x32_bf16 v[110:113], v[140:143], v[190:193], v[110:113]
	v_mfma_f32_16x16x32_bf16 v[106:109], v[152:155], v[190:193], v[106:109]
	v_mfma_f32_16x16x32_bf16 v[94:97], v[140:143], v[218:221], v[94:97]
	v_mfma_f32_16x16x32_bf16 v[90:93], v[152:155], v[218:221], v[90:93]
	v_mfma_f32_16x16x32_bf16 v[78:81], v[140:143], v[230:233], v[78:81]
	v_mfma_f32_16x16x32_bf16 v[74:77], v[152:155], v[230:233], v[74:77]
	v_mfma_f32_16x16x32_bf16 v[122:125], v[144:147], v[186:189], v[122:125]
	v_mfma_f32_16x16x32_bf16 v[126:129], v[156:159], v[186:189], v[126:129]
	v_mfma_f32_16x16x32_bf16 v[110:113], v[144:147], v[194:197], v[110:113]
	v_mfma_f32_16x16x32_bf16 v[106:109], v[156:159], v[194:197], v[106:109]
	v_mfma_f32_16x16x32_bf16 v[94:97], v[144:147], v[222:225], v[94:97]
	v_mfma_f32_16x16x32_bf16 v[90:93], v[156:159], v[222:225], v[90:93]
	v_mfma_f32_16x16x32_bf16 v[78:81], v[144:147], v[234:237], v[78:81]
	v_mfma_f32_16x16x32_bf16 v[74:77], v[156:159], v[234:237], v[74:77]
	v_mfma_f32_16x16x32_bf16 v[118:121], v[160:163], v[182:185], v[118:121]
	v_mfma_f32_16x16x32_bf16 v[114:117], v[168:171], v[182:185], v[114:117]
	v_mfma_f32_16x16x32_bf16 v[102:105], v[160:163], v[190:193], v[102:105]
	v_mfma_f32_16x16x32_bf16 v[98:101], v[168:171], v[190:193], v[98:101]
	v_mfma_f32_16x16x32_bf16 v[86:89], v[160:163], v[218:221], v[86:89]
	v_mfma_f32_16x16x32_bf16 v[82:85], v[168:171], v[218:221], v[82:85]
	v_mfma_f32_16x16x32_bf16 v[70:73], v[160:163], v[230:233], v[70:73]
	v_mfma_f32_16x16x32_bf16 v[66:69], v[168:171], v[230:233], v[66:69]
	v_mfma_f32_16x16x32_bf16 v[118:121], v[164:167], v[186:189], v[118:121]
	v_mfma_f32_16x16x32_bf16 v[114:117], v[172:175], v[186:189], v[114:117]
	v_mfma_f32_16x16x32_bf16 v[102:105], v[164:167], v[194:197], v[102:105]
	v_mfma_f32_16x16x32_bf16 v[98:101], v[172:175], v[194:197], v[98:101]
	v_mfma_f32_16x16x32_bf16 v[86:89], v[164:167], v[222:225], v[86:89]
	v_mfma_f32_16x16x32_bf16 v[82:85], v[172:175], v[222:225], v[82:85]
	v_mfma_f32_16x16x32_bf16 v[70:73], v[164:167], v[234:237], v[70:73]
	v_mfma_f32_16x16x32_bf16 v[66:69], v[172:175], v[234:237], v[66:69]
	s_barrier
	s_mov_b32 m0, s35
	v_lshl_add_u64 v[176:177], s[84:85], 0, v[0:1]
	v_lshl_add_u64 v[198:199], s[84:85], 0, v[134:135]
	s_add_u32 s84, s84, s10
	ds_read_b128 v[182:185], v151 offset:16384
	ds_read_b128 v[186:189], v151 offset:17408
	ds_read_b128 v[190:193], v151 offset:18432
	ds_read_b128 v[194:197], v151 offset:19456
	ds_read_b128 v[218:221], v151 offset:20480
	ds_read_b128 v[222:225], v151 offset:21504
	ds_read_b128 v[230:233], v151 offset:22528
	ds_read_b128 v[234:237], v151 offset:23552
	global_load_lds_dwordx4 v[176:177], off
	s_mov_b32 m0, s37
	s_addc_u32 s85, s85, s11
	global_load_lds_dwordx4 v[198:199], off
	v_lshl_add_u64 v[238:239], s[84:85], 0, v[0:1]
	s_mov_b32 m0, s46
	v_lshl_add_u64 v[240:241], s[84:85], 0, v[134:135]
	global_load_lds_dwordx4 v[238:239], off
	s_mov_b32 m0, s47
	v_lshl_add_u64 v[242:243], s[28:29], 0, v[130:131]
	global_load_lds_dwordx4 v[240:241], off
	s_mov_b32 m0, s50
	v_lshl_add_u64 v[244:245], s[28:29], 0, v[132:133]
	global_load_lds_dwordx4 v[242:243], off
	s_mov_b32 m0, s51
	s_nop 0
	global_load_lds_dwordx4 v[244:245], off
	s_waitcnt vmcnt(8)
	s_waitcnt lgkmcnt(0)
	s_barrier
	s_waitcnt lgkmcnt(0)
	v_mfma_f32_16x16x32_bf16 v[62:65], v[140:143], v[182:185], v[62:65]
	v_mfma_f32_16x16x32_bf16 v[58:61], v[152:155], v[182:185], v[58:61]
	v_mfma_f32_16x16x32_bf16 v[46:49], v[140:143], v[190:193], v[46:49]
	v_mfma_f32_16x16x32_bf16 v[42:45], v[152:155], v[190:193], v[42:45]
	v_mfma_f32_16x16x32_bf16 v[30:33], v[140:143], v[218:221], v[30:33]
	v_mfma_f32_16x16x32_bf16 v[26:29], v[152:155], v[218:221], v[26:29]
	v_mfma_f32_16x16x32_bf16 v[14:17], v[140:143], v[230:233], v[14:17]
	v_mfma_f32_16x16x32_bf16 v[10:13], v[152:155], v[230:233], v[10:13]
	v_mfma_f32_16x16x32_bf16 v[62:65], v[144:147], v[186:189], v[62:65]
	v_mfma_f32_16x16x32_bf16 v[58:61], v[156:159], v[186:189], v[58:61]
	v_mfma_f32_16x16x32_bf16 v[46:49], v[144:147], v[194:197], v[46:49]
	v_mfma_f32_16x16x32_bf16 v[42:45], v[156:159], v[194:197], v[42:45]
	v_mfma_f32_16x16x32_bf16 v[30:33], v[144:147], v[222:225], v[30:33]
	v_mfma_f32_16x16x32_bf16 v[26:29], v[156:159], v[222:225], v[26:29]
	v_mfma_f32_16x16x32_bf16 v[14:17], v[144:147], v[234:237], v[14:17]
	v_mfma_f32_16x16x32_bf16 v[10:13], v[156:159], v[234:237], v[10:13]
	v_mfma_f32_16x16x32_bf16 v[54:57], v[160:163], v[182:185], v[54:57]
	v_mfma_f32_16x16x32_bf16 v[50:53], v[168:171], v[182:185], v[50:53]
	v_mfma_f32_16x16x32_bf16 v[38:41], v[160:163], v[190:193], v[38:41]
	v_mfma_f32_16x16x32_bf16 v[34:37], v[168:171], v[190:193], v[34:37]
	v_mfma_f32_16x16x32_bf16 v[22:25], v[160:163], v[218:221], v[22:25]
	v_mfma_f32_16x16x32_bf16 v[18:21], v[168:171], v[218:221], v[18:21]
	v_mfma_f32_16x16x32_bf16 v[6:9], v[160:163], v[230:233], v[6:9]
	v_mfma_f32_16x16x32_bf16 v[2:5], v[168:171], v[230:233], v[2:5]
	v_mfma_f32_16x16x32_bf16 v[54:57], v[164:167], v[186:189], v[54:57]
	v_mfma_f32_16x16x32_bf16 v[50:53], v[172:175], v[186:189], v[50:53]
	v_mfma_f32_16x16x32_bf16 v[38:41], v[164:167], v[194:197], v[38:41]
	v_mfma_f32_16x16x32_bf16 v[34:37], v[172:175], v[194:197], v[34:37]
	v_mfma_f32_16x16x32_bf16 v[22:25], v[164:167], v[222:225], v[22:25]
	v_mfma_f32_16x16x32_bf16 v[18:21], v[172:175], v[222:225], v[18:21]
	v_mfma_f32_16x16x32_bf16 v[6:9], v[164:167], v[234:237], v[6:9]
	v_mfma_f32_16x16x32_bf16 v[2:5], v[172:175], v[234:237], v[2:5]
	s_barrier
	v_add_u32_e32 v156, s58, v150
	v_add_u32_e32 v172, s63, v150
	ds_read_b128 v[140:143], v156
	ds_read_b128 v[144:147], v156 offset:1024
	ds_read_b128 v[152:155], v156 offset:2048
	ds_read_b128 v[156:159], v156 offset:3072
	ds_read_b128 v[160:163], v172
	ds_read_b128 v[164:167], v172 offset:1024
	ds_read_b128 v[168:171], v172 offset:2048
	ds_read_b128 v[172:175], v172 offset:3072
	s_add_u32 s28, s28, s8
	s_addc_u32 s29, s29, s9
	s_mov_b32 m0, s52
	v_lshl_add_u64 v[246:247], s[28:29], 0, v[130:131]
	ds_read_b128 v[182:185], v151 offset:32768
	ds_read_b128 v[186:189], v151 offset:33792
	ds_read_b128 v[190:193], v151 offset:34816
	ds_read_b128 v[194:197], v151 offset:35840
	ds_read_b128 v[218:221], v151 offset:36864
	ds_read_b128 v[222:225], v151 offset:37888
	ds_read_b128 v[230:233], v151 offset:38912
	ds_read_b128 v[234:237], v151 offset:39936
	global_load_lds_dwordx4 v[246:247], off
	v_lshl_add_u64 v[246:247], s[28:29], 0, v[132:133]
	s_mov_b32 m0, s53
	s_nop 0
	global_load_lds_dwordx4 v[246:247], off
	s_waitcnt vmcnt(8)
	s_waitcnt lgkmcnt(0)
	s_barrier
	s_waitcnt lgkmcnt(0)
	v_mfma_f32_16x16x32_bf16 v[122:125], v[140:143], v[182:185], v[122:125]
	v_mfma_f32_16x16x32_bf16 v[126:129], v[152:155], v[182:185], v[126:129]
	v_mfma_f32_16x16x32_bf16 v[110:113], v[140:143], v[190:193], v[110:113]
	v_mfma_f32_16x16x32_bf16 v[106:109], v[152:155], v[190:193], v[106:109]
	v_mfma_f32_16x16x32_bf16 v[94:97], v[140:143], v[218:221], v[94:97]
	v_mfma_f32_16x16x32_bf16 v[90:93], v[152:155], v[218:221], v[90:93]
	v_mfma_f32_16x16x32_bf16 v[78:81], v[140:143], v[230:233], v[78:81]
	v_mfma_f32_16x16x32_bf16 v[74:77], v[152:155], v[230:233], v[74:77]
	v_mfma_f32_16x16x32_bf16 v[122:125], v[144:147], v[186:189], v[122:125]
	v_mfma_f32_16x16x32_bf16 v[126:129], v[156:159], v[186:189], v[126:129]
	v_mfma_f32_16x16x32_bf16 v[110:113], v[144:147], v[194:197], v[110:113]
	v_mfma_f32_16x16x32_bf16 v[106:109], v[156:159], v[194:197], v[106:109]
	v_mfma_f32_16x16x32_bf16 v[94:97], v[144:147], v[222:225], v[94:97]
	v_mfma_f32_16x16x32_bf16 v[90:93], v[156:159], v[222:225], v[90:93]
	v_mfma_f32_16x16x32_bf16 v[78:81], v[144:147], v[234:237], v[78:81]
	v_mfma_f32_16x16x32_bf16 v[74:77], v[156:159], v[234:237], v[74:77]
	v_mfma_f32_16x16x32_bf16 v[118:121], v[160:163], v[182:185], v[118:121]
	v_mfma_f32_16x16x32_bf16 v[114:117], v[168:171], v[182:185], v[114:117]
	v_mfma_f32_16x16x32_bf16 v[102:105], v[160:163], v[190:193], v[102:105]
	v_mfma_f32_16x16x32_bf16 v[98:101], v[168:171], v[190:193], v[98:101]
	v_mfma_f32_16x16x32_bf16 v[86:89], v[160:163], v[218:221], v[86:89]
	v_mfma_f32_16x16x32_bf16 v[82:85], v[168:171], v[218:221], v[82:85]
	v_mfma_f32_16x16x32_bf16 v[70:73], v[160:163], v[230:233], v[70:73]
	v_mfma_f32_16x16x32_bf16 v[66:69], v[168:171], v[230:233], v[66:69]
	v_mfma_f32_16x16x32_bf16 v[118:121], v[164:167], v[186:189], v[118:121]
	v_mfma_f32_16x16x32_bf16 v[114:117], v[172:175], v[186:189], v[114:117]
	v_mfma_f32_16x16x32_bf16 v[102:105], v[164:167], v[194:197], v[102:105]
	v_mfma_f32_16x16x32_bf16 v[98:101], v[172:175], v[194:197], v[98:101]
	v_mfma_f32_16x16x32_bf16 v[86:89], v[164:167], v[222:225], v[86:89]
	v_mfma_f32_16x16x32_bf16 v[82:85], v[172:175], v[222:225], v[82:85]
	v_mfma_f32_16x16x32_bf16 v[70:73], v[164:167], v[234:237], v[70:73]
	v_mfma_f32_16x16x32_bf16 v[66:69], v[172:175], v[234:237], v[66:69]
	s_barrier
	s_mov_b32 m0, s59
	v_lshl_add_u64 v[176:177], v[176:177], 0, s[48:49]
	ds_read_b128 v[182:185], v151 offset:49152
	ds_read_b128 v[186:189], v151 offset:50176
	ds_read_b128 v[190:193], v151 offset:51200
	ds_read_b128 v[194:197], v151 offset:52224
	ds_read_b128 v[218:221], v151 offset:53248
	ds_read_b128 v[222:225], v151 offset:54272
	ds_read_b128 v[230:233], v151 offset:55296
	ds_read_b128 v[234:237], v151 offset:56320
	global_load_lds_dwordx4 v[176:177], off
	v_lshl_add_u64 v[176:177], v[198:199], 0, s[48:49]
	s_mov_b32 m0, s60
	s_nop 0
	global_load_lds_dwordx4 v[176:177], off
	v_lshl_add_u64 v[176:177], v[238:239], 0, s[48:49]
	s_mov_b32 m0, s64
	s_nop 0
	global_load_lds_dwordx4 v[176:177], off
	v_lshl_add_u64 v[176:177], v[240:241], 0, s[48:49]
	s_mov_b32 m0, s65
	s_nop 0
	global_load_lds_dwordx4 v[176:177], off
	v_lshl_add_u64 v[176:177], v[242:243], 0, s[48:49]
	s_mov_b32 m0, s61
	s_nop 0
	global_load_lds_dwordx4 v[176:177], off
	v_lshl_add_u64 v[176:177], v[244:245], 0, s[48:49]
	s_mov_b32 m0, s62
	s_nop 0
	global_load_lds_dwordx4 v[176:177], off
	s_waitcnt vmcnt(8)
	s_waitcnt lgkmcnt(0)
	s_barrier
	s_waitcnt lgkmcnt(0)
	v_mfma_f32_16x16x32_bf16 v[62:65], v[140:143], v[182:185], v[62:65]
	v_mfma_f32_16x16x32_bf16 v[58:61], v[152:155], v[182:185], v[58:61]
	v_mfma_f32_16x16x32_bf16 v[46:49], v[140:143], v[190:193], v[46:49]
	v_mfma_f32_16x16x32_bf16 v[42:45], v[152:155], v[190:193], v[42:45]
	v_mfma_f32_16x16x32_bf16 v[30:33], v[140:143], v[218:221], v[30:33]
	v_mfma_f32_16x16x32_bf16 v[26:29], v[152:155], v[218:221], v[26:29]
	v_mfma_f32_16x16x32_bf16 v[14:17], v[140:143], v[230:233], v[14:17]
	v_mfma_f32_16x16x32_bf16 v[10:13], v[152:155], v[230:233], v[10:13]
	v_mfma_f32_16x16x32_bf16 v[62:65], v[144:147], v[186:189], v[62:65]
	v_mfma_f32_16x16x32_bf16 v[58:61], v[156:159], v[186:189], v[58:61]
	v_mfma_f32_16x16x32_bf16 v[46:49], v[144:147], v[194:197], v[46:49]
	v_mfma_f32_16x16x32_bf16 v[42:45], v[156:159], v[194:197], v[42:45]
	v_mfma_f32_16x16x32_bf16 v[30:33], v[144:147], v[222:225], v[30:33]
	v_mfma_f32_16x16x32_bf16 v[26:29], v[156:159], v[222:225], v[26:29]
	v_mfma_f32_16x16x32_bf16 v[14:17], v[144:147], v[234:237], v[14:17]
	v_mfma_f32_16x16x32_bf16 v[10:13], v[156:159], v[234:237], v[10:13]
	v_mfma_f32_16x16x32_bf16 v[54:57], v[160:163], v[182:185], v[54:57]
	v_mfma_f32_16x16x32_bf16 v[50:53], v[168:171], v[182:185], v[50:53]
	v_mfma_f32_16x16x32_bf16 v[38:41], v[160:163], v[190:193], v[38:41]
	v_mfma_f32_16x16x32_bf16 v[34:37], v[168:171], v[190:193], v[34:37]
	v_mfma_f32_16x16x32_bf16 v[22:25], v[160:163], v[218:221], v[22:25]
	v_mfma_f32_16x16x32_bf16 v[18:21], v[168:171], v[218:221], v[18:21]
	v_mfma_f32_16x16x32_bf16 v[6:9], v[160:163], v[230:233], v[6:9]
	v_mfma_f32_16x16x32_bf16 v[2:5], v[168:171], v[230:233], v[2:5]
	v_mfma_f32_16x16x32_bf16 v[54:57], v[164:167], v[186:189], v[54:57]
	v_mfma_f32_16x16x32_bf16 v[50:53], v[172:175], v[186:189], v[50:53]
	v_mfma_f32_16x16x32_bf16 v[38:41], v[164:167], v[194:197], v[38:41]
	v_mfma_f32_16x16x32_bf16 v[34:37], v[172:175], v[194:197], v[34:37]
	v_mfma_f32_16x16x32_bf16 v[22:25], v[164:167], v[222:225], v[22:25]
	v_mfma_f32_16x16x32_bf16 v[18:21], v[172:175], v[222:225], v[18:21]
	v_mfma_f32_16x16x32_bf16 v[6:9], v[164:167], v[234:237], v[6:9]
	v_mfma_f32_16x16x32_bf16 v[2:5], v[172:175], v[234:237], v[2:5]
	s_barrier
	s_add_u32 s81, s81, 0x100
	s_addc_u32 s82, s82, 0
	s_add_u32 s4, s4, 0x100
	s_addc_u32 s5, s5, 0
	s_cmp_ge_i32 s83, s55
	s_mov_b32 s28, s83
	s_cbranch_scc0 .LBB0_763

.LBB0_802:
	s_mov_b32 s0, s45
	s_add_i32 s0, s0, 0x200e8
	v_mov_b32_e32 v0, s0
	ds_read_b64 v[2:3], v0
	s_mov_b32 s16, 0
	s_setprio 0
	s_getreg_b32 s0, hwreg(HW_REG_XCC_ID, 0, 4)
	s_waitcnt vmcnt(0)
	s_waitcnt lgkmcnt(0)
	v_readfirstlane_b32 s73, v3
	v_readfirstlane_b32 s72, v2
	s_waitcnt vmcnt(0)
	s_barrier
	s_mov_b64 s[70:71], exec
	v_readlane_b32 s2, v252, 1
	v_readlane_b32 s3, v252, 2
	s_and_b64 s[2:3], s[70:71], s[2:3]
	s_mov_b32 s58, 0x3fb8aa3b
	s_movk_i32 s59, 0xe80
	s_mov_b32 s63, 0xc2fc0000
	s_mov_b32 s66, 0x1ffff
	s_movk_i32 s67, 0x1ff
	s_mov_b64 exec, s[2:3]
	s_cbranch_execz .LBB0_846
	s_add_i32 s15, s16, 0x20200
	v_mov_b32_e32 v0, s15
	s_waitcnt vmcnt(0) expcnt(0) lgkmcnt(0)
	ds_read_b32 v2, v0
	s_add_i32 s16, s16, 0x20204
	v_mov_b32_e32 v0, s16
	ds_read_b32 v0, v0
	s_and_b32 s14, s0, 15
	s_waitcnt lgkmcnt(1)
	v_cmp_ne_u32_e32 vcc, 0, v2
	s_cbranch_vccnz .LBB0_817
	s_add_u32 s0, s72, 0x1000
	s_addc_u32 s1, s73, 0
	s_add_u32 s2, s72, 0x1100
	s_addc_u32 s3, s73, 0
	s_add_u32 s4, s72, 0x1200
	s_addc_u32 s5, s73, 0
	s_add_u32 s6, s72, 0x1300
	s_addc_u32 s7, s73, 0
	s_mov_b32 s30, 1
	s_mov_b64 s[8:9], 0
	s_branch .LBB0_807

.LBB0_919:
	s_mov_b32 s0, s45
	s_waitcnt lgkmcnt(0)
	s_barrier
	s_add_i32 s0, s0, 0x200e8
	v_mov_b32_e32 v0, s0
	ds_read_b64 v[2:3], v0
	s_mov_b32 s16, 0
	s_setprio 0
	s_getreg_b32 s0, hwreg(HW_REG_XCC_ID, 0, 4)
	s_waitcnt vmcnt(0)
	s_waitcnt lgkmcnt(0)
	v_readfirstlane_b32 s73, v3
	v_readfirstlane_b32 s72, v2
	s_barrier
	s_mov_b64 s[68:69], exec
	v_readlane_b32 s2, v252, 1
	v_readlane_b32 s3, v252, 2
	s_and_b64 s[2:3], s[68:69], s[2:3]
	s_mov_b64 exec, s[2:3]
	s_cbranch_execz .LBB0_963
	s_add_i32 s15, s16, 0x20200
	v_mov_b32_e32 v0, s15
	s_waitcnt vmcnt(0) expcnt(0) lgkmcnt(0)
	ds_read_b32 v2, v0
	s_add_i32 s16, s16, 0x20204
	v_mov_b32_e32 v0, s16
	ds_read_b32 v0, v0
	s_and_b32 s14, s0, 15
	s_waitcnt lgkmcnt(1)
	v_cmp_ne_u32_e32 vcc, 0, v2
	s_cbranch_vccnz .LBB0_934
	s_add_u32 s0, s72, 0x1000
	s_addc_u32 s1, s73, 0
	s_add_u32 s2, s72, 0x1100
	s_addc_u32 s3, s73, 0
	s_add_u32 s4, s72, 0x1200
	s_addc_u32 s5, s73, 0
	s_add_u32 s6, s72, 0x1300
	s_addc_u32 s7, s73, 0
	s_mov_b32 s30, 1
	s_mov_b64 s[8:9], 0
	s_branch .LBB0_924

.LBB0_966:
	s_or_b64 exec, exec, s[2:3]
	s_mov_b32 s0, s45
	s_add_i32 s0, s0, 0x200e8
	v_mov_b32_e32 v0, s0
	ds_read_b64 v[2:3], v0
	s_mov_b32 s16, 0
	s_setprio 0
	s_getreg_b32 s0, hwreg(HW_REG_XCC_ID, 0, 4)
	s_waitcnt vmcnt(0)
	s_waitcnt lgkmcnt(0)
	v_readfirstlane_b32 s71, v3
	v_readfirstlane_b32 s70, v2
	s_barrier
	s_mov_b64 s[68:69], exec
	v_readlane_b32 s2, v252, 1
	v_readlane_b32 s3, v252, 2
	s_and_b64 s[2:3], s[68:69], s[2:3]
	s_mov_b64 exec, s[2:3]
	s_cbranch_execz .LBB0_1010
	s_add_i32 s15, s16, 0x20200
	v_mov_b32_e32 v0, s15
	s_waitcnt vmcnt(0) expcnt(0) lgkmcnt(0)
	ds_read_b32 v2, v0
	s_add_i32 s16, s16, 0x20204
	v_mov_b32_e32 v0, s16
	ds_read_b32 v0, v0
	s_and_b32 s14, s0, 15
	s_waitcnt lgkmcnt(1)
	v_cmp_ne_u32_e32 vcc, 0, v2
	s_cbranch_vccnz .LBB0_981
	s_add_u32 s0, s70, 0x1000
	s_addc_u32 s1, s71, 0
	s_add_u32 s2, s70, 0x1100
	s_addc_u32 s3, s71, 0
	s_add_u32 s4, s70, 0x1200
	s_addc_u32 s5, s71, 0
	s_add_u32 s6, s70, 0x1300
	s_addc_u32 s7, s71, 0
	s_mov_b32 s30, 1
	s_mov_b64 s[8:9], 0
	s_branch .LBB0_971

.LBB0_1010:
	s_or_b64 exec, exec, s[68:69]
	s_mov_b32 s90, s45
	s_mov_b32 s24, 0
	s_mov_b32 s0, 0
	s_waitcnt lgkmcnt(0)
	s_barrier
	s_add_i32 s0, s0, 0x200e8
	v_mov_b32_e32 v0, s0
	s_mov_b32 s0, 0
	ds_read_b64 v[2:3], v0
	s_add_i32 s0, s0, 0x200e8
	v_mov_b32_e32 v0, s0
	s_movk_i32 s0, 0x200
	s_movk_i32 s2, 0x1740
	s_movk_i32 s4, 0x400
	ds_read_b64 v[4:5], v0
	s_ashr_i32 s5, s4, 31
	s_lshr_b32 s5, s5, 24
	s_add_i32 s4, s4, s5
	s_ashr_i32 s16, s4, 8
	v_readlane_b32 s14, v252, 0
	s_lshl_b32 s4, s16, 7
	v_mov_b32_e32 v20, v200
	s_waitcnt lgkmcnt(0)
	v_readfirstlane_b32 s1, v3
	v_readfirstlane_b32 s3, v2
	v_readfirstlane_b32 s6, v5
	v_readfirstlane_b32 s7, v4
	s_cmp_ge_i32 s14, s4
	v_readfirstlane_b32 s5, v20
	s_cbranch_scc1 .LBB0_1031
	v_lshlrev_b32_e32 v0, 4, v20
	v_add_u32_e32 v2, 0x2000, v0
	v_ashrrev_i32_e32 v3, 31, v2
	v_lshrrev_b32_e32 v3, 22, v3
	v_add_u32_e32 v3, v2, v3
	v_ashrrev_i32_e32 v3, 10, v3
	v_mul_i32_i24_e32 v4, 0x400, v3
	v_sub_u32_e32 v2, v2, v4
	v_lshrrev_b32_e32 v4, 4, v2
	v_bitop3_b32 v2, v4, v2, 32 bitop3:0x6c
	v_ashrrev_i32_e32 v4, 31, v2
	v_lshrrev_b32_e32 v4, 26, v4
	v_add_u32_e32 v4, v2, v4
	v_lshlrev_b32_e32 v6, 3, v3
	v_ashrrev_i32_e32 v5, 6, v4
	v_and_b32_e32 v6, -16, v6
	v_lshlrev_b32_e32 v3, 5, v3
	v_add_u32_e32 v6, v5, v6
	v_and_b32_e32 v14, 32, v3
	v_and_b32_e32 v3, 0xc0, v4
	v_and_b32_e32 v5, 3, v5
	s_mov_b32 s18, 0x7fffffe0
	v_lshrrev_b32_e32 v7, 2, v6
	v_lshlrev_b32_e32 v8, 1, v6
	v_sub_u32_e32 v2, v2, v3
	v_and_or_b32 v5, v6, s18, v5
	v_and_b32_e32 v7, 4, v7
	v_and_b32_e32 v8, 24, v8
	v_ashrrev_i16_sdwa v2, v201, sext(v2) dst_sel:DWORD dst_unused:UNUSED_PAD src0_sel:DWORD src1_sel:BYTE_0
	v_or3_b32 v5, v5, v7, v8
	v_bfe_i32 v15, v2, 0, 16
	v_mul_lo_u32 v5, v5, s0
	v_add_u32_e32 v2, v14, v15
	v_mul_lo_u32 v16, v6, s2
	v_add_lshl_u32 v130, v5, v2, 1
	v_add_lshl_u32 v132, v2, v16, 1
	v_bfe_i32 v2, v20, 27, 1
	v_lshrrev_b32_e32 v2, 22, v2
	v_add_u32_e32 v2, v0, v2
	v_and_b32_e32 v2, 0xfffffc00, v2
	v_sub_u32_e32 v0, v0, v2
	v_lshrrev_b32_e32 v2, 4, v0
	v_ashrrev_i32_e32 v4, 31, v20
	v_bitop3_b32 v0, v2, v0, 32 bitop3:0x6c
	v_lshrrev_b32_e32 v4, 26, v4
	v_ashrrev_i32_e32 v2, 31, v0
	v_add_u32_e32 v4, v20, v4
	v_lshrrev_b32_e32 v2, 26, v2
	v_ashrrev_i32_e32 v4, 6, v4
	v_add_u32_e32 v2, v0, v2
	v_lshlrev_b32_e32 v5, 3, v4
	v_ashrrev_i32_e32 v3, 6, v2
	v_and_b32_e32 v5, -16, v5
	s_add_u32 s15, s3, 0x8bf0000
	v_add_u32_e32 v5, v3, v5
	v_and_b32_e32 v2, 0xc0, v2
	s_addc_u32 s30, s1, 0
	v_and_b32_e32 v3, 3, v3
	v_lshrrev_b32_e32 v6, 2, v5
	v_lshlrev_b32_e32 v7, 1, v5
	v_sub_u32_e32 v0, v0, v2
	s_add_u32 s31, s7, 0x1770000
	v_and_or_b32 v3, v5, s18, v3
	v_and_b32_e32 v6, 4, v6
	v_and_b32_e32 v7, 24, v7
	v_lshlrev_b32_e32 v4, 5, v4
	v_ashrrev_i16_sdwa v0, v201, sext(v0) dst_sel:DWORD dst_unused:UNUSED_PAD src0_sel:DWORD src1_sel:BYTE_0
	s_addc_u32 s33, s6, 0
	v_or3_b32 v3, v3, v6, v7
	v_and_b32_e32 v17, 32, v4
	v_bfe_i32 v18, v0, 0, 16
	s_lshl_b32 s50, s16, 3
	v_mul_lo_u32 v3, v3, s0
	v_add_u32_e32 v2, v17, v18
	v_mul_lo_u32 v19, v5, s2
	s_abs_i32 s53, s50
	v_add_lshl_u32 v0, v3, v2, 1
	v_add_lshl_u32 v134, v2, v19, 1
	v_cvt_f32_u32_e32 v2, s53
	s_ashr_i32 s44, s14, 31
	s_lshr_b32 s18, s44, 29
	s_add_i32 s18, s14, s18
	v_rcp_iflag_f32_e32 v2, v2
	s_ashr_i32 s19, s18, 3
	s_and_b32 s18, s18, -8
	s_sub_i32 s18, s14, s18
	v_mul_f32_e32 v2, 0x4f7ffffe, v2
	v_cvt_u32_f32_e32 v2, v2
	s_lshl_b32 s35, s16, 4
	s_lshr_b32 s22, s18, 31
	s_or_b32 s22, s35, s22
	s_mul_i32 s18, s22, s18
	s_sub_i32 s22, 0, s53
	v_readfirstlane_b32 s55, v2
	s_add_i32 s18, s18, s19
	s_mul_i32 s22, s22, s55
	s_ashr_i32 s19, s18, 31
	s_bfe_i32 s51, s16, 0x1001c
	s_mul_hi_u32 s22, s55, s22
	s_xor_b32 s16, s19, s51
	s_abs_i32 s19, s18
	s_add_i32 s55, s55, s22
	s_mul_hi_u32 s22, s19, s55
	s_mul_i32 s23, s22, s53
	s_ashr_i32 s21, s5, 6
	s_ashr_i32 s3, s2, 31
	s_ashr_i32 s1, s0, 31
	s_sub_i32 s19, s19, s23
	s_ashr_i32 s34, s5, 8
	s_lshl_b64 s[6:7], s[2:3], 8
	s_lshl_b64 s[8:9], s[0:1], 8
	s_lshl_b64 s[10:11], s[2:3], 9
	s_lshl_b64 s[12:13], s[0:1], 9
	s_lshl_b32 s20, s21, 10
	s_add_i32 s23, s22, 1
	s_sub_i32 s25, s19, s53
	s_cmp_ge_u32 s19, s53
	s_cselect_b32 s22, s23, s22
	s_cselect_b32 s19, s25, s19
	s_add_i32 s23, s22, 1
	s_cmp_ge_u32 s19, s53
	s_cselect_b32 s19, s23, s22
	s_xor_b32 s19, s19, s16
	s_sub_i32 s16, s19, s16
	s_lshl_b32 s19, s16, 3
	s_sub_i32 s22, 0x80, s19
	s_min_i32 s22, s22, 8
	s_abs_i32 s25, s22
	v_cvt_f32_u32_e32 v2, s25
	s_sub_i32 s26, 0, s25
	s_mul_i32 s16, s16, s50
	s_sub_i32 s18, s18, s16
	v_rcp_iflag_f32_e32 v2, v2
	s_abs_i32 s23, s18
	s_xor_b32 s16, s18, s22
	s_ashr_i32 s16, s16, 31
	v_mul_f32_e32 v2, 0x4f7ffffe, v2
	v_cvt_u32_f32_e32 v2, v2
	v_mov_b32_e32 v131, v1
	v_mov_b32_e32 v135, v1
	v_mov_b32_e32 v133, v1
	v_readfirstlane_b32 s27, v2
	s_mul_i32 s26, s26, s27
	s_mul_hi_u32 s26, s27, s26
	s_add_i32 s27, s27, s26
	s_mul_hi_u32 s26, s23, s27
	s_mul_i32 s27, s26, s25
	s_sub_i32 s23, s23, s27
	s_add_i32 s27, s26, 1
	s_sub_i32 s28, s23, s25
	s_cmp_ge_u32 s23, s25
	s_cselect_b32 s26, s27, s26
	s_cselect_b32 s23, s28, s23
	s_add_i32 s27, s26, 1
	s_cmp_ge_u32 s23, s25
	s_cselect_b32 s23, s27, s26
	s_xor_b32 s23, s23, s16
	s_sub_i32 s16, s23, s16
	s_mul_i32 s22, s16, s22
	s_sub_i32 s18, s18, s22
	s_add_i32 s37, s18, s19
	s_ashr_i32 s18, s37, 31
	s_mul_i32 s18, s10, s18
	s_mul_hi_u32 s19, s10, s37
	s_lshr_b64 s[2:3], s[2:3], 23
	s_add_i32 s18, s19, s18
	s_mul_i32 s2, s2, s37
	s_add_i32 s18, s18, s2
	s_ashr_i32 s2, s16, 31
	s_mul_i32 s2, s12, s2
	s_mul_hi_u32 s3, s12, s16
	s_add_i32 s22, s3, s2
	s_lshr_b64 s[2:3], s[0:1], 23
	s_mul_i32 s2, s2, s16
	s_add_i32 s22, s22, s2
	s_mul_i32 s2, s12, s16
	s_add_u32 s26, s31, s2
	s_addc_u32 s27, s33, s22
	s_add_i32 s66, s24, 0x10000
	s_add_i32 s67, s66, s20
	s_add_i32 s68, s67, 0x2000
	s_add_u32 s2, s26, s8
	s_addc_u32 s3, s27, s9
	s_add_i32 s69, s24, 0x14000
	s_add_i32 s70, s69, s20
	s_mul_i32 s19, s10, s37
	s_mov_b32 m0, s67
	s_add_i32 s71, s70, 0x2000
	global_load_lds_dwordx4 v0, s[26:27]
	s_mov_b32 m0, s68
	s_add_u32 s28, s15, s19
	global_load_lds_dwordx4 v130, s[26:27]
	s_mov_b32 m0, s70
	s_addc_u32 s29, s30, s18
	s_add_i32 s72, s24, s20
	global_load_lds_dwordx4 v0, s[2:3]
	s_mov_b32 m0, s71
	s_add_i32 s73, s72, 0x2000
	v_lshl_add_u64 v[6:7], s[2:3], 0, v[0:1]
	v_lshl_add_u64 v[8:9], s[2:3], 0, v[130:131]
	global_load_lds_dwordx4 v130, s[2:3]
	s_mov_b32 m0, s72
	s_add_u32 s2, s28, s6
	global_load_lds_dwordx4 v134, s[28:29]
	s_mov_b32 m0, s73
	s_addc_u32 s3, s29, s7
	s_add_i32 s74, s72, 0x4000
	global_load_lds_dwordx4 v132, s[28:29]
	s_mov_b32 m0, s74
	s_add_i32 s75, s72, 0x6000
	global_load_lds_dwordx4 v134, s[2:3]
	s_mov_b32 m0, s75
	s_cmp_eq_u32 s34, 1
	global_load_lds_dwordx4 v132, s[2:3]
	v_lshl_add_u64 v[2:3], s[26:27], 0, v[0:1]
	v_lshl_add_u64 v[4:5], s[26:27], 0, v[130:131]
	v_lshl_add_u64 v[10:11], s[28:29], 0, v[134:135]
	v_lshl_add_u64 v[12:13], s[28:29], 0, v[132:133]
	s_cselect_b64 s[18:19], -1, 0
	s_cmp_lg_u32 s34, 1
	s_cbranch_scc1 .LBB0_1013
	s_barrier
	s_setprio 1

.LBB0_1024:
	v_add_u32_e32 v144, s66, v148
	ds_read_b128 v[140:143], v144
	ds_read_b128 v[150:153], v144 offset:1024
	ds_read_b128 v[154:157], v144 offset:2048
	ds_read_b128 v[158:161], v144 offset:3072
	v_add_u32_e32 v144, s69, v148
	ds_read_b128 v[162:165], v144
	ds_read_b128 v[166:169], v144 offset:1024
	ds_read_b128 v[170:173], v144 offset:2048
	ds_read_b128 v[174:177], v144 offset:3072
	s_add_i32 s52, s28, 2
	s_add_u32 s54, s26, 0x80
	s_addc_u32 s29, s27, 0
	s_cmp_eq_u32 s88, s28
	s_cselect_b32 s28, s0, s54
	s_cselect_b32 s29, s1, s29
	s_cselect_b32 s59, s25, s47
	s_cselect_b32 s58, s24, s46
	v_lshl_add_u64 v[144:145], s[26:27], 0, v[138:139]
	s_add_i32 m0, s72, 0xc000
	ds_read_b128 v[182:185], v149
	ds_read_b128 v[186:189], v149 offset:1024
	ds_read_b128 v[190:193], v149 offset:2048
	ds_read_b128 v[194:197], v149 offset:3072
	ds_read_b128 v[218:221], v149 offset:4096
	ds_read_b128 v[222:225], v149 offset:5120
	ds_read_b128 v[230:233], v149 offset:6144
	ds_read_b128 v[234:237], v149 offset:7168
	global_load_lds_dwordx4 v[144:145], off
	v_lshl_add_u64 v[144:145], s[26:27], 0, v[136:137]
	s_add_i32 m0, s72, 0xe000
	s_nop 0
	global_load_lds_dwordx4 v[144:145], off
	s_waitcnt vmcnt(8)
	s_waitcnt lgkmcnt(0)
	s_barrier
	s_waitcnt lgkmcnt(0)
	v_mfma_f32_16x16x32_bf16 v[126:129], v[140:143], v[182:185], v[126:129]
	v_mfma_f32_16x16x32_bf16 v[122:125], v[154:157], v[182:185], v[122:125]
	v_mfma_f32_16x16x32_bf16 v[110:113], v[140:143], v[190:193], v[110:113]
	v_mfma_f32_16x16x32_bf16 v[106:109], v[154:157], v[190:193], v[106:109]
	v_mfma_f32_16x16x32_bf16 v[94:97], v[140:143], v[218:221], v[94:97]
	v_mfma_f32_16x16x32_bf16 v[90:93], v[154:157], v[218:221], v[90:93]
	v_mfma_f32_16x16x32_bf16 v[78:81], v[140:143], v[230:233], v[78:81]
	v_mfma_f32_16x16x32_bf16 v[74:77], v[154:157], v[230:233], v[74:77]
	v_mfma_f32_16x16x32_bf16 v[126:129], v[150:153], v[186:189], v[126:129]
	v_mfma_f32_16x16x32_bf16 v[122:125], v[158:161], v[186:189], v[122:125]
	v_mfma_f32_16x16x32_bf16 v[110:113], v[150:153], v[194:197], v[110:113]
	v_mfma_f32_16x16x32_bf16 v[106:109], v[158:161], v[194:197], v[106:109]
	v_mfma_f32_16x16x32_bf16 v[94:97], v[150:153], v[222:225], v[94:97]
	v_mfma_f32_16x16x32_bf16 v[90:93], v[158:161], v[222:225], v[90:93]
	v_mfma_f32_16x16x32_bf16 v[78:81], v[150:153], v[234:237], v[78:81]
	v_mfma_f32_16x16x32_bf16 v[74:77], v[158:161], v[234:237], v[74:77]
	v_mfma_f32_16x16x32_bf16 v[118:121], v[162:165], v[182:185], v[118:121]
	v_mfma_f32_16x16x32_bf16 v[114:117], v[170:173], v[182:185], v[114:117]
	v_mfma_f32_16x16x32_bf16 v[102:105], v[162:165], v[190:193], v[102:105]
	v_mfma_f32_16x16x32_bf16 v[98:101], v[170:173], v[190:193], v[98:101]
	v_mfma_f32_16x16x32_bf16 v[86:89], v[162:165], v[218:221], v[86:89]
	v_mfma_f32_16x16x32_bf16 v[82:85], v[170:173], v[218:221], v[82:85]
	v_mfma_f32_16x16x32_bf16 v[70:73], v[162:165], v[230:233], v[70:73]
	v_mfma_f32_16x16x32_bf16 v[66:69], v[170:173], v[230:233], v[66:69]
	v_mfma_f32_16x16x32_bf16 v[118:121], v[166:169], v[186:189], v[118:121]
	v_mfma_f32_16x16x32_bf16 v[114:117], v[174:177], v[186:189], v[114:117]
	v_mfma_f32_16x16x32_bf16 v[102:105], v[166:169], v[194:197], v[102:105]
	v_mfma_f32_16x16x32_bf16 v[98:101], v[174:177], v[194:197], v[98:101]
	v_mfma_f32_16x16x32_bf16 v[86:89], v[166:169], v[222:225], v[86:89]
	v_mfma_f32_16x16x32_bf16 v[82:85], v[174:177], v[222:225], v[82:85]
	v_mfma_f32_16x16x32_bf16 v[70:73], v[166:169], v[234:237], v[70:73]
	v_mfma_f32_16x16x32_bf16 v[66:69], v[174:177], v[234:237], v[66:69]
	s_barrier
	s_mov_b32 m0, s67
	v_lshl_add_u64 v[144:145], s[58:59], 0, v[0:1]
	v_lshl_add_u64 v[198:199], s[58:59], 0, v[130:131]
	s_add_u32 s58, s58, s8
	ds_read_b128 v[182:185], v149 offset:16384
	ds_read_b128 v[186:189], v149 offset:17408
	ds_read_b128 v[190:193], v149 offset:18432
	ds_read_b128 v[194:197], v149 offset:19456
	ds_read_b128 v[218:221], v149 offset:20480
	ds_read_b128 v[222:225], v149 offset:21504
	ds_read_b128 v[230:233], v149 offset:22528
	ds_read_b128 v[234:237], v149 offset:23552
	global_load_lds_dwordx4 v[144:145], off
	s_mov_b32 m0, s68
	s_addc_u32 s59, s59, s9
	global_load_lds_dwordx4 v[198:199], off
	v_lshl_add_u64 v[238:239], s[58:59], 0, v[0:1]
	s_mov_b32 m0, s70
	v_lshl_add_u64 v[240:241], s[58:59], 0, v[130:131]
	global_load_lds_dwordx4 v[238:239], off
	s_mov_b32 m0, s71
	v_lshl_add_u64 v[242:243], s[28:29], 0, v[134:135]
	global_load_lds_dwordx4 v[240:241], off
	s_mov_b32 m0, s72
	v_lshl_add_u64 v[244:245], s[28:29], 0, v[132:133]
	global_load_lds_dwordx4 v[242:243], off
	s_mov_b32 m0, s73
	s_nop 0
	global_load_lds_dwordx4 v[244:245], off
	s_waitcnt vmcnt(8)
	s_waitcnt lgkmcnt(0)
	s_barrier
	s_waitcnt lgkmcnt(0)
	v_mfma_f32_16x16x32_bf16 v[62:65], v[140:143], v[182:185], v[62:65]
	v_mfma_f32_16x16x32_bf16 v[58:61], v[154:157], v[182:185], v[58:61]
	v_mfma_f32_16x16x32_bf16 v[46:49], v[140:143], v[190:193], v[46:49]
	v_mfma_f32_16x16x32_bf16 v[42:45], v[154:157], v[190:193], v[42:45]
	v_mfma_f32_16x16x32_bf16 v[30:33], v[140:143], v[218:221], v[30:33]
	v_mfma_f32_16x16x32_bf16 v[26:29], v[154:157], v[218:221], v[26:29]
	v_mfma_f32_16x16x32_bf16 v[14:17], v[140:143], v[230:233], v[14:17]
	v_mfma_f32_16x16x32_bf16 v[10:13], v[154:157], v[230:233], v[10:13]
	v_mfma_f32_16x16x32_bf16 v[62:65], v[150:153], v[186:189], v[62:65]
	v_mfma_f32_16x16x32_bf16 v[58:61], v[158:161], v[186:189], v[58:61]
	v_mfma_f32_16x16x32_bf16 v[46:49], v[150:153], v[194:197], v[46:49]
	v_mfma_f32_16x16x32_bf16 v[42:45], v[158:161], v[194:197], v[42:45]
	v_mfma_f32_16x16x32_bf16 v[30:33], v[150:153], v[222:225], v[30:33]
	v_mfma_f32_16x16x32_bf16 v[26:29], v[158:161], v[222:225], v[26:29]
	v_mfma_f32_16x16x32_bf16 v[14:17], v[150:153], v[234:237], v[14:17]
	v_mfma_f32_16x16x32_bf16 v[10:13], v[158:161], v[234:237], v[10:13]
	v_mfma_f32_16x16x32_bf16 v[54:57], v[162:165], v[182:185], v[54:57]
	v_mfma_f32_16x16x32_bf16 v[50:53], v[170:173], v[182:185], v[50:53]
	v_mfma_f32_16x16x32_bf16 v[38:41], v[162:165], v[190:193], v[38:41]
	v_mfma_f32_16x16x32_bf16 v[34:37], v[170:173], v[190:193], v[34:37]
	v_mfma_f32_16x16x32_bf16 v[22:25], v[162:165], v[218:221], v[22:25]
	v_mfma_f32_16x16x32_bf16 v[18:21], v[170:173], v[218:221], v[18:21]
	v_mfma_f32_16x16x32_bf16 v[6:9], v[162:165], v[230:233], v[6:9]
	v_mfma_f32_16x16x32_bf16 v[2:5], v[170:173], v[230:233], v[2:5]
	v_mfma_f32_16x16x32_bf16 v[54:57], v[166:169], v[186:189], v[54:57]
	v_mfma_f32_16x16x32_bf16 v[50:53], v[174:177], v[186:189], v[50:53]
	v_mfma_f32_16x16x32_bf16 v[38:41], v[166:169], v[194:197], v[38:41]
	v_mfma_f32_16x16x32_bf16 v[34:37], v[174:177], v[194:197], v[34:37]
	v_mfma_f32_16x16x32_bf16 v[22:25], v[166:169], v[222:225], v[22:25]
	v_mfma_f32_16x16x32_bf16 v[18:21], v[174:177], v[222:225], v[18:21]
	v_mfma_f32_16x16x32_bf16 v[6:9], v[166:169], v[234:237], v[6:9]
	v_mfma_f32_16x16x32_bf16 v[2:5], v[174:177], v[234:237], v[2:5]
	s_barrier
	v_add_u32_e32 v158, s78, v148
	v_add_u32_e32 v174, s83, v148
	ds_read_b128 v[140:143], v158
	ds_read_b128 v[150:153], v158 offset:1024
	ds_read_b128 v[154:157], v158 offset:2048
	ds_read_b128 v[158:161], v158 offset:3072
	ds_read_b128 v[162:165], v174
	ds_read_b128 v[166:169], v174 offset:1024
	ds_read_b128 v[170:173], v174 offset:2048
	ds_read_b128 v[174:177], v174 offset:3072
	s_add_u32 s28, s28, s6
	s_addc_u32 s29, s29, s7
	s_mov_b32 m0, s74
	v_lshl_add_u64 v[246:247], s[28:29], 0, v[134:135]
	ds_read_b128 v[182:185], v149 offset:32768
	ds_read_b128 v[186:189], v149 offset:33792
	ds_read_b128 v[190:193], v149 offset:34816
	ds_read_b128 v[194:197], v149 offset:35840
	ds_read_b128 v[218:221], v149 offset:36864
	ds_read_b128 v[222:225], v149 offset:37888
	ds_read_b128 v[230:233], v149 offset:38912
	ds_read_b128 v[234:237], v149 offset:39936
	global_load_lds_dwordx4 v[246:247], off
	v_lshl_add_u64 v[246:247], s[28:29], 0, v[132:133]
	s_mov_b32 m0, s75
	s_nop 0
	global_load_lds_dwordx4 v[246:247], off
	s_waitcnt vmcnt(8)
	s_waitcnt lgkmcnt(0)
	s_barrier
	s_waitcnt lgkmcnt(0)
	v_mfma_f32_16x16x32_bf16 v[126:129], v[140:143], v[182:185], v[126:129]
	v_mfma_f32_16x16x32_bf16 v[122:125], v[154:157], v[182:185], v[122:125]
	v_mfma_f32_16x16x32_bf16 v[110:113], v[140:143], v[190:193], v[110:113]
	v_mfma_f32_16x16x32_bf16 v[106:109], v[154:157], v[190:193], v[106:109]
	v_mfma_f32_16x16x32_bf16 v[94:97], v[140:143], v[218:221], v[94:97]
	v_mfma_f32_16x16x32_bf16 v[90:93], v[154:157], v[218:221], v[90:93]
	v_mfma_f32_16x16x32_bf16 v[78:81], v[140:143], v[230:233], v[78:81]
	v_mfma_f32_16x16x32_bf16 v[74:77], v[154:157], v[230:233], v[74:77]
	v_mfma_f32_16x16x32_bf16 v[126:129], v[150:153], v[186:189], v[126:129]
	v_mfma_f32_16x16x32_bf16 v[122:125], v[158:161], v[186:189], v[122:125]
	v_mfma_f32_16x16x32_bf16 v[110:113], v[150:153], v[194:197], v[110:113]
	v_mfma_f32_16x16x32_bf16 v[106:109], v[158:161], v[194:197], v[106:109]
	v_mfma_f32_16x16x32_bf16 v[94:97], v[150:153], v[222:225], v[94:97]
	v_mfma_f32_16x16x32_bf16 v[90:93], v[158:161], v[222:225], v[90:93]
	v_mfma_f32_16x16x32_bf16 v[78:81], v[150:153], v[234:237], v[78:81]
	v_mfma_f32_16x16x32_bf16 v[74:77], v[158:161], v[234:237], v[74:77]
	v_mfma_f32_16x16x32_bf16 v[118:121], v[162:165], v[182:185], v[118:121]
	v_mfma_f32_16x16x32_bf16 v[114:117], v[170:173], v[182:185], v[114:117]
	v_mfma_f32_16x16x32_bf16 v[102:105], v[162:165], v[190:193], v[102:105]
	v_mfma_f32_16x16x32_bf16 v[98:101], v[170:173], v[190:193], v[98:101]
	v_mfma_f32_16x16x32_bf16 v[86:89], v[162:165], v[218:221], v[86:89]
	v_mfma_f32_16x16x32_bf16 v[82:85], v[170:173], v[218:221], v[82:85]
	v_mfma_f32_16x16x32_bf16 v[70:73], v[162:165], v[230:233], v[70:73]
	v_mfma_f32_16x16x32_bf16 v[66:69], v[170:173], v[230:233], v[66:69]
	v_mfma_f32_16x16x32_bf16 v[118:121], v[166:169], v[186:189], v[118:121]
	v_mfma_f32_16x16x32_bf16 v[114:117], v[174:177], v[186:189], v[114:117]
	v_mfma_f32_16x16x32_bf16 v[102:105], v[166:169], v[194:197], v[102:105]
	v_mfma_f32_16x16x32_bf16 v[98:101], v[174:177], v[194:197], v[98:101]
	v_mfma_f32_16x16x32_bf16 v[86:89], v[166:169], v[222:225], v[86:89]
	v_mfma_f32_16x16x32_bf16 v[82:85], v[174:177], v[222:225], v[82:85]
	v_mfma_f32_16x16x32_bf16 v[70:73], v[166:169], v[234:237], v[70:73]
	v_mfma_f32_16x16x32_bf16 v[66:69], v[174:177], v[234:237], v[66:69]
	s_barrier
	s_mov_b32 m0, s79
	v_lshl_add_u64 v[144:145], v[144:145], 0, s[48:49]
	ds_read_b128 v[182:185], v149 offset:49152
	ds_read_b128 v[186:189], v149 offset:50176
	ds_read_b128 v[190:193], v149 offset:51200
	ds_read_b128 v[194:197], v149 offset:52224
	ds_read_b128 v[218:221], v149 offset:53248
	ds_read_b128 v[222:225], v149 offset:54272
	ds_read_b128 v[230:233], v149 offset:55296
	ds_read_b128 v[234:237], v149 offset:56320
	global_load_lds_dwordx4 v[144:145], off
	v_lshl_add_u64 v[144:145], v[198:199], 0, s[48:49]
	s_mov_b32 m0, s80
	s_nop 0
	global_load_lds_dwordx4 v[144:145], off
	v_lshl_add_u64 v[144:145], v[238:239], 0, s[48:49]
	s_mov_b32 m0, s84
	s_nop 0
	global_load_lds_dwordx4 v[144:145], off
	v_lshl_add_u64 v[144:145], v[240:241], 0, s[48:49]
	s_mov_b32 m0, s85
	s_nop 0
	global_load_lds_dwordx4 v[144:145], off
	v_lshl_add_u64 v[144:145], v[242:243], 0, s[48:49]
	s_mov_b32 m0, s81
	s_nop 0
	global_load_lds_dwordx4 v[144:145], off
	v_lshl_add_u64 v[144:145], v[244:245], 0, s[48:49]
	s_mov_b32 m0, s82
	s_nop 0
	global_load_lds_dwordx4 v[144:145], off
	s_waitcnt vmcnt(8)
	s_waitcnt lgkmcnt(0)
	s_barrier
	s_waitcnt lgkmcnt(0)
	v_mfma_f32_16x16x32_bf16 v[62:65], v[140:143], v[182:185], v[62:65]
	v_mfma_f32_16x16x32_bf16 v[58:61], v[154:157], v[182:185], v[58:61]
	v_mfma_f32_16x16x32_bf16 v[46:49], v[140:143], v[190:193], v[46:49]
	v_mfma_f32_16x16x32_bf16 v[42:45], v[154:157], v[190:193], v[42:45]
	v_mfma_f32_16x16x32_bf16 v[30:33], v[140:143], v[218:221], v[30:33]
	v_mfma_f32_16x16x32_bf16 v[26:29], v[154:157], v[218:221], v[26:29]
	v_mfma_f32_16x16x32_bf16 v[14:17], v[140:143], v[230:233], v[14:17]
	v_mfma_f32_16x16x32_bf16 v[10:13], v[154:157], v[230:233], v[10:13]
	v_mfma_f32_16x16x32_bf16 v[62:65], v[150:153], v[186:189], v[62:65]
	v_mfma_f32_16x16x32_bf16 v[58:61], v[158:161], v[186:189], v[58:61]
	v_mfma_f32_16x16x32_bf16 v[46:49], v[150:153], v[194:197], v[46:49]
	v_mfma_f32_16x16x32_bf16 v[42:45], v[158:161], v[194:197], v[42:45]
	v_mfma_f32_16x16x32_bf16 v[30:33], v[150:153], v[222:225], v[30:33]
	v_mfma_f32_16x16x32_bf16 v[26:29], v[158:161], v[222:225], v[26:29]
	v_mfma_f32_16x16x32_bf16 v[14:17], v[150:153], v[234:237], v[14:17]
	v_mfma_f32_16x16x32_bf16 v[10:13], v[158:161], v[234:237], v[10:13]
	v_mfma_f32_16x16x32_bf16 v[54:57], v[162:165], v[182:185], v[54:57]
	v_mfma_f32_16x16x32_bf16 v[50:53], v[170:173], v[182:185], v[50:53]
	v_mfma_f32_16x16x32_bf16 v[38:41], v[162:165], v[190:193], v[38:41]
	v_mfma_f32_16x16x32_bf16 v[34:37], v[170:173], v[190:193], v[34:37]
	v_mfma_f32_16x16x32_bf16 v[22:25], v[162:165], v[218:221], v[22:25]
	v_mfma_f32_16x16x32_bf16 v[18:21], v[170:173], v[218:221], v[18:21]
	v_mfma_f32_16x16x32_bf16 v[6:9], v[162:165], v[230:233], v[6:9]
	v_mfma_f32_16x16x32_bf16 v[2:5], v[170:173], v[230:233], v[2:5]
	v_mfma_f32_16x16x32_bf16 v[54:57], v[166:169], v[186:189], v[54:57]
	v_mfma_f32_16x16x32_bf16 v[50:53], v[174:177], v[186:189], v[50:53]
	v_mfma_f32_16x16x32_bf16 v[38:41], v[166:169], v[194:197], v[38:41]
	v_mfma_f32_16x16x32_bf16 v[34:37], v[174:177], v[194:197], v[34:37]
	v_mfma_f32_16x16x32_bf16 v[22:25], v[166:169], v[222:225], v[22:25]
	v_mfma_f32_16x16x32_bf16 v[18:21], v[174:177], v[222:225], v[18:21]
	v_mfma_f32_16x16x32_bf16 v[6:9], v[166:169], v[234:237], v[6:9]
	v_mfma_f32_16x16x32_bf16 v[2:5], v[174:177], v[234:237], v[2:5]
	s_barrier
	s_add_u32 s46, s46, 0x100
	s_addc_u32 s47, s47, 0
	s_add_u32 s26, s26, 0x100
	s_addc_u32 s27, s27, 0
	s_cmp_ge_i32 s52, s77
	s_mov_b32 s28, s52
	s_cbranch_scc0 .LBB0_1024

.LBB0_1031:
	s_mov_b32 s50, s45
	s_mov_b32 s24, 0
	s_mov_b32 s0, 0
	s_add_i32 s0, s0, 0x200e8
	v_mov_b32_e32 v0, s0
	s_mov_b32 s0, 0
	ds_read_b64 v[2:3], v0
	s_add_i32 s0, s0, 0x200e8
	v_mov_b32_e32 v0, s0
	s_movk_i32 s0, 0x200
	s_movk_i32 s2, 0x1740
	s_movk_i32 s4, 0x400
	ds_read_b64 v[4:5], v0
	s_ashr_i32 s5, s4, 31
	s_lshr_b32 s5, s5, 24
	s_add_i32 s4, s4, s5
	s_ashr_i32 s16, s4, 8
	v_readlane_b32 s15, v252, 0
	s_lshl_b32 s4, s16, 7
	v_mov_b32_e32 v20, v200
	s_waitcnt lgkmcnt(0)
	v_readfirstlane_b32 s1, v3
	v_readfirstlane_b32 s3, v2
	v_readfirstlane_b32 s6, v5
	v_readfirstlane_b32 s7, v4
	s_cmp_ge_i32 s15, s4
	v_readfirstlane_b32 s5, v20
	s_cbranch_scc1 .LBB0_1052
	v_lshlrev_b32_e32 v0, 4, v20
	v_add_u32_e32 v2, 0x2000, v0
	v_ashrrev_i32_e32 v3, 31, v2
	v_lshrrev_b32_e32 v3, 22, v3
	v_add_u32_e32 v3, v2, v3
	v_ashrrev_i32_e32 v3, 10, v3
	v_mul_i32_i24_e32 v4, 0x400, v3
	v_sub_u32_e32 v2, v2, v4
	v_lshrrev_b32_e32 v4, 4, v2
	v_bitop3_b32 v2, v4, v2, 32 bitop3:0x6c
	v_ashrrev_i32_e32 v4, 31, v2
	v_lshrrev_b32_e32 v4, 26, v4
	v_add_u32_e32 v4, v2, v4
	v_lshlrev_b32_e32 v6, 3, v3
	v_ashrrev_i32_e32 v5, 6, v4
	v_and_b32_e32 v6, -16, v6
	v_lshlrev_b32_e32 v3, 5, v3
	v_add_u32_e32 v6, v5, v6
	v_and_b32_e32 v14, 32, v3
	v_and_b32_e32 v3, 0xc0, v4
	v_and_b32_e32 v5, 3, v5
	s_mov_b32 s18, 0x7fffffe0
	v_lshrrev_b32_e32 v7, 2, v6
	v_lshlrev_b32_e32 v8, 1, v6
	v_sub_u32_e32 v2, v2, v3
	v_and_or_b32 v5, v6, s18, v5
	v_and_b32_e32 v7, 4, v7
	v_and_b32_e32 v8, 24, v8
	v_ashrrev_i16_sdwa v2, v201, sext(v2) dst_sel:DWORD dst_unused:UNUSED_PAD src0_sel:DWORD src1_sel:BYTE_0
	v_or3_b32 v5, v5, v7, v8
	v_bfe_i32 v15, v2, 0, 16
	v_mul_lo_u32 v5, v5, s0
	v_add_u32_e32 v2, v14, v15
	v_mul_lo_u32 v16, v6, s2
	v_add_lshl_u32 v130, v5, v2, 1
	v_add_lshl_u32 v132, v2, v16, 1
	v_bfe_i32 v2, v20, 27, 1
	v_lshrrev_b32_e32 v2, 22, v2
	v_add_u32_e32 v2, v0, v2
	v_and_b32_e32 v2, 0xfffffc00, v2
	v_sub_u32_e32 v0, v0, v2
	v_lshrrev_b32_e32 v2, 4, v0
	v_ashrrev_i32_e32 v4, 31, v20
	v_bitop3_b32 v0, v2, v0, 32 bitop3:0x6c
	v_lshrrev_b32_e32 v4, 26, v4
	v_ashrrev_i32_e32 v2, 31, v0
	v_add_u32_e32 v4, v20, v4
	v_lshrrev_b32_e32 v2, 26, v2
	v_ashrrev_i32_e32 v4, 6, v4
	v_add_u32_e32 v2, v0, v2
	v_lshlrev_b32_e32 v5, 3, v4
	v_ashrrev_i32_e32 v3, 6, v2
	v_and_b32_e32 v5, -16, v5
	s_add_u32 s30, s3, 0x8bf0400
	v_add_u32_e32 v5, v3, v5
	v_and_b32_e32 v2, 0xc0, v2
	s_addc_u32 s31, s1, 0
	v_and_b32_e32 v3, 3, v3
	v_lshrrev_b32_e32 v6, 2, v5
	v_lshlrev_b32_e32 v7, 1, v5
	v_sub_u32_e32 v0, v0, v2
	s_add_u32 s34, s7, 0x1870000
	v_and_or_b32 v3, v5, s18, v3
	v_and_b32_e32 v6, 4, v6
	v_and_b32_e32 v7, 24, v7
	v_lshlrev_b32_e32 v4, 5, v4
	v_ashrrev_i16_sdwa v0, v201, sext(v0) dst_sel:DWORD dst_unused:UNUSED_PAD src0_sel:DWORD src1_sel:BYTE_0
	s_addc_u32 s35, s6, 0
	v_or3_b32 v3, v3, v6, v7
	v_and_b32_e32 v17, 32, v4
	v_bfe_i32 v18, v0, 0, 16
	s_lshl_b32 s70, s16, 3
	v_mul_lo_u32 v3, v3, s0
	v_add_u32_e32 v2, v17, v18
	v_mul_lo_u32 v19, v5, s2
	s_abs_i32 s72, s70
	v_add_lshl_u32 v0, v3, v2, 1
	v_add_lshl_u32 v134, v2, v19, 1
	v_cvt_f32_u32_e32 v2, s72
	s_ashr_i32 s69, s15, 31
	s_lshr_b32 s18, s69, 29
	s_add_i32 s18, s15, s18
	v_rcp_iflag_f32_e32 v2, v2
	s_ashr_i32 s19, s18, 3
	s_and_b32 s18, s18, -8
	s_sub_i32 s18, s15, s18
	v_mul_f32_e32 v2, 0x4f7ffffe, v2
	v_cvt_u32_f32_e32 v2, v2
	s_lshl_b32 s68, s16, 4
	s_lshr_b32 s21, s18, 31
	s_or_b32 s21, s68, s21
	s_mul_i32 s18, s21, s18
	s_sub_i32 s21, 0, s72
	v_readfirstlane_b32 s73, v2
	s_add_i32 s18, s18, s19
	s_mul_i32 s21, s21, s73
	s_ashr_i32 s19, s18, 31
	s_bfe_i32 s71, s16, 0x1001c
	s_mul_hi_u32 s21, s73, s21
	s_xor_b32 s16, s19, s71
	s_abs_i32 s19, s18
	s_add_i32 s73, s73, s21
	s_mul_hi_u32 s21, s19, s73
	s_mul_i32 s22, s21, s72
	s_ashr_i32 s20, s5, 6
	s_ashr_i32 s3, s2, 31
	s_ashr_i32 s1, s0, 31
	s_sub_i32 s19, s19, s22
	s_ashr_i32 s44, s5, 8
	s_lshl_b64 s[6:7], s[2:3], 8
	s_lshl_b64 s[8:9], s[0:1], 8
	s_lshl_b64 s[10:11], s[2:3], 9
	s_lshl_b64 s[12:13], s[0:1], 9
	s_lshl_b32 s14, s20, 10
	s_add_i32 s22, s21, 1
	s_sub_i32 s23, s19, s72
	s_cmp_ge_u32 s19, s72
	s_cselect_b32 s21, s22, s21
	s_cselect_b32 s19, s23, s19
	s_add_i32 s22, s21, 1
	s_cmp_ge_u32 s19, s72
	s_cselect_b32 s19, s22, s21
	s_xor_b32 s19, s19, s16
	s_sub_i32 s16, s19, s16
	s_lshl_b32 s19, s16, 3
	s_sub_i32 s21, 0x80, s19
	s_min_i32 s21, s21, 8
	s_abs_i32 s23, s21
	v_cvt_f32_u32_e32 v2, s23
	s_sub_i32 s25, 0, s23
	s_mul_i32 s16, s16, s70
	s_sub_i32 s18, s18, s16
	v_rcp_iflag_f32_e32 v2, v2
	s_abs_i32 s22, s18
	s_xor_b32 s16, s18, s21
	s_ashr_i32 s16, s16, 31
	v_mul_f32_e32 v2, 0x4f7ffffe, v2
	v_cvt_u32_f32_e32 v2, v2
	v_mov_b32_e32 v131, v1
	v_mov_b32_e32 v135, v1
	v_mov_b32_e32 v133, v1
	v_readfirstlane_b32 s26, v2
	s_mul_i32 s25, s25, s26
	s_mul_hi_u32 s25, s26, s25
	s_add_i32 s26, s26, s25
	s_mul_hi_u32 s25, s22, s26
	s_mul_i32 s26, s25, s23
	s_sub_i32 s22, s22, s26
	s_add_i32 s26, s25, 1
	s_sub_i32 s27, s22, s23
	s_cmp_ge_u32 s22, s23
	s_cselect_b32 s25, s26, s25
	s_cselect_b32 s22, s27, s22
	s_add_i32 s26, s25, 1
	s_cmp_ge_u32 s22, s23
	s_cselect_b32 s22, s26, s25
	s_xor_b32 s22, s22, s16
	s_sub_i32 s16, s22, s16
	s_mul_i32 s21, s16, s21
	s_sub_i32 s18, s18, s21
	s_add_i32 s37, s18, s19
	s_ashr_i32 s18, s37, 31
	s_mul_i32 s18, s10, s18
	s_mul_hi_u32 s19, s10, s37
	s_lshr_b64 s[2:3], s[2:3], 23
	s_add_i32 s18, s19, s18
	s_mul_i32 s2, s2, s37
	s_add_i32 s18, s18, s2
	s_ashr_i32 s2, s16, 31
	s_mul_i32 s2, s12, s2
	s_mul_hi_u32 s3, s12, s16
	s_add_i32 s21, s3, s2
	s_lshr_b64 s[2:3], s[0:1], 23
	s_mul_i32 s2, s2, s16
	s_add_i32 s21, s21, s2
	s_mul_i32 s2, s12, s16
	s_add_u32 s26, s34, s2
	s_addc_u32 s27, s35, s21
	s_add_i32 s74, s24, 0x10000
	s_add_i32 s75, s74, s14
	s_add_i32 s76, s75, 0x2000
	s_add_u32 s2, s26, s8
	s_addc_u32 s3, s27, s9
	s_add_i32 s77, s24, 0x14000
	s_add_i32 s78, s77, s14
	s_mul_i32 s19, s10, s37
	s_mov_b32 m0, s75
	s_add_i32 s79, s78, 0x2000
	global_load_lds_dwordx4 v0, s[26:27]
	s_mov_b32 m0, s76
	s_add_u32 s28, s30, s19
	global_load_lds_dwordx4 v130, s[26:27]
	s_mov_b32 m0, s78
	s_addc_u32 s29, s31, s18
	s_add_i32 s80, s24, s14
	global_load_lds_dwordx4 v0, s[2:3]
	s_mov_b32 m0, s79
	s_add_i32 s81, s80, 0x2000
	v_lshl_add_u64 v[6:7], s[2:3], 0, v[0:1]
	v_lshl_add_u64 v[8:9], s[2:3], 0, v[130:131]
	global_load_lds_dwordx4 v130, s[2:3]
	s_mov_b32 m0, s80
	s_add_u32 s2, s28, s6
	global_load_lds_dwordx4 v134, s[28:29]
	s_mov_b32 m0, s81
	s_addc_u32 s3, s29, s7
	s_add_i32 s82, s80, 0x4000
	global_load_lds_dwordx4 v132, s[28:29]
	s_mov_b32 m0, s82
	s_add_i32 s83, s80, 0x6000
	global_load_lds_dwordx4 v134, s[2:3]
	s_mov_b32 m0, s83
	s_cmp_eq_u32 s44, 1
	global_load_lds_dwordx4 v132, s[2:3]
	v_lshl_add_u64 v[2:3], s[26:27], 0, v[0:1]
	v_lshl_add_u64 v[4:5], s[26:27], 0, v[130:131]
	v_lshl_add_u64 v[10:11], s[28:29], 0, v[134:135]
	v_lshl_add_u64 v[12:13], s[28:29], 0, v[132:133]
	s_cselect_b64 s[18:19], -1, 0
	s_cmp_lg_u32 s44, 1
	s_cbranch_scc1 .LBB0_1034
	s_barrier
	s_setprio 1

.LBB0_1045:
	v_add_u32_e32 v144, s74, v148
	ds_read_b128 v[140:143], v144
	ds_read_b128 v[150:153], v144 offset:1024
	ds_read_b128 v[154:157], v144 offset:2048
	ds_read_b128 v[158:161], v144 offset:3072
	v_add_u32_e32 v144, s77, v148
	ds_read_b128 v[162:165], v144
	ds_read_b128 v[166:169], v144 offset:1024
	ds_read_b128 v[170:173], v144 offset:2048
	ds_read_b128 v[174:177], v144 offset:3072
	s_add_i32 s52, s28, 2
	s_add_u32 s54, s26, 0x80
	s_addc_u32 s29, s27, 0
	s_cmp_eq_u32 s85, s28
	s_cselect_b32 s28, s0, s54
	s_cselect_b32 s29, s1, s29
	s_cselect_b32 s59, s25, s47
	s_cselect_b32 s58, s24, s46
	v_lshl_add_u64 v[144:145], s[26:27], 0, v[138:139]
	s_add_i32 m0, s80, 0xc000
	ds_read_b128 v[182:185], v149
	ds_read_b128 v[186:189], v149 offset:1024
	ds_read_b128 v[190:193], v149 offset:2048
	ds_read_b128 v[194:197], v149 offset:3072
	ds_read_b128 v[218:221], v149 offset:4096
	ds_read_b128 v[222:225], v149 offset:5120
	ds_read_b128 v[230:233], v149 offset:6144
	ds_read_b128 v[234:237], v149 offset:7168
	global_load_lds_dwordx4 v[144:145], off
	v_lshl_add_u64 v[144:145], s[26:27], 0, v[136:137]
	s_add_i32 m0, s80, 0xe000
	s_nop 0
	global_load_lds_dwordx4 v[144:145], off
	s_waitcnt vmcnt(8)
	s_waitcnt lgkmcnt(0)
	s_barrier
	s_waitcnt lgkmcnt(0)
	v_mfma_f32_16x16x32_bf16 v[126:129], v[140:143], v[182:185], v[126:129]
	v_mfma_f32_16x16x32_bf16 v[122:125], v[154:157], v[182:185], v[122:125]
	v_mfma_f32_16x16x32_bf16 v[110:113], v[140:143], v[190:193], v[110:113]
	v_mfma_f32_16x16x32_bf16 v[106:109], v[154:157], v[190:193], v[106:109]
	v_mfma_f32_16x16x32_bf16 v[94:97], v[140:143], v[218:221], v[94:97]
	v_mfma_f32_16x16x32_bf16 v[90:93], v[154:157], v[218:221], v[90:93]
	v_mfma_f32_16x16x32_bf16 v[78:81], v[140:143], v[230:233], v[78:81]
	v_mfma_f32_16x16x32_bf16 v[74:77], v[154:157], v[230:233], v[74:77]
	v_mfma_f32_16x16x32_bf16 v[126:129], v[150:153], v[186:189], v[126:129]
	v_mfma_f32_16x16x32_bf16 v[122:125], v[158:161], v[186:189], v[122:125]
	v_mfma_f32_16x16x32_bf16 v[110:113], v[150:153], v[194:197], v[110:113]
	v_mfma_f32_16x16x32_bf16 v[106:109], v[158:161], v[194:197], v[106:109]
	v_mfma_f32_16x16x32_bf16 v[94:97], v[150:153], v[222:225], v[94:97]
	v_mfma_f32_16x16x32_bf16 v[90:93], v[158:161], v[222:225], v[90:93]
	v_mfma_f32_16x16x32_bf16 v[78:81], v[150:153], v[234:237], v[78:81]
	v_mfma_f32_16x16x32_bf16 v[74:77], v[158:161], v[234:237], v[74:77]
	v_mfma_f32_16x16x32_bf16 v[118:121], v[162:165], v[182:185], v[118:121]
	v_mfma_f32_16x16x32_bf16 v[114:117], v[170:173], v[182:185], v[114:117]
	v_mfma_f32_16x16x32_bf16 v[102:105], v[162:165], v[190:193], v[102:105]
	v_mfma_f32_16x16x32_bf16 v[98:101], v[170:173], v[190:193], v[98:101]
	v_mfma_f32_16x16x32_bf16 v[86:89], v[162:165], v[218:221], v[86:89]
	v_mfma_f32_16x16x32_bf16 v[82:85], v[170:173], v[218:221], v[82:85]
	v_mfma_f32_16x16x32_bf16 v[70:73], v[162:165], v[230:233], v[70:73]
	v_mfma_f32_16x16x32_bf16 v[66:69], v[170:173], v[230:233], v[66:69]
	v_mfma_f32_16x16x32_bf16 v[118:121], v[166:169], v[186:189], v[118:121]
	v_mfma_f32_16x16x32_bf16 v[114:117], v[174:177], v[186:189], v[114:117]
	v_mfma_f32_16x16x32_bf16 v[102:105], v[166:169], v[194:197], v[102:105]
	v_mfma_f32_16x16x32_bf16 v[98:101], v[174:177], v[194:197], v[98:101]
	v_mfma_f32_16x16x32_bf16 v[86:89], v[166:169], v[222:225], v[86:89]
	v_mfma_f32_16x16x32_bf16 v[82:85], v[174:177], v[222:225], v[82:85]
	v_mfma_f32_16x16x32_bf16 v[70:73], v[166:169], v[234:237], v[70:73]
	v_mfma_f32_16x16x32_bf16 v[66:69], v[174:177], v[234:237], v[66:69]
	s_barrier
	s_mov_b32 m0, s75
	v_lshl_add_u64 v[144:145], s[58:59], 0, v[0:1]
	v_lshl_add_u64 v[198:199], s[58:59], 0, v[130:131]
	s_add_u32 s58, s58, s8
	ds_read_b128 v[182:185], v149 offset:16384
	ds_read_b128 v[186:189], v149 offset:17408
	ds_read_b128 v[190:193], v149 offset:18432
	ds_read_b128 v[194:197], v149 offset:19456
	ds_read_b128 v[218:221], v149 offset:20480
	ds_read_b128 v[222:225], v149 offset:21504
	ds_read_b128 v[230:233], v149 offset:22528
	ds_read_b128 v[234:237], v149 offset:23552
	global_load_lds_dwordx4 v[144:145], off
	s_mov_b32 m0, s76
	s_addc_u32 s59, s59, s9
	global_load_lds_dwordx4 v[198:199], off
	v_lshl_add_u64 v[238:239], s[58:59], 0, v[0:1]
	s_mov_b32 m0, s78
	v_lshl_add_u64 v[240:241], s[58:59], 0, v[130:131]
	global_load_lds_dwordx4 v[238:239], off
	s_mov_b32 m0, s79
	v_lshl_add_u64 v[242:243], s[28:29], 0, v[134:135]
	global_load_lds_dwordx4 v[240:241], off
	s_mov_b32 m0, s80
	v_lshl_add_u64 v[244:245], s[28:29], 0, v[132:133]
	global_load_lds_dwordx4 v[242:243], off
	s_mov_b32 m0, s81
	s_nop 0
	global_load_lds_dwordx4 v[244:245], off
	s_waitcnt vmcnt(8)
	s_waitcnt lgkmcnt(0)
	s_barrier
	s_waitcnt lgkmcnt(0)
	v_mfma_f32_16x16x32_bf16 v[62:65], v[140:143], v[182:185], v[62:65]
	v_mfma_f32_16x16x32_bf16 v[58:61], v[154:157], v[182:185], v[58:61]
	v_mfma_f32_16x16x32_bf16 v[46:49], v[140:143], v[190:193], v[46:49]
	v_mfma_f32_16x16x32_bf16 v[42:45], v[154:157], v[190:193], v[42:45]
	v_mfma_f32_16x16x32_bf16 v[30:33], v[140:143], v[218:221], v[30:33]
	v_mfma_f32_16x16x32_bf16 v[26:29], v[154:157], v[218:221], v[26:29]
	v_mfma_f32_16x16x32_bf16 v[14:17], v[140:143], v[230:233], v[14:17]
	v_mfma_f32_16x16x32_bf16 v[10:13], v[154:157], v[230:233], v[10:13]
	v_mfma_f32_16x16x32_bf16 v[62:65], v[150:153], v[186:189], v[62:65]
	v_mfma_f32_16x16x32_bf16 v[58:61], v[158:161], v[186:189], v[58:61]
	v_mfma_f32_16x16x32_bf16 v[46:49], v[150:153], v[194:197], v[46:49]
	v_mfma_f32_16x16x32_bf16 v[42:45], v[158:161], v[194:197], v[42:45]
	v_mfma_f32_16x16x32_bf16 v[30:33], v[150:153], v[222:225], v[30:33]
	v_mfma_f32_16x16x32_bf16 v[26:29], v[158:161], v[222:225], v[26:29]
	v_mfma_f32_16x16x32_bf16 v[14:17], v[150:153], v[234:237], v[14:17]
	v_mfma_f32_16x16x32_bf16 v[10:13], v[158:161], v[234:237], v[10:13]
	v_mfma_f32_16x16x32_bf16 v[54:57], v[162:165], v[182:185], v[54:57]
	v_mfma_f32_16x16x32_bf16 v[50:53], v[170:173], v[182:185], v[50:53]
	v_mfma_f32_16x16x32_bf16 v[38:41], v[162:165], v[190:193], v[38:41]
	v_mfma_f32_16x16x32_bf16 v[34:37], v[170:173], v[190:193], v[34:37]
	v_mfma_f32_16x16x32_bf16 v[22:25], v[162:165], v[218:221], v[22:25]
	v_mfma_f32_16x16x32_bf16 v[18:21], v[170:173], v[218:221], v[18:21]
	v_mfma_f32_16x16x32_bf16 v[6:9], v[162:165], v[230:233], v[6:9]
	v_mfma_f32_16x16x32_bf16 v[2:5], v[170:173], v[230:233], v[2:5]
	v_mfma_f32_16x16x32_bf16 v[54:57], v[166:169], v[186:189], v[54:57]
	v_mfma_f32_16x16x32_bf16 v[50:53], v[174:177], v[186:189], v[50:53]
	v_mfma_f32_16x16x32_bf16 v[38:41], v[166:169], v[194:197], v[38:41]
	v_mfma_f32_16x16x32_bf16 v[34:37], v[174:177], v[194:197], v[34:37]
	v_mfma_f32_16x16x32_bf16 v[22:25], v[166:169], v[222:225], v[22:25]
	v_mfma_f32_16x16x32_bf16 v[18:21], v[174:177], v[222:225], v[18:21]
	v_mfma_f32_16x16x32_bf16 v[6:9], v[166:169], v[234:237], v[6:9]
	v_mfma_f32_16x16x32_bf16 v[2:5], v[174:177], v[234:237], v[2:5]
	s_barrier
	v_add_u32_e32 v158, s66, v148
	v_add_u32_e32 v174, s93, v148
	ds_read_b128 v[140:143], v158
	ds_read_b128 v[150:153], v158 offset:1024
	ds_read_b128 v[154:157], v158 offset:2048
	ds_read_b128 v[158:161], v158 offset:3072
	ds_read_b128 v[162:165], v174
	ds_read_b128 v[166:169], v174 offset:1024
	ds_read_b128 v[170:173], v174 offset:2048
	ds_read_b128 v[174:177], v174 offset:3072
	s_add_u32 s28, s28, s6
	s_addc_u32 s29, s29, s7
	s_mov_b32 m0, s82
	v_lshl_add_u64 v[246:247], s[28:29], 0, v[134:135]
	ds_read_b128 v[182:185], v149 offset:32768
	ds_read_b128 v[186:189], v149 offset:33792
	ds_read_b128 v[190:193], v149 offset:34816
	ds_read_b128 v[194:197], v149 offset:35840
	ds_read_b128 v[218:221], v149 offset:36864
	ds_read_b128 v[222:225], v149 offset:37888
	ds_read_b128 v[230:233], v149 offset:38912
	ds_read_b128 v[234:237], v149 offset:39936
	global_load_lds_dwordx4 v[246:247], off
	v_lshl_add_u64 v[246:247], s[28:29], 0, v[132:133]
	s_mov_b32 m0, s83
	s_nop 0
	global_load_lds_dwordx4 v[246:247], off
	s_waitcnt vmcnt(8)
	s_waitcnt lgkmcnt(0)
	s_barrier
	s_waitcnt lgkmcnt(0)
	v_mfma_f32_16x16x32_bf16 v[126:129], v[140:143], v[182:185], v[126:129]
	v_mfma_f32_16x16x32_bf16 v[122:125], v[154:157], v[182:185], v[122:125]
	v_mfma_f32_16x16x32_bf16 v[110:113], v[140:143], v[190:193], v[110:113]
	v_mfma_f32_16x16x32_bf16 v[106:109], v[154:157], v[190:193], v[106:109]
	v_mfma_f32_16x16x32_bf16 v[94:97], v[140:143], v[218:221], v[94:97]
	v_mfma_f32_16x16x32_bf16 v[90:93], v[154:157], v[218:221], v[90:93]
	v_mfma_f32_16x16x32_bf16 v[78:81], v[140:143], v[230:233], v[78:81]
	v_mfma_f32_16x16x32_bf16 v[74:77], v[154:157], v[230:233], v[74:77]
	v_mfma_f32_16x16x32_bf16 v[126:129], v[150:153], v[186:189], v[126:129]
	v_mfma_f32_16x16x32_bf16 v[122:125], v[158:161], v[186:189], v[122:125]
	v_mfma_f32_16x16x32_bf16 v[110:113], v[150:153], v[194:197], v[110:113]
	v_mfma_f32_16x16x32_bf16 v[106:109], v[158:161], v[194:197], v[106:109]
	v_mfma_f32_16x16x32_bf16 v[94:97], v[150:153], v[222:225], v[94:97]
	v_mfma_f32_16x16x32_bf16 v[90:93], v[158:161], v[222:225], v[90:93]
	v_mfma_f32_16x16x32_bf16 v[78:81], v[150:153], v[234:237], v[78:81]
	v_mfma_f32_16x16x32_bf16 v[74:77], v[158:161], v[234:237], v[74:77]
	v_mfma_f32_16x16x32_bf16 v[118:121], v[162:165], v[182:185], v[118:121]
	v_mfma_f32_16x16x32_bf16 v[114:117], v[170:173], v[182:185], v[114:117]
	v_mfma_f32_16x16x32_bf16 v[102:105], v[162:165], v[190:193], v[102:105]
	v_mfma_f32_16x16x32_bf16 v[98:101], v[170:173], v[190:193], v[98:101]
	v_mfma_f32_16x16x32_bf16 v[86:89], v[162:165], v[218:221], v[86:89]
	v_mfma_f32_16x16x32_bf16 v[82:85], v[170:173], v[218:221], v[82:85]
	v_mfma_f32_16x16x32_bf16 v[70:73], v[162:165], v[230:233], v[70:73]
	v_mfma_f32_16x16x32_bf16 v[66:69], v[170:173], v[230:233], v[66:69]
	v_mfma_f32_16x16x32_bf16 v[118:121], v[166:169], v[186:189], v[118:121]
	v_mfma_f32_16x16x32_bf16 v[114:117], v[174:177], v[186:189], v[114:117]
	v_mfma_f32_16x16x32_bf16 v[102:105], v[166:169], v[194:197], v[102:105]
	v_mfma_f32_16x16x32_bf16 v[98:101], v[174:177], v[194:197], v[98:101]
	v_mfma_f32_16x16x32_bf16 v[86:89], v[166:169], v[222:225], v[86:89]
	v_mfma_f32_16x16x32_bf16 v[82:85], v[174:177], v[222:225], v[82:85]
	v_mfma_f32_16x16x32_bf16 v[70:73], v[166:169], v[234:237], v[70:73]
	v_mfma_f32_16x16x32_bf16 v[66:69], v[174:177], v[234:237], v[66:69]
	s_barrier
	s_mov_b32 m0, s67
	v_lshl_add_u64 v[144:145], v[144:145], 0, s[48:49]
	ds_read_b128 v[182:185], v149 offset:49152
	ds_read_b128 v[186:189], v149 offset:50176
	ds_read_b128 v[190:193], v149 offset:51200
	ds_read_b128 v[194:197], v149 offset:52224
	ds_read_b128 v[218:221], v149 offset:53248
	ds_read_b128 v[222:225], v149 offset:54272
	ds_read_b128 v[230:233], v149 offset:55296
	ds_read_b128 v[234:237], v149 offset:56320
	global_load_lds_dwordx4 v[144:145], off
	v_lshl_add_u64 v[144:145], v[198:199], 0, s[48:49]
	s_mov_b32 m0, s96
	s_nop 0
	global_load_lds_dwordx4 v[144:145], off
	v_lshl_add_u64 v[144:145], v[238:239], 0, s[48:49]
	s_mov_b32 m0, s14
	s_nop 0
	global_load_lds_dwordx4 v[144:145], off
	v_lshl_add_u64 v[144:145], v[240:241], 0, s[48:49]
	s_mov_b32 m0, s90
	s_nop 0
	global_load_lds_dwordx4 v[144:145], off
	v_lshl_add_u64 v[144:145], v[242:243], 0, s[48:49]
	s_mov_b32 m0, s51
	s_nop 0
	global_load_lds_dwordx4 v[144:145], off
	v_lshl_add_u64 v[144:145], v[244:245], 0, s[48:49]
	s_mov_b32 m0, s33
	s_nop 0
	global_load_lds_dwordx4 v[144:145], off
	s_waitcnt vmcnt(8)
	s_waitcnt lgkmcnt(0)
	s_barrier
	s_waitcnt lgkmcnt(0)
	v_mfma_f32_16x16x32_bf16 v[62:65], v[140:143], v[182:185], v[62:65]
	v_mfma_f32_16x16x32_bf16 v[58:61], v[154:157], v[182:185], v[58:61]
	v_mfma_f32_16x16x32_bf16 v[46:49], v[140:143], v[190:193], v[46:49]
	v_mfma_f32_16x16x32_bf16 v[42:45], v[154:157], v[190:193], v[42:45]
	v_mfma_f32_16x16x32_bf16 v[30:33], v[140:143], v[218:221], v[30:33]
	v_mfma_f32_16x16x32_bf16 v[26:29], v[154:157], v[218:221], v[26:29]
	v_mfma_f32_16x16x32_bf16 v[14:17], v[140:143], v[230:233], v[14:17]
	v_mfma_f32_16x16x32_bf16 v[10:13], v[154:157], v[230:233], v[10:13]
	v_mfma_f32_16x16x32_bf16 v[62:65], v[150:153], v[186:189], v[62:65]
	v_mfma_f32_16x16x32_bf16 v[58:61], v[158:161], v[186:189], v[58:61]
	v_mfma_f32_16x16x32_bf16 v[46:49], v[150:153], v[194:197], v[46:49]
	v_mfma_f32_16x16x32_bf16 v[42:45], v[158:161], v[194:197], v[42:45]
	v_mfma_f32_16x16x32_bf16 v[30:33], v[150:153], v[222:225], v[30:33]
	v_mfma_f32_16x16x32_bf16 v[26:29], v[158:161], v[222:225], v[26:29]
	v_mfma_f32_16x16x32_bf16 v[14:17], v[150:153], v[234:237], v[14:17]
	v_mfma_f32_16x16x32_bf16 v[10:13], v[158:161], v[234:237], v[10:13]
	v_mfma_f32_16x16x32_bf16 v[54:57], v[162:165], v[182:185], v[54:57]
	v_mfma_f32_16x16x32_bf16 v[50:53], v[170:173], v[182:185], v[50:53]
	v_mfma_f32_16x16x32_bf16 v[38:41], v[162:165], v[190:193], v[38:41]
	v_mfma_f32_16x16x32_bf16 v[34:37], v[170:173], v[190:193], v[34:37]
	v_mfma_f32_16x16x32_bf16 v[22:25], v[162:165], v[218:221], v[22:25]
	v_mfma_f32_16x16x32_bf16 v[18:21], v[170:173], v[218:221], v[18:21]
	v_mfma_f32_16x16x32_bf16 v[6:9], v[162:165], v[230:233], v[6:9]
	v_mfma_f32_16x16x32_bf16 v[2:5], v[170:173], v[230:233], v[2:5]
	v_mfma_f32_16x16x32_bf16 v[54:57], v[166:169], v[186:189], v[54:57]
	v_mfma_f32_16x16x32_bf16 v[50:53], v[174:177], v[186:189], v[50:53]
	v_mfma_f32_16x16x32_bf16 v[38:41], v[166:169], v[194:197], v[38:41]
	v_mfma_f32_16x16x32_bf16 v[34:37], v[174:177], v[194:197], v[34:37]
	v_mfma_f32_16x16x32_bf16 v[22:25], v[166:169], v[222:225], v[22:25]
	v_mfma_f32_16x16x32_bf16 v[18:21], v[174:177], v[222:225], v[18:21]
	v_mfma_f32_16x16x32_bf16 v[6:9], v[166:169], v[234:237], v[6:9]
	v_mfma_f32_16x16x32_bf16 v[2:5], v[174:177], v[234:237], v[2:5]
	s_barrier
	s_add_u32 s46, s46, 0x100
	s_addc_u32 s47, s47, 0
	s_add_u32 s26, s26, 0x100
	s_addc_u32 s27, s27, 0
	s_cmp_ge_i32 s52, s94
	s_mov_b32 s28, s52
	s_cbranch_scc0 .LBB0_1045

.LBB0_1052:
	s_mov_b32 s0, s45
	s_add_i32 s0, s0, 0x200e8
	v_mov_b32_e32 v0, s0
	ds_read_b64 v[2:3], v0
	s_mov_b32 s16, 0
	s_setprio 0
	s_getreg_b32 s0, hwreg(HW_REG_XCC_ID, 0, 4)
	s_waitcnt vmcnt(0)
	s_waitcnt lgkmcnt(0)
	v_readfirstlane_b32 s71, v3
	v_readfirstlane_b32 s70, v2
	s_barrier
	s_mov_b64 s[68:69], exec
	v_readlane_b32 s2, v252, 1
	v_readlane_b32 s3, v252, 2
	s_and_b64 s[2:3], s[68:69], s[2:3]
	s_mov_b64 exec, s[2:3]
	s_cbranch_execz .LBB0_1096
	s_add_i32 s15, s16, 0x20200
	v_mov_b32_e32 v0, s15
	s_waitcnt vmcnt(0) expcnt(0) lgkmcnt(0)
	ds_read_b32 v2, v0
	s_add_i32 s16, s16, 0x20204
	v_mov_b32_e32 v0, s16
	ds_read_b32 v0, v0
	s_and_b32 s14, s0, 15
	s_waitcnt lgkmcnt(1)
	v_cmp_ne_u32_e32 vcc, 0, v2
	s_cbranch_vccnz .LBB0_1067
	s_add_u32 s0, s70, 0x1000
	s_addc_u32 s1, s71, 0
	s_add_u32 s2, s70, 0x1100
	s_addc_u32 s3, s71, 0
	s_add_u32 s4, s70, 0x1200
	s_addc_u32 s5, s71, 0
	s_add_u32 s6, s70, 0x1300
	s_addc_u32 s7, s71, 0
	s_mov_b32 s30, 1
	s_mov_b64 s[8:9], 0
	s_branch .LBB0_1057

.LBB0_1096:
	s_or_b64 exec, exec, s[68:69]
	s_mov_b32 s16, s45
	s_mov_b32 s14, 0
	s_mov_b32 s0, 0
	s_waitcnt lgkmcnt(0)
	s_barrier
	s_add_i32 s0, s0, 0x200e8
	v_mov_b32_e32 v0, s0
	s_mov_b32 s0, 0
	ds_read_b64 v[2:3], v0
	s_add_i32 s0, s0, 0x200e8
	v_mov_b32_e32 v0, s0
	v_readlane_b32 s0, v252, 6
	s_lshl_b32 s15, s0, 1
	s_movk_i32 s0, 0x400
	s_movk_i32 s5, 0x400
	s_movk_i32 s2, 0x400
	ds_read_b64 v[4:5], v0
	s_ashr_i32 s7, s5, 31
	s_lshr_b32 s7, s7, 24
	s_add_i32 s5, s5, s7
	s_ashr_i32 s5, s5, 8
	v_readlane_b32 s47, v252, 0
	s_lshl_b32 s8, s5, 6
	v_mov_b32_e32 v150, v200
	s_waitcnt lgkmcnt(0)
	v_readfirstlane_b32 s1, v3
	v_readfirstlane_b32 s3, v2
	v_readfirstlane_b32 s4, v5
	v_readfirstlane_b32 s6, v4
	s_cmp_ge_i32 s47, s8
	v_readfirstlane_b32 s33, v150
	s_cbranch_scc1 .LBB0_1156
	v_lshlrev_b32_e32 v2, 4, v150
	v_add_u32_e32 v3, 0x2000, v2
	v_ashrrev_i32_e32 v0, 31, v3
	v_lshrrev_b32_e32 v0, 22, v0
	v_add_u32_e32 v0, v3, v0
	v_ashrrev_i32_e32 v4, 10, v0
	v_mul_i32_i24_e32 v5, 0x400, v4
	v_sub_u32_e32 v3, v3, v5
	v_lshrrev_b32_e32 v5, 4, v3
	v_bitop3_b32 v3, v5, v3, 32 bitop3:0x6c
	v_ashrrev_i32_e32 v5, 31, v3
	v_lshrrev_b32_e32 v5, 26, v5
	v_add_u32_e32 v5, v3, v5
	v_ashrrev_i32_e32 v6, 6, v5
	v_and_b32_e32 v5, 0xc0, v5
	v_lshlrev_b32_e32 v0, 5, v4
	v_sub_u32_e32 v3, v3, v5
	v_lshlrev_b32_e32 v4, 3, v4
	v_ashrrev_i16_sdwa v3, v201, sext(v3) dst_sel:DWORD dst_unused:UNUSED_PAD src0_sel:DWORD src1_sel:BYTE_0
	v_and_b32_e32 v4, -16, v4
	v_and_b32_e32 v0, 32, v0
	v_bfe_i32 v14, v3, 0, 16
	v_add_u32_e32 v4, v6, v4
	v_add_u32_e32 v3, v0, v14
	v_mul_lo_u32 v5, v4, s0
	v_mul_lo_u32 v15, v4, s2
	v_add_lshl_u32 v94, v3, v5, 1
	v_add_lshl_u32 v96, v3, v15, 1
	v_ashrrev_i32_e32 v3, 31, v150
	v_lshrrev_b32_e32 v3, 26, v3
	v_add_u32_e32 v3, v150, v3
	v_ashrrev_i32_e32 v3, 6, v3
	v_lshlrev_b32_e32 v4, 5, v3
	v_and_b32_e32 v16, 32, v4
	v_bfe_i32 v4, v150, 27, 1
	v_lshrrev_b32_e32 v4, 22, v4
	v_add_u32_e32 v4, v2, v4
	v_and_b32_e32 v4, 0xfffffc00, v4
	v_sub_u32_e32 v2, v2, v4
	s_add_u32 s50, s3, 0x4bf0000
	v_lshrrev_b32_e32 v4, 4, v2
	s_addc_u32 s51, s1, 0
	v_bitop3_b32 v2, v4, v2, 32 bitop3:0x6c
	s_add_u32 s52, s6, 0x1970000
	v_ashrrev_i32_e32 v4, 31, v2
	s_addc_u32 s53, s4, 0
	v_lshrrev_b32_e32 v4, 26, v4
	s_ashr_i32 s55, s47, 31
	v_add_u32_e32 v4, v2, v4
	s_lshr_b32 s6, s55, 29
	v_ashrrev_i32_e32 v5, 6, v4
	v_and_b32_e32 v4, 0xc0, v4
	s_add_i32 s6, s47, s6
	s_ashr_i32 s7, s33, 6
	s_ashr_i32 s3, s2, 31
	s_ashr_i32 s1, s0, 31
	v_sub_u32_e32 v2, v2, v4
	v_lshlrev_b32_e32 v3, 3, v3
	s_lshl_b32 s54, s5, 3
	s_ashr_i32 s9, s6, 3
	s_and_b32 s6, s6, -8
	s_ashr_i32 s37, s33, 8
	s_lshl_b64 s[10:11], s[2:3], 8
	s_lshl_b64 s[12:13], s[0:1], 8
	s_lshl_b64 s[18:19], s[2:3], 9
	s_lshl_b64 s[20:21], s[0:1], 9
	s_lshl_b32 s4, s7, 10
	v_ashrrev_i16_sdwa v2, v201, sext(v2) dst_sel:DWORD dst_unused:UNUSED_PAD src0_sel:DWORD src1_sel:BYTE_0
	v_and_b32_e32 v3, -16, v3
	s_sub_i32 s6, s47, s6
	s_or_b32 s58, s54, 1
	v_bfe_i32 v17, v2, 0, 16
	v_add_u32_e32 v3, v5, v3
	s_cmp_lt_i32 s6, 0
	v_add_u32_e32 v2, v16, v17
	v_mul_lo_u32 v4, v3, s0
	v_mul_lo_u32 v18, v3, s2
	s_cselect_b32 s22, s58, s54
	s_abs_i32 s60, s54
	v_add_lshl_u32 v134, v2, v4, 1
	v_add_lshl_u32 v136, v2, v18, 1
	v_cvt_f32_u32_e32 v2, s60
	s_mul_i32 s6, s22, s6
	s_sub_i32 s22, 0, s60
	s_add_i32 s6, s6, s9
	v_rcp_iflag_f32_e32 v2, v2
	s_ashr_i32 s9, s6, 31
	s_bfe_i32 s59, s5, 0x1001c
	s_xor_b32 s5, s9, s59
	v_mul_f32_e32 v2, 0x4f7ffffe, v2
	v_cvt_u32_f32_e32 v2, v2
	s_abs_i32 s9, s6
	v_mov_b32_e32 v135, v1
	v_mov_b32_e32 v95, v1
	v_readfirstlane_b32 s61, v2
	s_mul_i32 s22, s22, s61
	s_mul_hi_u32 s22, s61, s22
	s_add_i32 s61, s61, s22
	s_mul_hi_u32 s22, s9, s61
	s_mul_i32 s23, s22, s60
	s_sub_i32 s9, s9, s23
	s_add_i32 s23, s22, 1
	s_sub_i32 s24, s9, s60
	s_cmp_ge_u32 s9, s60
	s_cselect_b32 s22, s23, s22
	s_cselect_b32 s9, s24, s9
	s_add_i32 s23, s22, 1
	s_cmp_ge_u32 s9, s60
	s_cselect_b32 s9, s23, s22
	s_xor_b32 s9, s9, s5
	s_sub_i32 s5, s9, s5
	s_lshl_b32 s9, s5, 3
	s_sub_i32 s22, 64, s9
	s_min_i32 s22, s22, 8
	s_abs_i32 s24, s22
	v_cvt_f32_u32_e32 v2, s24
	s_sub_i32 s25, 0, s24
	s_mul_i32 s5, s5, s54
	s_sub_i32 s5, s6, s5
	v_rcp_iflag_f32_e32 v2, v2
	s_abs_i32 s23, s5
	s_xor_b32 s6, s5, s22
	s_ashr_i32 s6, s6, 31
	v_mul_f32_e32 v2, 0x4f7ffffe, v2
	v_cvt_u32_f32_e32 v2, v2
	v_mov_b32_e32 v137, v1
	v_mov_b32_e32 v97, v1
	v_readfirstlane_b32 s26, v2
	s_mul_i32 s25, s25, s26
	s_mul_hi_u32 s25, s26, s25
	s_add_i32 s26, s26, s25
	s_mul_hi_u32 s25, s23, s26
	s_mul_i32 s26, s25, s24
	s_sub_i32 s23, s23, s26
	s_add_i32 s26, s25, 1
	s_sub_i32 s27, s23, s24
	s_cmp_ge_u32 s23, s24
	s_cselect_b32 s25, s26, s25
	s_cselect_b32 s23, s27, s23
	s_add_i32 s26, s25, 1
	s_cmp_ge_u32 s23, s24
	s_cselect_b32 s23, s26, s25
	s_xor_b32 s23, s23, s6
	s_sub_i32 s6, s23, s6
	s_mul_i32 s22, s6, s22
	s_sub_i32 s5, s5, s22
	s_add_i32 s46, s5, s9
	s_ashr_i32 s5, s46, 31
	s_mul_i32 s5, s18, s5
	s_mul_hi_u32 s9, s18, s46
	s_lshr_b64 s[2:3], s[2:3], 23
	s_add_i32 s5, s9, s5
	s_mul_i32 s2, s2, s46
	s_add_i32 s5, s5, s2
	s_ashr_i32 s2, s6, 31
	s_mul_i32 s2, s20, s2
	s_mul_hi_u32 s3, s20, s6
	s_add_i32 s22, s3, s2
	s_lshr_b64 s[2:3], s[0:1], 23
	s_mul_i32 s2, s2, s6
	s_add_i32 s2, s22, s2
	s_mul_i32 s3, s20, s6
	s_add_u32 s22, s52, s3
	s_addc_u32 s23, s53, s2
	s_add_i32 s62, s14, 0x10000
	s_add_i32 s63, s62, s4
	s_add_i32 s64, s63, 0x2000
	s_add_u32 s2, s22, s12
	s_addc_u32 s3, s23, s13
	s_add_i32 s65, s14, 0x14000
	s_add_i32 s66, s65, s4
	s_mul_i32 s9, s18, s46
	s_mov_b32 m0, s63
	s_add_i32 s67, s66, 0x2000
	global_load_lds_dwordx4 v134, s[22:23]
	s_mov_b32 m0, s64
	s_add_u32 s24, s50, s9
	global_load_lds_dwordx4 v94, s[22:23]
	s_mov_b32 m0, s66
	s_addc_u32 s25, s51, s5
	s_add_i32 s68, s14, s4
	global_load_lds_dwordx4 v134, s[2:3]
	s_mov_b32 m0, s67
	s_add_i32 s69, s68, 0x2000
	v_lshl_add_u64 v[6:7], s[2:3], 0, v[134:135]
	v_lshl_add_u64 v[8:9], s[2:3], 0, v[94:95]
	global_load_lds_dwordx4 v94, s[2:3]
	s_mov_b32 m0, s68
	s_add_u32 s2, s24, s10
	global_load_lds_dwordx4 v136, s[24:25]
	s_mov_b32 m0, s69
	s_addc_u32 s3, s25, s11
	s_add_i32 s70, s68, 0x4000
	global_load_lds_dwordx4 v96, s[24:25]
	s_mov_b32 m0, s70
	s_add_i32 s71, s68, 0x6000
	global_load_lds_dwordx4 v136, s[2:3]
	s_mov_b32 m0, s71
	v_lshl_add_u64 v[2:3], s[22:23], 0, v[134:135]
	global_load_lds_dwordx4 v96, s[2:3]
	v_lshl_add_u64 v[4:5], s[22:23], 0, v[94:95]
	v_lshl_add_u64 v[10:11], s[24:25], 0, v[136:137]
	v_lshl_add_u64 v[12:13], s[24:25], 0, v[96:97]
	s_cmp_lg_u32 s37, 1
	s_cbranch_scc1 .LBB0_1099
	s_barrier
	s_setprio 1

.LBB0_1109:
	v_add_u32_e32 v0, s62, v142
	ds_read_b128 v[144:147], v0
	ds_read_b128 v[156:159], v0 offset:1024
	ds_read_b128 v[160:163], v0 offset:2048
	ds_read_b128 v[164:167], v0 offset:3072
	v_add_u32_e32 v0, s65, v142
	ds_read_b128 v[168:171], v0
	ds_read_b128 v[172:175], v0 offset:1024
	ds_read_b128 v[182:185], v0 offset:2048
	ds_read_b128 v[186:189], v0 offset:3072
	s_add_i32 s88, s34, 2
	s_add_u32 s89, s30, 0x80
	s_addc_u32 s35, s31, 0
	s_cmp_eq_u32 s81, s34
	s_cselect_b32 s34, s0, s89
	s_cselect_b32 s35, s1, s35
	s_cselect_b32 s91, s29, s87
	s_cselect_b32 s90, s28, s86
	v_lshl_add_u64 v[148:149], s[30:31], 0, v[140:141]
	s_add_i32 m0, s68, 0xc000
	ds_read_b128 v[190:193], v143
	ds_read_b128 v[194:197], v143 offset:1024
	ds_read_b128 v[218:221], v143 offset:2048
	ds_read_b128 v[222:225], v143 offset:3072
	ds_read_b128 v[230:233], v143 offset:4096
	ds_read_b128 v[234:237], v143 offset:5120
	ds_read_b128 v[238:241], v143 offset:6144
	ds_read_b128 v[242:245], v143 offset:7168
	global_load_lds_dwordx4 v[148:149], off
	v_lshl_add_u64 v[148:149], s[30:31], 0, v[138:139]
	s_add_i32 m0, s68, 0xe000
	s_nop 0
	global_load_lds_dwordx4 v[148:149], off
	s_waitcnt vmcnt(8)
	s_waitcnt lgkmcnt(0)
	s_barrier
	s_waitcnt lgkmcnt(0)
	v_mfma_f32_16x16x32_bf16 v[2:5], v[144:147], v[190:193], v[2:5]
	v_mfma_f32_16x16x32_bf16 v[66:69], v[160:163], v[190:193], v[66:69]
	v_mfma_f32_16x16x32_bf16 v[102:105], v[144:147], v[218:221], v[102:105]
	v_mfma_f32_16x16x32_bf16 v[70:73], v[160:163], v[218:221], v[70:73]
	v_mfma_f32_16x16x32_bf16 v[106:109], v[144:147], v[230:233], v[106:109]
	v_mfma_f32_16x16x32_bf16 v[74:77], v[160:163], v[230:233], v[74:77]
	v_mfma_f32_16x16x32_bf16 v[110:113], v[144:147], v[238:241], v[110:113]
	v_mfma_f32_16x16x32_bf16 v[78:81], v[160:163], v[238:241], v[78:81]
	v_mfma_f32_16x16x32_bf16 v[2:5], v[156:159], v[194:197], v[2:5]
	v_mfma_f32_16x16x32_bf16 v[66:69], v[164:167], v[194:197], v[66:69]
	v_mfma_f32_16x16x32_bf16 v[102:105], v[156:159], v[222:225], v[102:105]
	v_mfma_f32_16x16x32_bf16 v[70:73], v[164:167], v[222:225], v[70:73]
	v_mfma_f32_16x16x32_bf16 v[106:109], v[156:159], v[234:237], v[106:109]
	v_mfma_f32_16x16x32_bf16 v[74:77], v[164:167], v[234:237], v[74:77]
	v_mfma_f32_16x16x32_bf16 v[110:113], v[156:159], v[242:245], v[110:113]
	v_mfma_f32_16x16x32_bf16 v[78:81], v[164:167], v[242:245], v[78:81]
	v_mfma_f32_16x16x32_bf16 v[34:37], v[168:171], v[190:193], v[34:37]
	v_mfma_f32_16x16x32_bf16 v[130:133], v[182:185], v[190:193], v[130:133]
	v_mfma_f32_16x16x32_bf16 v[38:41], v[168:171], v[218:221], v[38:41]
	v_mfma_f32_16x16x32_bf16 v[6:9], v[182:185], v[218:221], v[6:9]
	v_mfma_f32_16x16x32_bf16 v[42:45], v[168:171], v[230:233], v[42:45]
	v_mfma_f32_16x16x32_bf16 v[10:13], v[182:185], v[230:233], v[10:13]
	v_mfma_f32_16x16x32_bf16 v[46:49], v[168:171], v[238:241], v[46:49]
	v_mfma_f32_16x16x32_bf16 v[14:17], v[182:185], v[238:241], v[14:17]
	v_mfma_f32_16x16x32_bf16 v[34:37], v[172:175], v[194:197], v[34:37]
	v_mfma_f32_16x16x32_bf16 v[130:133], v[186:189], v[194:197], v[130:133]
	v_mfma_f32_16x16x32_bf16 v[38:41], v[172:175], v[222:225], v[38:41]
	v_mfma_f32_16x16x32_bf16 v[6:9], v[186:189], v[222:225], v[6:9]
	v_mfma_f32_16x16x32_bf16 v[42:45], v[172:175], v[234:237], v[42:45]
	v_mfma_f32_16x16x32_bf16 v[10:13], v[186:189], v[234:237], v[10:13]
	v_mfma_f32_16x16x32_bf16 v[46:49], v[172:175], v[242:245], v[46:49]
	v_mfma_f32_16x16x32_bf16 v[14:17], v[186:189], v[242:245], v[14:17]
	s_barrier
	s_mov_b32 m0, s63
	v_lshl_add_u64 v[148:149], s[90:91], 0, v[134:135]
	v_lshl_add_u64 v[152:153], s[90:91], 0, v[94:95]
	s_add_u32 s90, s90, s12
	ds_read_b128 v[190:193], v143 offset:16384
	ds_read_b128 v[194:197], v143 offset:17408
	ds_read_b128 v[218:221], v143 offset:18432
	ds_read_b128 v[222:225], v143 offset:19456
	ds_read_b128 v[230:233], v143 offset:20480
	ds_read_b128 v[234:237], v143 offset:21504
	ds_read_b128 v[238:241], v143 offset:22528
	ds_read_b128 v[242:245], v143 offset:23552
	global_load_lds_dwordx4 v[148:149], off
	s_mov_b32 m0, s64
	s_addc_u32 s91, s91, s13
	global_load_lds_dwordx4 v[152:153], off
	v_lshl_add_u64 v[176:177], s[90:91], 0, v[134:135]
	s_mov_b32 m0, s66
	v_lshl_add_u64 v[198:199], s[90:91], 0, v[94:95]
	global_load_lds_dwordx4 v[176:177], off
	s_mov_b32 m0, s67
	v_lshl_add_u64 v[246:247], s[34:35], 0, v[136:137]
	global_load_lds_dwordx4 v[198:199], off
	s_mov_b32 m0, s68
	v_lshl_add_u64 v[248:249], s[34:35], 0, v[96:97]
	global_load_lds_dwordx4 v[246:247], off
	s_mov_b32 m0, s69
	s_nop 0
	global_load_lds_dwordx4 v[248:249], off
	s_waitcnt vmcnt(8)
	s_waitcnt lgkmcnt(0)
	s_barrier
	s_waitcnt lgkmcnt(0)
	v_mfma_f32_16x16x32_bf16 v[114:117], v[144:147], v[190:193], v[114:117]
	v_mfma_f32_16x16x32_bf16 v[82:85], v[160:163], v[190:193], v[82:85]
	v_mfma_f32_16x16x32_bf16 v[118:121], v[144:147], v[218:221], v[118:121]
	v_mfma_f32_16x16x32_bf16 v[86:89], v[160:163], v[218:221], v[86:89]
	v_mfma_f32_16x16x32_bf16 v[122:125], v[144:147], v[230:233], v[122:125]
	v_mfma_f32_16x16x32_bf16 v[90:93], v[160:163], v[230:233], v[90:93]
	v_mfma_f32_16x16x32_bf16 v[126:129], v[144:147], v[238:241], v[126:129]
	v_mfma_f32_16x16x32_bf16 v[98:101], v[160:163], v[238:241], v[98:101]
	v_mfma_f32_16x16x32_bf16 v[114:117], v[156:159], v[194:197], v[114:117]
	v_mfma_f32_16x16x32_bf16 v[82:85], v[164:167], v[194:197], v[82:85]
	v_mfma_f32_16x16x32_bf16 v[118:121], v[156:159], v[222:225], v[118:121]
	v_mfma_f32_16x16x32_bf16 v[86:89], v[164:167], v[222:225], v[86:89]
	v_mfma_f32_16x16x32_bf16 v[122:125], v[156:159], v[234:237], v[122:125]
	v_mfma_f32_16x16x32_bf16 v[90:93], v[164:167], v[234:237], v[90:93]
	v_mfma_f32_16x16x32_bf16 v[126:129], v[156:159], v[242:245], v[126:129]
	v_mfma_f32_16x16x32_bf16 v[98:101], v[164:167], v[242:245], v[98:101]
	v_mfma_f32_16x16x32_bf16 v[50:53], v[168:171], v[190:193], v[50:53]
	v_mfma_f32_16x16x32_bf16 v[18:21], v[182:185], v[190:193], v[18:21]
	v_mfma_f32_16x16x32_bf16 v[54:57], v[168:171], v[218:221], v[54:57]
	v_mfma_f32_16x16x32_bf16 v[22:25], v[182:185], v[218:221], v[22:25]
	v_mfma_f32_16x16x32_bf16 v[58:61], v[168:171], v[230:233], v[58:61]
	v_mfma_f32_16x16x32_bf16 v[26:29], v[182:185], v[230:233], v[26:29]
	v_mfma_f32_16x16x32_bf16 v[62:65], v[168:171], v[238:241], v[62:65]
	v_mfma_f32_16x16x32_bf16 v[30:33], v[182:185], v[238:241], v[30:33]
	v_mfma_f32_16x16x32_bf16 v[50:53], v[172:175], v[194:197], v[50:53]
	v_mfma_f32_16x16x32_bf16 v[18:21], v[186:189], v[194:197], v[18:21]
	v_mfma_f32_16x16x32_bf16 v[54:57], v[172:175], v[222:225], v[54:57]
	v_mfma_f32_16x16x32_bf16 v[22:25], v[186:189], v[222:225], v[22:25]
	v_mfma_f32_16x16x32_bf16 v[58:61], v[172:175], v[234:237], v[58:61]
	v_mfma_f32_16x16x32_bf16 v[26:29], v[186:189], v[234:237], v[26:29]
	v_mfma_f32_16x16x32_bf16 v[62:65], v[172:175], v[242:245], v[62:65]
	v_mfma_f32_16x16x32_bf16 v[30:33], v[186:189], v[242:245], v[30:33]
	s_barrier
	v_add_u32_e32 v0, s72, v142
	ds_read_b128 v[144:147], v0
	ds_read_b128 v[156:159], v0 offset:1024
	ds_read_b128 v[160:163], v0 offset:2048
	ds_read_b128 v[164:167], v0 offset:3072
	v_add_u32_e32 v0, s77, v142
	ds_read_b128 v[168:171], v0
	ds_read_b128 v[172:175], v0 offset:1024
	ds_read_b128 v[182:185], v0 offset:2048
	ds_read_b128 v[186:189], v0 offset:3072
	s_add_u32 s34, s34, s10
	s_addc_u32 s35, s35, s11
	s_mov_b32 m0, s70
	v_lshl_add_u64 v[250:251], s[34:35], 0, v[136:137]
	ds_read_b128 v[190:193], v143 offset:32768
	ds_read_b128 v[194:197], v143 offset:33792
	ds_read_b128 v[218:221], v143 offset:34816
	ds_read_b128 v[222:225], v143 offset:35840
	ds_read_b128 v[230:233], v143 offset:36864
	ds_read_b128 v[234:237], v143 offset:37888
	ds_read_b128 v[238:241], v143 offset:38912
	ds_read_b128 v[242:245], v143 offset:39936
	global_load_lds_dwordx4 v[250:251], off
	v_lshl_add_u64 v[250:251], s[34:35], 0, v[96:97]
	s_mov_b32 m0, s71
	s_nop 0
	global_load_lds_dwordx4 v[250:251], off
	s_waitcnt vmcnt(8)
	s_waitcnt lgkmcnt(0)
	s_barrier
	s_waitcnt lgkmcnt(0)
	v_mfma_f32_16x16x32_bf16 v[2:5], v[144:147], v[190:193], v[2:5]
	v_mfma_f32_16x16x32_bf16 v[66:69], v[160:163], v[190:193], v[66:69]
	v_mfma_f32_16x16x32_bf16 v[102:105], v[144:147], v[218:221], v[102:105]
	v_mfma_f32_16x16x32_bf16 v[70:73], v[160:163], v[218:221], v[70:73]
	v_mfma_f32_16x16x32_bf16 v[106:109], v[144:147], v[230:233], v[106:109]
	v_mfma_f32_16x16x32_bf16 v[74:77], v[160:163], v[230:233], v[74:77]
	v_mfma_f32_16x16x32_bf16 v[110:113], v[144:147], v[238:241], v[110:113]
	v_mfma_f32_16x16x32_bf16 v[78:81], v[160:163], v[238:241], v[78:81]
	v_mfma_f32_16x16x32_bf16 v[2:5], v[156:159], v[194:197], v[2:5]
	v_mfma_f32_16x16x32_bf16 v[66:69], v[164:167], v[194:197], v[66:69]
	v_mfma_f32_16x16x32_bf16 v[102:105], v[156:159], v[222:225], v[102:105]
	v_mfma_f32_16x16x32_bf16 v[70:73], v[164:167], v[222:225], v[70:73]
	v_mfma_f32_16x16x32_bf16 v[106:109], v[156:159], v[234:237], v[106:109]
	v_mfma_f32_16x16x32_bf16 v[74:77], v[164:167], v[234:237], v[74:77]
	v_mfma_f32_16x16x32_bf16 v[110:113], v[156:159], v[242:245], v[110:113]
	v_mfma_f32_16x16x32_bf16 v[78:81], v[164:167], v[242:245], v[78:81]
	v_mfma_f32_16x16x32_bf16 v[34:37], v[168:171], v[190:193], v[34:37]
	v_mfma_f32_16x16x32_bf16 v[130:133], v[182:185], v[190:193], v[130:133]
	v_mfma_f32_16x16x32_bf16 v[38:41], v[168:171], v[218:221], v[38:41]
	v_mfma_f32_16x16x32_bf16 v[6:9], v[182:185], v[218:221], v[6:9]
	v_mfma_f32_16x16x32_bf16 v[42:45], v[168:171], v[230:233], v[42:45]
	v_mfma_f32_16x16x32_bf16 v[10:13], v[182:185], v[230:233], v[10:13]
	v_mfma_f32_16x16x32_bf16 v[46:49], v[168:171], v[238:241], v[46:49]
	v_mfma_f32_16x16x32_bf16 v[14:17], v[182:185], v[238:241], v[14:17]
	v_mfma_f32_16x16x32_bf16 v[34:37], v[172:175], v[194:197], v[34:37]
	v_mfma_f32_16x16x32_bf16 v[130:133], v[186:189], v[194:197], v[130:133]
	v_mfma_f32_16x16x32_bf16 v[38:41], v[172:175], v[222:225], v[38:41]
	v_mfma_f32_16x16x32_bf16 v[6:9], v[186:189], v[222:225], v[6:9]
	v_mfma_f32_16x16x32_bf16 v[42:45], v[172:175], v[234:237], v[42:45]
	v_mfma_f32_16x16x32_bf16 v[10:13], v[186:189], v[234:237], v[10:13]
	v_mfma_f32_16x16x32_bf16 v[46:49], v[172:175], v[242:245], v[46:49]
	v_mfma_f32_16x16x32_bf16 v[14:17], v[186:189], v[242:245], v[14:17]
	s_barrier
	s_mov_b32 m0, s73
	v_lshl_add_u64 v[148:149], v[148:149], 0, s[48:49]
	ds_read_b128 v[190:193], v143 offset:49152
	ds_read_b128 v[194:197], v143 offset:50176
	ds_read_b128 v[218:221], v143 offset:51200
	ds_read_b128 v[222:225], v143 offset:52224
	ds_read_b128 v[230:233], v143 offset:53248
	ds_read_b128 v[234:237], v143 offset:54272
	ds_read_b128 v[238:241], v143 offset:55296
	ds_read_b128 v[242:245], v143 offset:56320
	global_load_lds_dwordx4 v[148:149], off
	v_lshl_add_u64 v[148:149], v[152:153], 0, s[48:49]
	s_mov_b32 m0, s74
	s_nop 0
	global_load_lds_dwordx4 v[148:149], off
	v_lshl_add_u64 v[148:149], v[176:177], 0, s[48:49]
	s_mov_b32 m0, s78
	s_nop 0
	global_load_lds_dwordx4 v[148:149], off
	v_lshl_add_u64 v[148:149], v[198:199], 0, s[48:49]
	s_mov_b32 m0, s79
	s_nop 0
	global_load_lds_dwordx4 v[148:149], off
	v_lshl_add_u64 v[148:149], v[246:247], 0, s[48:49]
	s_mov_b32 m0, s75
	s_nop 0
	global_load_lds_dwordx4 v[148:149], off
	v_lshl_add_u64 v[148:149], v[248:249], 0, s[48:49]
	s_mov_b32 m0, s76
	s_nop 0
	global_load_lds_dwordx4 v[148:149], off
	s_waitcnt vmcnt(8)
	s_waitcnt lgkmcnt(0)
	s_barrier
	s_waitcnt lgkmcnt(0)
	v_mfma_f32_16x16x32_bf16 v[114:117], v[144:147], v[190:193], v[114:117]
	v_mfma_f32_16x16x32_bf16 v[82:85], v[160:163], v[190:193], v[82:85]
	v_mfma_f32_16x16x32_bf16 v[118:121], v[144:147], v[218:221], v[118:121]
	v_mfma_f32_16x16x32_bf16 v[86:89], v[160:163], v[218:221], v[86:89]
	v_mfma_f32_16x16x32_bf16 v[122:125], v[144:147], v[230:233], v[122:125]
	v_mfma_f32_16x16x32_bf16 v[90:93], v[160:163], v[230:233], v[90:93]
	v_mfma_f32_16x16x32_bf16 v[126:129], v[144:147], v[238:241], v[126:129]
	v_mfma_f32_16x16x32_bf16 v[98:101], v[160:163], v[238:241], v[98:101]
	v_mfma_f32_16x16x32_bf16 v[114:117], v[156:159], v[194:197], v[114:117]
	v_mfma_f32_16x16x32_bf16 v[82:85], v[164:167], v[194:197], v[82:85]
	v_mfma_f32_16x16x32_bf16 v[118:121], v[156:159], v[222:225], v[118:121]
	v_mfma_f32_16x16x32_bf16 v[86:89], v[164:167], v[222:225], v[86:89]
	v_mfma_f32_16x16x32_bf16 v[122:125], v[156:159], v[234:237], v[122:125]
	v_mfma_f32_16x16x32_bf16 v[90:93], v[164:167], v[234:237], v[90:93]
	v_mfma_f32_16x16x32_bf16 v[126:129], v[156:159], v[242:245], v[126:129]
	v_mfma_f32_16x16x32_bf16 v[98:101], v[164:167], v[242:245], v[98:101]
	v_mfma_f32_16x16x32_bf16 v[50:53], v[168:171], v[190:193], v[50:53]
	v_mfma_f32_16x16x32_bf16 v[18:21], v[182:185], v[190:193], v[18:21]
	v_mfma_f32_16x16x32_bf16 v[54:57], v[168:171], v[218:221], v[54:57]
	v_mfma_f32_16x16x32_bf16 v[22:25], v[182:185], v[218:221], v[22:25]
	v_mfma_f32_16x16x32_bf16 v[58:61], v[168:171], v[230:233], v[58:61]
	v_mfma_f32_16x16x32_bf16 v[26:29], v[182:185], v[230:233], v[26:29]
	v_mfma_f32_16x16x32_bf16 v[62:65], v[168:171], v[238:241], v[62:65]
	v_mfma_f32_16x16x32_bf16 v[30:33], v[182:185], v[238:241], v[30:33]
	v_mfma_f32_16x16x32_bf16 v[50:53], v[172:175], v[194:197], v[50:53]
	v_mfma_f32_16x16x32_bf16 v[18:21], v[186:189], v[194:197], v[18:21]
	v_mfma_f32_16x16x32_bf16 v[54:57], v[172:175], v[222:225], v[54:57]
	v_mfma_f32_16x16x32_bf16 v[22:25], v[186:189], v[222:225], v[22:25]
	v_mfma_f32_16x16x32_bf16 v[58:61], v[172:175], v[234:237], v[58:61]
	v_mfma_f32_16x16x32_bf16 v[26:29], v[186:189], v[234:237], v[26:29]
	v_mfma_f32_16x16x32_bf16 v[62:65], v[172:175], v[242:245], v[62:65]
	v_mfma_f32_16x16x32_bf16 v[30:33], v[186:189], v[242:245], v[30:33]
	s_barrier
	s_add_u32 s86, s86, 0x100
	s_addc_u32 s87, s87, 0
	s_add_u32 s30, s30, 0x100
	s_addc_u32 s31, s31, 0
	s_cmp_ge_i32 s88, s80
	s_mov_b32 s34, s88
	s_cbranch_scc0 .LBB0_1109

.LBB0_1156:
	s_mov_b32 s16, s45
	s_mov_b32 s14, 0
	s_mov_b32 s0, 0
	s_waitcnt lgkmcnt(0)
	s_barrier
	s_add_i32 s0, s0, 0x200e8
	v_mov_b32_e32 v0, s0
	s_mov_b32 s0, 0
	ds_read_b64 v[2:3], v0
	s_add_i32 s0, s0, 0x200e8
	v_mov_b32_e32 v0, s0
	s_movk_i32 s0, 0x400
	s_movk_i32 s5, 0x400
	s_movk_i32 s2, 0x400
	ds_read_b64 v[4:5], v0
	s_ashr_i32 s7, s5, 31
	s_lshr_b32 s7, s7, 24
	s_add_i32 s5, s5, s7
	s_ashr_i32 s5, s5, 8
	v_readlane_b32 s46, v252, 0
	s_lshl_b32 s8, s5, 6
	v_mov_b32_e32 v150, v200
	s_waitcnt lgkmcnt(0)
	v_readfirstlane_b32 s1, v3
	v_readfirstlane_b32 s3, v2
	v_readfirstlane_b32 s4, v5
	v_readfirstlane_b32 s6, v4
	s_cmp_ge_i32 s46, s8
	v_readfirstlane_b32 s33, v150
	s_cbranch_scc1 .LBB0_1216
	v_lshlrev_b32_e32 v2, 4, v150
	v_add_u32_e32 v3, 0x2000, v2
	v_ashrrev_i32_e32 v0, 31, v3
	v_lshrrev_b32_e32 v0, 22, v0
	v_add_u32_e32 v0, v3, v0
	v_ashrrev_i32_e32 v4, 10, v0
	v_mul_i32_i24_e32 v5, 0x400, v4
	v_sub_u32_e32 v3, v3, v5
	v_lshrrev_b32_e32 v5, 4, v3
	v_bitop3_b32 v3, v5, v3, 32 bitop3:0x6c
	v_ashrrev_i32_e32 v5, 31, v3
	v_lshrrev_b32_e32 v5, 26, v5
	v_add_u32_e32 v5, v3, v5
	v_ashrrev_i32_e32 v6, 6, v5
	v_and_b32_e32 v5, 0xc0, v5
	v_lshlrev_b32_e32 v0, 5, v4
	v_sub_u32_e32 v3, v3, v5
	v_lshlrev_b32_e32 v4, 3, v4
	v_ashrrev_i16_sdwa v3, v201, sext(v3) dst_sel:DWORD dst_unused:UNUSED_PAD src0_sel:DWORD src1_sel:BYTE_0
	v_and_b32_e32 v4, -16, v4
	v_and_b32_e32 v0, 32, v0
	v_bfe_i32 v14, v3, 0, 16
	v_add_u32_e32 v4, v6, v4
	v_add_u32_e32 v3, v0, v14
	v_mul_lo_u32 v5, v4, s0
	v_mul_lo_u32 v15, v4, s2
	v_add_lshl_u32 v94, v3, v5, 1
	v_add_lshl_u32 v96, v3, v15, 1
	v_ashrrev_i32_e32 v3, 31, v150
	v_lshrrev_b32_e32 v3, 26, v3
	v_add_u32_e32 v3, v150, v3
	v_ashrrev_i32_e32 v3, 6, v3
	v_lshlrev_b32_e32 v4, 5, v3
	v_and_b32_e32 v16, 32, v4
	v_bfe_i32 v4, v150, 27, 1
	v_lshrrev_b32_e32 v4, 22, v4
	v_add_u32_e32 v4, v2, v4
	v_and_b32_e32 v4, 0xfffffc00, v4
	v_sub_u32_e32 v2, v2, v4
	s_add_u32 s47, s3, 0x6bf0000
	v_lshrrev_b32_e32 v4, 4, v2
	s_addc_u32 s50, s1, 0
	v_bitop3_b32 v2, v4, v2, 32 bitop3:0x6c
	s_add_u32 s51, s6, 0x1970000
	v_ashrrev_i32_e32 v4, 31, v2
	s_addc_u32 s52, s4, 0
	v_lshrrev_b32_e32 v4, 26, v4
	s_ashr_i32 s54, s46, 31
	v_add_u32_e32 v4, v2, v4
	s_lshr_b32 s6, s54, 29
	v_ashrrev_i32_e32 v5, 6, v4
	v_and_b32_e32 v4, 0xc0, v4
	s_add_i32 s6, s46, s6
	s_ashr_i32 s7, s33, 6
	s_ashr_i32 s3, s2, 31
	s_ashr_i32 s1, s0, 31
	v_sub_u32_e32 v2, v2, v4
	v_lshlrev_b32_e32 v3, 3, v3
	s_lshl_b32 s53, s5, 3
	s_ashr_i32 s9, s6, 3
	s_and_b32 s6, s6, -8
	s_ashr_i32 s37, s33, 8
	s_lshl_b64 s[10:11], s[2:3], 8
	s_lshl_b64 s[12:13], s[0:1], 8
	s_lshl_b64 s[18:19], s[2:3], 9
	s_lshl_b64 s[20:21], s[0:1], 9
	s_lshl_b32 s4, s7, 10
	v_ashrrev_i16_sdwa v2, v201, sext(v2) dst_sel:DWORD dst_unused:UNUSED_PAD src0_sel:DWORD src1_sel:BYTE_0
	v_and_b32_e32 v3, -16, v3
	s_sub_i32 s6, s46, s6
	s_or_b32 s55, s53, 1
	v_bfe_i32 v17, v2, 0, 16
	v_add_u32_e32 v3, v5, v3
	s_cmp_lt_i32 s6, 0
	v_add_u32_e32 v2, v16, v17
	v_mul_lo_u32 v4, v3, s0
	v_mul_lo_u32 v18, v3, s2
	s_cselect_b32 s22, s55, s53
	s_abs_i32 s59, s53
	v_add_lshl_u32 v134, v2, v4, 1
	v_add_lshl_u32 v136, v2, v18, 1
	v_cvt_f32_u32_e32 v2, s59
	s_mul_i32 s6, s22, s6
	s_sub_i32 s22, 0, s59
	s_add_i32 s6, s6, s9
	v_rcp_iflag_f32_e32 v2, v2
	s_ashr_i32 s9, s6, 31
	s_bfe_i32 s58, s5, 0x1001c
	s_xor_b32 s5, s9, s58
	v_mul_f32_e32 v2, 0x4f7ffffe, v2
	v_cvt_u32_f32_e32 v2, v2
	s_abs_i32 s9, s6
	v_mov_b32_e32 v135, v1
	v_mov_b32_e32 v95, v1
	v_readfirstlane_b32 s60, v2
	s_mul_i32 s22, s22, s60
	s_mul_hi_u32 s22, s60, s22
	s_add_i32 s60, s60, s22
	s_mul_hi_u32 s22, s9, s60
	s_mul_i32 s23, s22, s59
	s_sub_i32 s9, s9, s23
	s_add_i32 s23, s22, 1
	s_sub_i32 s24, s9, s59
	s_cmp_ge_u32 s9, s59
	s_cselect_b32 s22, s23, s22
	s_cselect_b32 s9, s24, s9
	s_add_i32 s23, s22, 1
	s_cmp_ge_u32 s9, s59
	s_cselect_b32 s9, s23, s22
	s_xor_b32 s9, s9, s5
	s_sub_i32 s5, s9, s5
	s_lshl_b32 s9, s5, 3
	s_sub_i32 s22, 64, s9
	s_min_i32 s22, s22, 8
	s_abs_i32 s24, s22
	v_cvt_f32_u32_e32 v2, s24
	s_sub_i32 s25, 0, s24
	s_mul_i32 s5, s5, s53
	s_sub_i32 s5, s6, s5
	v_rcp_iflag_f32_e32 v2, v2
	s_abs_i32 s23, s5
	s_xor_b32 s6, s5, s22
	s_ashr_i32 s6, s6, 31
	v_mul_f32_e32 v2, 0x4f7ffffe, v2
	v_cvt_u32_f32_e32 v2, v2
	v_mov_b32_e32 v137, v1
	v_mov_b32_e32 v97, v1
	v_readfirstlane_b32 s26, v2
	s_mul_i32 s25, s25, s26
	s_mul_hi_u32 s25, s26, s25
	s_add_i32 s26, s26, s25
	s_mul_hi_u32 s25, s23, s26
	s_mul_i32 s26, s25, s24
	s_sub_i32 s23, s23, s26
	s_add_i32 s26, s25, 1
	s_sub_i32 s27, s23, s24
	s_cmp_ge_u32 s23, s24
	s_cselect_b32 s25, s26, s25
	s_cselect_b32 s23, s27, s23
	s_add_i32 s26, s25, 1
	s_cmp_ge_u32 s23, s24
	s_cselect_b32 s23, s26, s25
	s_xor_b32 s23, s23, s6
	s_sub_i32 s6, s23, s6
	s_mul_i32 s22, s6, s22
	s_sub_i32 s5, s5, s22
	s_add_i32 s61, s5, s9
	s_ashr_i32 s5, s61, 31
	s_mul_i32 s5, s18, s5
	s_mul_hi_u32 s9, s18, s61
	s_lshr_b64 s[2:3], s[2:3], 23
	s_add_i32 s5, s9, s5
	s_mul_i32 s2, s2, s61
	s_add_i32 s5, s5, s2
	s_ashr_i32 s2, s6, 31
	s_mul_i32 s2, s20, s2
	s_mul_hi_u32 s3, s20, s6
	s_add_i32 s22, s3, s2
	s_lshr_b64 s[2:3], s[0:1], 23
	s_mul_i32 s2, s2, s6
	s_add_i32 s2, s22, s2
	s_mul_i32 s3, s20, s6
	s_add_u32 s22, s51, s3
	s_addc_u32 s23, s52, s2
	s_add_i32 s62, s14, 0x10000
	s_add_i32 s63, s62, s4
	s_add_i32 s64, s63, 0x2000
	s_add_u32 s2, s22, s12
	s_addc_u32 s3, s23, s13
	s_add_i32 s65, s14, 0x14000
	s_add_i32 s66, s65, s4
	s_mul_i32 s9, s18, s61
	s_mov_b32 m0, s63
	s_add_i32 s67, s66, 0x2000
	global_load_lds_dwordx4 v134, s[22:23]
	s_mov_b32 m0, s64
	s_add_u32 s24, s47, s9
	global_load_lds_dwordx4 v94, s[22:23]
	s_mov_b32 m0, s66
	s_addc_u32 s25, s50, s5
	s_add_i32 s68, s14, s4
	global_load_lds_dwordx4 v134, s[2:3]
	s_mov_b32 m0, s67
	s_add_i32 s69, s68, 0x2000
	v_lshl_add_u64 v[6:7], s[2:3], 0, v[134:135]
	v_lshl_add_u64 v[8:9], s[2:3], 0, v[94:95]
	global_load_lds_dwordx4 v94, s[2:3]
	s_mov_b32 m0, s68
	s_add_u32 s2, s24, s10
	global_load_lds_dwordx4 v136, s[24:25]
	s_mov_b32 m0, s69
	s_addc_u32 s3, s25, s11
	s_add_i32 s70, s68, 0x4000
	global_load_lds_dwordx4 v96, s[24:25]
	s_mov_b32 m0, s70
	s_add_i32 s71, s68, 0x6000
	global_load_lds_dwordx4 v136, s[2:3]
	s_mov_b32 m0, s71
	v_lshl_add_u64 v[2:3], s[22:23], 0, v[134:135]
	global_load_lds_dwordx4 v96, s[2:3]
	v_lshl_add_u64 v[4:5], s[22:23], 0, v[94:95]
	v_lshl_add_u64 v[10:11], s[24:25], 0, v[136:137]
	v_lshl_add_u64 v[12:13], s[24:25], 0, v[96:97]
	s_cmp_lg_u32 s37, 1
	s_cbranch_scc1 .LBB0_1159
	s_barrier
	s_setprio 1

.LBB0_1216:
	s_mov_b32 s0, s45
	s_waitcnt lgkmcnt(0)
	s_barrier
	s_add_i32 s0, s0, 0x200e8
	v_mov_b32_e32 v0, s0
	ds_read_b64 v[2:3], v0
	s_mov_b32 s33, 0
	s_setprio 0
	s_getreg_b32 s0, hwreg(HW_REG_XCC_ID, 0, 4)
	s_waitcnt vmcnt(0)
	s_waitcnt lgkmcnt(0)
	v_readfirstlane_b32 s71, v3
	v_readfirstlane_b32 s70, v2
	s_barrier
	s_mov_b64 s[68:69], exec
	v_readlane_b32 s2, v252, 1
	v_readlane_b32 s3, v252, 2
	s_and_b64 s[2:3], s[68:69], s[2:3]
	s_mov_b64 exec, s[2:3]
	s_cbranch_execz .LBB0_1260
	s_add_i32 s16, s33, 0x20200
	v_mov_b32_e32 v0, s16
	s_waitcnt vmcnt(0) expcnt(0) lgkmcnt(0)
	ds_read_b32 v2, v0
	s_add_i32 s33, s33, 0x20204
	v_mov_b32_e32 v0, s33
	ds_read_b32 v0, v0
	s_and_b32 s14, s0, 15
	s_waitcnt lgkmcnt(1)
	v_cmp_ne_u32_e32 vcc, 0, v2
	s_cbranch_vccnz .LBB0_1231
	s_add_u32 s0, s70, 0x1000
	s_addc_u32 s1, s71, 0
	s_add_u32 s2, s70, 0x1100
	s_addc_u32 s3, s71, 0
	s_add_u32 s4, s70, 0x1200
	s_addc_u32 s5, s71, 0
	s_add_u32 s6, s70, 0x1300
	s_addc_u32 s7, s71, 0
	s_mov_b32 s30, 1
	s_mov_b64 s[8:9], 0
	s_branch .LBB0_1221

.LBB0_1260:
	s_or_b64 exec, exec, s[68:69]
	s_mov_b32 s89, s45
	s_mov_b32 s9, 0
	s_mov_b32 s0, 0
	s_waitcnt lgkmcnt(0)
	s_barrier
	s_add_i32 s0, s0, 0x200e8
	v_mov_b32_e32 v0, s0
	s_mov_b32 s0, 0
	ds_read_b64 v[2:3], v0
	s_add_i32 s0, s0, 0x200e8
	v_mov_b32_e32 v0, s0
	s_movk_i32 s4, 0x1600
	s_movk_i32 s0, 0x400
	s_movk_i32 s2, 0x400
	ds_read_b64 v[4:5], v0
	s_ashr_i32 s7, s4, 31
	s_lshr_b32 s7, s7, 24
	s_add_i32 s4, s4, s7
	s_ashr_i32 s4, s4, 8
	v_readlane_b32 s33, v252, 0
	s_lshl_b32 s10, s4, 7
	v_mov_b32_e32 v19, v200
	v_readlane_b32 s7, v252, 6
	s_waitcnt lgkmcnt(0)
	v_readfirstlane_b32 s1, v3
	v_readfirstlane_b32 s3, v2
	v_readfirstlane_b32 s5, v5
	v_readfirstlane_b32 s6, v4
	s_cmp_ge_i32 s33, s10
	v_readfirstlane_b32 s11, v19
	s_mul_i32 s16, s7, 0x8400
	s_mul_i32 s14, s7, 0x2c00
	s_cbranch_scc1 .LBB0_1289
	v_lshlrev_b32_e32 v2, 4, v19
	v_add_u32_e32 v0, 0x2000, v2
	v_ashrrev_i32_e32 v3, 31, v0
	v_lshrrev_b32_e32 v3, 22, v3
	v_add_u32_e32 v3, v0, v3
	v_ashrrev_i32_e32 v3, 10, v3
	v_mul_i32_i24_e32 v4, 0x400, v3
	v_sub_u32_e32 v0, v0, v4
	v_lshrrev_b32_e32 v4, 4, v0
	v_bitop3_b32 v4, v4, v0, 32 bitop3:0x6c
	v_ashrrev_i32_e32 v0, 31, v4
	v_lshrrev_b32_e32 v0, 26, v0
	s_add_u32 s37, s3, 0x4bf0000
	v_add_u32_e32 v5, v4, v0
	v_lshlrev_b32_e32 v6, 3, v3
	s_addc_u32 s44, s1, 0
	v_ashrrev_i32_e32 v0, 6, v5
	v_and_b32_e32 v6, -16, v6
	s_add_u32 s46, s6, 0x1b70000
	v_add_u32_e32 v6, v0, v6
	s_addc_u32 s47, s5, 0
	v_and_b32_e32 v0, 3, v0
	s_mov_b32 s5, 0x7fffffe0
	v_lshrrev_b32_e32 v7, 2, v6
	v_lshlrev_b32_e32 v8, 1, v6
	v_and_or_b32 v0, v6, s5, v0
	v_and_b32_e32 v7, 4, v7
	v_and_b32_e32 v8, 24, v8
	v_or3_b32 v0, v0, v7, v8
	v_mul_lo_u32 v7, v0, s0
	v_lshlrev_b32_e32 v0, 5, v3
	v_and_b32_e32 v3, 0xc0, v5
	v_sub_u32_e32 v3, v4, v3
	v_ashrrev_i16_sdwa v3, v201, sext(v3) dst_sel:DWORD dst_unused:UNUSED_PAD src0_sel:DWORD src1_sel:BYTE_0
	v_and_b32_e32 v0, 32, v0
	v_bfe_i32 v14, v3, 0, 16
	v_add_u32_e32 v3, v0, v14
	v_mul_lo_u32 v15, v6, s2
	v_add_lshl_u32 v182, v7, v3, 1
	v_add_lshl_u32 v184, v3, v15, 1
	v_bfe_i32 v3, v19, 27, 1
	v_lshrrev_b32_e32 v3, 22, v3
	v_add_u32_e32 v3, v2, v3
	v_and_b32_e32 v3, 0xfffffc00, v3
	v_sub_u32_e32 v2, v2, v3
	v_lshrrev_b32_e32 v3, 4, v2
	v_ashrrev_i32_e32 v5, 31, v19
	v_bitop3_b32 v2, v3, v2, 32 bitop3:0x6c
	v_lshrrev_b32_e32 v5, 26, v5
	v_ashrrev_i32_e32 v3, 31, v2
	v_add_u32_e32 v5, v19, v5
	v_lshrrev_b32_e32 v3, 26, v3
	v_ashrrev_i32_e32 v5, 6, v5
	v_add_u32_e32 v3, v2, v3
	v_lshlrev_b32_e32 v6, 3, v5
	v_ashrrev_i32_e32 v4, 6, v3
	v_and_b32_e32 v6, -16, v6
	v_add_u32_e32 v6, v4, v6
	v_and_b32_e32 v3, 0xc0, v3
	v_and_b32_e32 v4, 3, v4
	v_lshrrev_b32_e32 v7, 2, v6
	v_lshlrev_b32_e32 v8, 1, v6
	v_sub_u32_e32 v2, v2, v3
	v_and_or_b32 v4, v6, s5, v4
	v_and_b32_e32 v7, 4, v7
	v_and_b32_e32 v8, 24, v8
	v_lshlrev_b32_e32 v5, 5, v5
	v_ashrrev_i16_sdwa v2, v201, sext(v2) dst_sel:DWORD dst_unused:UNUSED_PAD src0_sel:DWORD src1_sel:BYTE_0
	v_or3_b32 v4, v4, v7, v8
	v_and_b32_e32 v16, 32, v5
	v_bfe_i32 v17, v2, 0, 16
	s_lshl_b32 s53, s4, 3
	v_mul_lo_u32 v4, v4, s0
	v_add_u32_e32 v2, v16, v17
	v_mul_lo_u32 v18, v6, s2
	s_abs_i32 s55, s53
	v_add_lshl_u32 v186, v4, v2, 1
	v_add_lshl_u32 v188, v2, v18, 1
	v_cvt_f32_u32_e32 v2, s55
	s_ashr_i32 s52, s33, 31
	s_lshr_b32 s5, s52, 29
	s_add_i32 s5, s33, s5
	v_rcp_iflag_f32_e32 v2, v2
	s_ashr_i32 s6, s5, 3
	s_and_b32 s5, s5, -8
	s_sub_i32 s5, s33, s5
	v_mul_f32_e32 v2, 0x4f7ffffe, v2
	v_cvt_u32_f32_e32 v2, v2
	s_lshl_b32 s51, s4, 4
	s_lshr_b32 s7, s5, 31
	s_or_b32 s7, s51, s7
	s_mul_i32 s5, s7, s5
	s_sub_i32 s7, 0, s55
	v_readfirstlane_b32 s58, v2
	s_add_i32 s5, s5, s6
	s_mul_i32 s7, s7, s58
	s_ashr_i32 s6, s5, 31
	s_bfe_i32 s54, s4, 0x1001c
	s_mul_hi_u32 s7, s58, s7
	s_xor_b32 s4, s6, s54
	s_abs_i32 s6, s5
	s_add_i32 s58, s58, s7
	s_mul_hi_u32 s7, s6, s58
	s_mul_i32 s8, s7, s55
	s_ashr_i32 s27, s11, 6
	s_ashr_i32 s3, s2, 31
	s_ashr_i32 s1, s0, 31
	s_sub_i32 s6, s6, s8
	s_ashr_i32 s50, s11, 8
	s_lshl_b64 s[12:13], s[2:3], 8
	s_lshl_b64 s[18:19], s[0:1], 8
	s_lshl_b64 s[20:21], s[2:3], 9
	s_lshl_b64 s[22:23], s[0:1], 9
	s_lshl_b32 s26, s27, 10
	s_add_i32 s8, s7, 1
	s_sub_i32 s24, s6, s55
	s_cmp_ge_u32 s6, s55
	s_cselect_b32 s7, s8, s7
	s_cselect_b32 s6, s24, s6
	s_add_i32 s8, s7, 1
	s_cmp_ge_u32 s6, s55
	s_cselect_b32 s6, s8, s7
	s_xor_b32 s6, s6, s4
	s_sub_i32 s4, s6, s4
	s_lshl_b32 s6, s4, 3
	s_sub_i32 s7, 0x80, s6
	s_min_i32 s7, s7, 8
	s_abs_i32 s24, s7
	v_cvt_f32_u32_e32 v2, s24
	s_sub_i32 s25, 0, s24
	s_mul_i32 s4, s4, s53
	s_sub_i32 s4, s5, s4
	v_rcp_iflag_f32_e32 v2, v2
	s_abs_i32 s8, s4
	s_xor_b32 s5, s4, s7
	s_ashr_i32 s5, s5, 31
	v_mul_f32_e32 v2, 0x4f7ffffe, v2
	v_cvt_u32_f32_e32 v2, v2
	v_mov_b32_e32 v187, v1
	v_mov_b32_e32 v183, v1
	v_mov_b32_e32 v189, v1
	v_readfirstlane_b32 s28, v2
	s_mul_i32 s25, s25, s28
	s_mul_hi_u32 s25, s28, s25
	s_add_i32 s28, s28, s25
	s_mul_hi_u32 s25, s8, s28
	s_mul_i32 s28, s25, s24
	s_sub_i32 s8, s8, s28
	s_add_i32 s28, s25, 1
	s_sub_i32 s29, s8, s24
	s_cmp_ge_u32 s8, s24
	s_cselect_b32 s25, s28, s25
	s_cselect_b32 s8, s29, s8
	s_add_i32 s28, s25, 1
	s_cmp_ge_u32 s8, s24
	s_cselect_b32 s8, s28, s25
	s_xor_b32 s8, s8, s5
	s_sub_i32 s8, s8, s5
	s_mul_i32 s5, s8, s7
	s_sub_i32 s4, s4, s5
	s_add_i32 s70, s4, s6
	s_ashr_i32 s4, s70, 31
	s_mul_i32 s4, s20, s4
	s_mul_hi_u32 s5, s20, s70
	s_lshr_b64 s[2:3], s[2:3], 23
	s_add_i32 s4, s5, s4
	s_mul_i32 s2, s2, s70
	s_add_i32 s7, s4, s2
	s_ashr_i32 s2, s8, 31
	s_mul_i32 s2, s22, s2
	s_mul_hi_u32 s3, s22, s8
	s_add_i32 s4, s3, s2
	s_lshr_b64 s[2:3], s[0:1], 23
	s_mul_i32 s2, s2, s8
	s_add_i32 s2, s4, s2
	s_mul_i32 s3, s22, s8
	s_add_u32 s4, s46, s3
	s_addc_u32 s5, s47, s2
	s_add_i32 s59, s9, 0x10000
	s_add_i32 s60, s59, s26
	s_add_i32 s61, s60, 0x2000
	s_add_u32 s2, s4, s18
	s_addc_u32 s3, s5, s19
	s_add_i32 s62, s9, 0x14000
	s_add_i32 s63, s62, s26
	s_mul_i32 s6, s20, s70
	s_mov_b32 m0, s60
	s_add_i32 s64, s63, 0x2000
	global_load_lds_dwordx4 v186, s[4:5]
	s_mov_b32 m0, s61
	s_add_u32 s6, s37, s6
	global_load_lds_dwordx4 v182, s[4:5]
	s_mov_b32 m0, s63
	s_addc_u32 s7, s44, s7
	s_add_i32 s65, s9, s26
	global_load_lds_dwordx4 v186, s[2:3]
	s_mov_b32 m0, s64
	s_add_i32 s66, s65, 0x2000
	v_lshl_add_u64 v[6:7], s[2:3], 0, v[186:187]
	v_lshl_add_u64 v[8:9], s[2:3], 0, v[182:183]
	global_load_lds_dwordx4 v182, s[2:3]
	s_mov_b32 m0, s65
	s_add_u32 s2, s6, s12
	global_load_lds_dwordx4 v188, s[6:7]
	s_mov_b32 m0, s66
	s_addc_u32 s3, s7, s13
	s_add_i32 s67, s65, 0x4000
	global_load_lds_dwordx4 v184, s[6:7]
	s_mov_b32 m0, s67
	s_add_i32 s74, s65, 0x6000
	global_load_lds_dwordx4 v188, s[2:3]
	s_mov_b32 m0, s74
	v_mov_b32_e32 v185, v1
	global_load_lds_dwordx4 v184, s[2:3]
	s_cmp_eq_u32 s50, 1
	v_lshl_add_u64 v[2:3], s[4:5], 0, v[186:187]
	v_lshl_add_u64 v[4:5], s[4:5], 0, v[182:183]
	v_lshl_add_u64 v[10:11], s[6:7], 0, v[188:189]
	v_lshl_add_u64 v[12:13], s[6:7], 0, v[184:185]
	s_cselect_b64 s[24:25], -1, 0
	s_cmp_lg_u32 s50, 1
	s_cbranch_scc1 .LBB0_1263
	s_barrier
	s_setprio 1

.LBB0_1274:
	v_add_u32_e32 v0, s59, v218
	ds_read_b128 v[74:77], v0
	ds_read_b128 v[78:81], v0 offset:1024
	ds_read_b128 v[82:85], v0 offset:2048
	ds_read_b128 v[86:89], v0 offset:3072
	v_add_u32_e32 v0, s62, v218
	ds_read_b128 v[98:101], v0
	ds_read_b128 v[102:105], v0 offset:1024
	ds_read_b128 v[106:109], v0 offset:2048
	ds_read_b128 v[110:113], v0 offset:3072
	s_add_i32 s35, s6, 2
	s_add_u32 s68, s4, 0x80
	s_addc_u32 s7, s5, 0
	s_cmp_eq_u32 s85, s6
	s_cselect_b32 s6, s0, s68
	s_cselect_b32 s7, s1, s7
	s_cselect_b32 s69, s31, s34
	s_cselect_b32 s68, s30, s9
	v_lshl_add_u64 v[198:199], s[4:5], 0, v[192:193]
	s_add_i32 m0, s65, 0xc000
	ds_read_b128 v[162:165], v219
	ds_read_b128 v[166:169], v219 offset:1024
	ds_read_b128 v[170:173], v219 offset:2048
	ds_read_b128 v[174:177], v219 offset:3072
	ds_read_b128 v[194:197], v219 offset:4096
	ds_read_b128 v[220:223], v219 offset:5120
	ds_read_b128 v[230:233], v219 offset:6144
	ds_read_b128 v[234:237], v219 offset:7168
	global_load_lds_dwordx4 v[198:199], off
	v_lshl_add_u64 v[198:199], s[4:5], 0, v[190:191]
	s_add_i32 m0, s65, 0xe000
	s_nop 0
	global_load_lds_dwordx4 v[198:199], off
	s_waitcnt vmcnt(8)
	s_waitcnt lgkmcnt(0)
	s_barrier
	s_waitcnt lgkmcnt(0)
	v_mfma_f32_16x16x32_bf16 v[154:157], v[74:77], v[162:165], v[154:157]
	v_mfma_f32_16x16x32_bf16 v[158:161], v[82:85], v[162:165], v[158:161]
	v_mfma_f32_16x16x32_bf16 v[142:145], v[74:77], v[170:173], v[142:145]
	v_mfma_f32_16x16x32_bf16 v[134:137], v[82:85], v[170:173], v[134:137]
	v_mfma_f32_16x16x32_bf16 v[126:129], v[74:77], v[194:197], v[126:129]
	v_mfma_f32_16x16x32_bf16 v[118:121], v[82:85], v[194:197], v[118:121]
	v_mfma_f32_16x16x32_bf16 v[94:97], v[74:77], v[230:233], v[94:97]
	v_mfma_f32_16x16x32_bf16 v[70:73], v[82:85], v[230:233], v[70:73]
	v_mfma_f32_16x16x32_bf16 v[154:157], v[78:81], v[166:169], v[154:157]
	v_mfma_f32_16x16x32_bf16 v[158:161], v[86:89], v[166:169], v[158:161]
	v_mfma_f32_16x16x32_bf16 v[142:145], v[78:81], v[174:177], v[142:145]
	v_mfma_f32_16x16x32_bf16 v[134:137], v[86:89], v[174:177], v[134:137]
	v_mfma_f32_16x16x32_bf16 v[126:129], v[78:81], v[220:223], v[126:129]
	v_mfma_f32_16x16x32_bf16 v[118:121], v[86:89], v[220:223], v[118:121]
	v_mfma_f32_16x16x32_bf16 v[94:97], v[78:81], v[234:237], v[94:97]
	v_mfma_f32_16x16x32_bf16 v[70:73], v[86:89], v[234:237], v[70:73]
	v_mfma_f32_16x16x32_bf16 v[150:153], v[98:101], v[162:165], v[150:153]
	v_mfma_f32_16x16x32_bf16 v[146:149], v[106:109], v[162:165], v[146:149]
	v_mfma_f32_16x16x32_bf16 v[138:141], v[98:101], v[170:173], v[138:141]
	v_mfma_f32_16x16x32_bf16 v[130:133], v[106:109], v[170:173], v[130:133]
	v_mfma_f32_16x16x32_bf16 v[122:125], v[98:101], v[194:197], v[122:125]
	v_mfma_f32_16x16x32_bf16 v[114:117], v[106:109], v[194:197], v[114:117]
	v_mfma_f32_16x16x32_bf16 v[90:93], v[98:101], v[230:233], v[90:93]
	v_mfma_f32_16x16x32_bf16 v[66:69], v[106:109], v[230:233], v[66:69]
	v_mfma_f32_16x16x32_bf16 v[150:153], v[102:105], v[166:169], v[150:153]
	v_mfma_f32_16x16x32_bf16 v[146:149], v[110:113], v[166:169], v[146:149]
	v_mfma_f32_16x16x32_bf16 v[138:141], v[102:105], v[174:177], v[138:141]
	v_mfma_f32_16x16x32_bf16 v[130:133], v[110:113], v[174:177], v[130:133]
	v_mfma_f32_16x16x32_bf16 v[122:125], v[102:105], v[220:223], v[122:125]
	v_mfma_f32_16x16x32_bf16 v[114:117], v[110:113], v[220:223], v[114:117]
	v_mfma_f32_16x16x32_bf16 v[90:93], v[102:105], v[234:237], v[90:93]
	v_mfma_f32_16x16x32_bf16 v[66:69], v[110:113], v[234:237], v[66:69]
	s_barrier
	s_mov_b32 m0, s60
	v_lshl_add_u64 v[198:199], s[68:69], 0, v[186:187]
	v_lshl_add_u64 v[224:225], s[68:69], 0, v[182:183]
	s_add_u32 s68, s68, s18
	ds_read_b128 v[162:165], v219 offset:16384
	ds_read_b128 v[166:169], v219 offset:17408
	ds_read_b128 v[170:173], v219 offset:18432
	ds_read_b128 v[174:177], v219 offset:19456
	ds_read_b128 v[194:197], v219 offset:20480
	ds_read_b128 v[220:223], v219 offset:21504
	ds_read_b128 v[230:233], v219 offset:22528
	ds_read_b128 v[234:237], v219 offset:23552
	global_load_lds_dwordx4 v[198:199], off
	s_mov_b32 m0, s61
	s_addc_u32 s69, s69, s19
	global_load_lds_dwordx4 v[224:225], off
	v_lshl_add_u64 v[238:239], s[68:69], 0, v[186:187]
	s_mov_b32 m0, s63
	v_lshl_add_u64 v[240:241], s[68:69], 0, v[182:183]
	global_load_lds_dwordx4 v[238:239], off
	s_mov_b32 m0, s64
	v_lshl_add_u64 v[242:243], s[6:7], 0, v[188:189]
	global_load_lds_dwordx4 v[240:241], off
	s_mov_b32 m0, s65
	v_lshl_add_u64 v[244:245], s[6:7], 0, v[184:185]
	global_load_lds_dwordx4 v[242:243], off
	s_mov_b32 m0, s66
	s_nop 0
	global_load_lds_dwordx4 v[244:245], off
	s_waitcnt vmcnt(8)
	s_waitcnt lgkmcnt(0)
	s_barrier
	s_waitcnt lgkmcnt(0)
	v_mfma_f32_16x16x32_bf16 v[62:65], v[74:77], v[162:165], v[62:65]
	v_mfma_f32_16x16x32_bf16 v[54:57], v[82:85], v[162:165], v[54:57]
	v_mfma_f32_16x16x32_bf16 v[46:49], v[74:77], v[170:173], v[46:49]
	v_mfma_f32_16x16x32_bf16 v[38:41], v[82:85], v[170:173], v[38:41]
	v_mfma_f32_16x16x32_bf16 v[30:33], v[74:77], v[194:197], v[30:33]
	v_mfma_f32_16x16x32_bf16 v[22:25], v[82:85], v[194:197], v[22:25]
	v_mfma_f32_16x16x32_bf16 v[6:9], v[74:77], v[230:233], v[6:9]
	v_mfma_f32_16x16x32_bf16 v[2:5], v[82:85], v[230:233], v[2:5]
	v_mfma_f32_16x16x32_bf16 v[62:65], v[78:81], v[166:169], v[62:65]
	v_mfma_f32_16x16x32_bf16 v[54:57], v[86:89], v[166:169], v[54:57]
	v_mfma_f32_16x16x32_bf16 v[46:49], v[78:81], v[174:177], v[46:49]
	v_mfma_f32_16x16x32_bf16 v[38:41], v[86:89], v[174:177], v[38:41]
	v_mfma_f32_16x16x32_bf16 v[30:33], v[78:81], v[220:223], v[30:33]
	v_mfma_f32_16x16x32_bf16 v[22:25], v[86:89], v[220:223], v[22:25]
	v_mfma_f32_16x16x32_bf16 v[6:9], v[78:81], v[234:237], v[6:9]
	v_mfma_f32_16x16x32_bf16 v[2:5], v[86:89], v[234:237], v[2:5]
	v_mfma_f32_16x16x32_bf16 v[58:61], v[98:101], v[162:165], v[58:61]
	v_mfma_f32_16x16x32_bf16 v[50:53], v[106:109], v[162:165], v[50:53]
	v_mfma_f32_16x16x32_bf16 v[42:45], v[98:101], v[170:173], v[42:45]
	v_mfma_f32_16x16x32_bf16 v[34:37], v[106:109], v[170:173], v[34:37]
	v_mfma_f32_16x16x32_bf16 v[26:29], v[98:101], v[194:197], v[26:29]
	v_mfma_f32_16x16x32_bf16 v[18:21], v[106:109], v[194:197], v[18:21]
	v_mfma_f32_16x16x32_bf16 v[14:17], v[98:101], v[230:233], v[14:17]
	v_mfma_f32_16x16x32_bf16 v[10:13], v[106:109], v[230:233], v[10:13]
	v_mfma_f32_16x16x32_bf16 v[58:61], v[102:105], v[166:169], v[58:61]
	v_mfma_f32_16x16x32_bf16 v[50:53], v[110:113], v[166:169], v[50:53]
	v_mfma_f32_16x16x32_bf16 v[42:45], v[102:105], v[174:177], v[42:45]
	v_mfma_f32_16x16x32_bf16 v[34:37], v[110:113], v[174:177], v[34:37]
	v_mfma_f32_16x16x32_bf16 v[26:29], v[102:105], v[220:223], v[26:29]
	v_mfma_f32_16x16x32_bf16 v[18:21], v[110:113], v[220:223], v[18:21]
	v_mfma_f32_16x16x32_bf16 v[14:17], v[102:105], v[234:237], v[14:17]
	v_mfma_f32_16x16x32_bf16 v[10:13], v[110:113], v[234:237], v[10:13]
	s_barrier
	v_add_u32_e32 v0, s77, v218
	ds_read_b128 v[74:77], v0
	ds_read_b128 v[78:81], v0 offset:1024
	ds_read_b128 v[82:85], v0 offset:2048
	ds_read_b128 v[86:89], v0 offset:3072
	v_add_u32_e32 v0, s82, v218
	ds_read_b128 v[98:101], v0
	ds_read_b128 v[102:105], v0 offset:1024
	ds_read_b128 v[106:109], v0 offset:2048
	ds_read_b128 v[110:113], v0 offset:3072
	s_add_u32 s6, s6, s12
	s_addc_u32 s7, s7, s13
	s_mov_b32 m0, s67
	v_lshl_add_u64 v[246:247], s[6:7], 0, v[188:189]
	ds_read_b128 v[162:165], v219 offset:32768
	ds_read_b128 v[166:169], v219 offset:33792
	ds_read_b128 v[170:173], v219 offset:34816
	ds_read_b128 v[174:177], v219 offset:35840
	ds_read_b128 v[194:197], v219 offset:36864
	ds_read_b128 v[220:223], v219 offset:37888
	ds_read_b128 v[230:233], v219 offset:38912
	ds_read_b128 v[234:237], v219 offset:39936
	global_load_lds_dwordx4 v[246:247], off
	v_lshl_add_u64 v[246:247], s[6:7], 0, v[184:185]
	s_mov_b32 m0, s74
	s_nop 0
	global_load_lds_dwordx4 v[246:247], off
	s_waitcnt vmcnt(8)
	s_waitcnt lgkmcnt(0)
	s_barrier
	s_waitcnt lgkmcnt(0)
	v_mfma_f32_16x16x32_bf16 v[154:157], v[74:77], v[162:165], v[154:157]
	v_mfma_f32_16x16x32_bf16 v[158:161], v[82:85], v[162:165], v[158:161]
	v_mfma_f32_16x16x32_bf16 v[142:145], v[74:77], v[170:173], v[142:145]
	v_mfma_f32_16x16x32_bf16 v[134:137], v[82:85], v[170:173], v[134:137]
	v_mfma_f32_16x16x32_bf16 v[126:129], v[74:77], v[194:197], v[126:129]
	v_mfma_f32_16x16x32_bf16 v[118:121], v[82:85], v[194:197], v[118:121]
	v_mfma_f32_16x16x32_bf16 v[94:97], v[74:77], v[230:233], v[94:97]
	v_mfma_f32_16x16x32_bf16 v[70:73], v[82:85], v[230:233], v[70:73]
	v_mfma_f32_16x16x32_bf16 v[154:157], v[78:81], v[166:169], v[154:157]
	v_mfma_f32_16x16x32_bf16 v[158:161], v[86:89], v[166:169], v[158:161]
	v_mfma_f32_16x16x32_bf16 v[142:145], v[78:81], v[174:177], v[142:145]
	v_mfma_f32_16x16x32_bf16 v[134:137], v[86:89], v[174:177], v[134:137]
	v_mfma_f32_16x16x32_bf16 v[126:129], v[78:81], v[220:223], v[126:129]
	v_mfma_f32_16x16x32_bf16 v[118:121], v[86:89], v[220:223], v[118:121]
	v_mfma_f32_16x16x32_bf16 v[94:97], v[78:81], v[234:237], v[94:97]
	v_mfma_f32_16x16x32_bf16 v[70:73], v[86:89], v[234:237], v[70:73]
	v_mfma_f32_16x16x32_bf16 v[150:153], v[98:101], v[162:165], v[150:153]
	v_mfma_f32_16x16x32_bf16 v[146:149], v[106:109], v[162:165], v[146:149]
	v_mfma_f32_16x16x32_bf16 v[138:141], v[98:101], v[170:173], v[138:141]
	v_mfma_f32_16x16x32_bf16 v[130:133], v[106:109], v[170:173], v[130:133]
	v_mfma_f32_16x16x32_bf16 v[122:125], v[98:101], v[194:197], v[122:125]
	v_mfma_f32_16x16x32_bf16 v[114:117], v[106:109], v[194:197], v[114:117]
	v_mfma_f32_16x16x32_bf16 v[90:93], v[98:101], v[230:233], v[90:93]
	v_mfma_f32_16x16x32_bf16 v[66:69], v[106:109], v[230:233], v[66:69]
	v_mfma_f32_16x16x32_bf16 v[150:153], v[102:105], v[166:169], v[150:153]
	v_mfma_f32_16x16x32_bf16 v[146:149], v[110:113], v[166:169], v[146:149]
	v_mfma_f32_16x16x32_bf16 v[138:141], v[102:105], v[174:177], v[138:141]
	v_mfma_f32_16x16x32_bf16 v[130:133], v[110:113], v[174:177], v[130:133]
	v_mfma_f32_16x16x32_bf16 v[122:125], v[102:105], v[220:223], v[122:125]
	v_mfma_f32_16x16x32_bf16 v[114:117], v[110:113], v[220:223], v[114:117]
	v_mfma_f32_16x16x32_bf16 v[90:93], v[102:105], v[234:237], v[90:93]
	v_mfma_f32_16x16x32_bf16 v[66:69], v[110:113], v[234:237], v[66:69]
	s_barrier
	s_mov_b32 m0, s78
	v_lshl_add_u64 v[198:199], v[198:199], 0, s[48:49]
	ds_read_b128 v[162:165], v219 offset:49152
	ds_read_b128 v[166:169], v219 offset:50176
	ds_read_b128 v[170:173], v219 offset:51200
	ds_read_b128 v[174:177], v219 offset:52224
	ds_read_b128 v[194:197], v219 offset:53248
	ds_read_b128 v[220:223], v219 offset:54272
	ds_read_b128 v[230:233], v219 offset:55296
	ds_read_b128 v[234:237], v219 offset:56320
	global_load_lds_dwordx4 v[198:199], off
	v_lshl_add_u64 v[198:199], v[224:225], 0, s[48:49]
	s_mov_b32 m0, s79
	s_nop 0
	global_load_lds_dwordx4 v[198:199], off
	v_lshl_add_u64 v[198:199], v[238:239], 0, s[48:49]
	s_mov_b32 m0, s83
	s_nop 0
	global_load_lds_dwordx4 v[198:199], off
	v_lshl_add_u64 v[198:199], v[240:241], 0, s[48:49]
	s_mov_b32 m0, s84
	s_nop 0
	global_load_lds_dwordx4 v[198:199], off
	v_lshl_add_u64 v[198:199], v[242:243], 0, s[48:49]
	s_mov_b32 m0, s80
	s_nop 0
	global_load_lds_dwordx4 v[198:199], off
	v_lshl_add_u64 v[198:199], v[244:245], 0, s[48:49]
	s_mov_b32 m0, s81
	s_nop 0
	global_load_lds_dwordx4 v[198:199], off
	s_waitcnt vmcnt(8)
	s_waitcnt lgkmcnt(0)
	s_barrier
	s_waitcnt lgkmcnt(0)
	v_mfma_f32_16x16x32_bf16 v[62:65], v[74:77], v[162:165], v[62:65]
	v_mfma_f32_16x16x32_bf16 v[54:57], v[82:85], v[162:165], v[54:57]
	v_mfma_f32_16x16x32_bf16 v[46:49], v[74:77], v[170:173], v[46:49]
	v_mfma_f32_16x16x32_bf16 v[38:41], v[82:85], v[170:173], v[38:41]
	v_mfma_f32_16x16x32_bf16 v[30:33], v[74:77], v[194:197], v[30:33]
	v_mfma_f32_16x16x32_bf16 v[22:25], v[82:85], v[194:197], v[22:25]
	v_mfma_f32_16x16x32_bf16 v[6:9], v[74:77], v[230:233], v[6:9]
	v_mfma_f32_16x16x32_bf16 v[2:5], v[82:85], v[230:233], v[2:5]
	v_mfma_f32_16x16x32_bf16 v[62:65], v[78:81], v[166:169], v[62:65]
	v_mfma_f32_16x16x32_bf16 v[54:57], v[86:89], v[166:169], v[54:57]
	v_mfma_f32_16x16x32_bf16 v[46:49], v[78:81], v[174:177], v[46:49]
	v_mfma_f32_16x16x32_bf16 v[38:41], v[86:89], v[174:177], v[38:41]
	v_mfma_f32_16x16x32_bf16 v[30:33], v[78:81], v[220:223], v[30:33]
	v_mfma_f32_16x16x32_bf16 v[22:25], v[86:89], v[220:223], v[22:25]
	v_mfma_f32_16x16x32_bf16 v[6:9], v[78:81], v[234:237], v[6:9]
	v_mfma_f32_16x16x32_bf16 v[2:5], v[86:89], v[234:237], v[2:5]
	v_mfma_f32_16x16x32_bf16 v[58:61], v[98:101], v[162:165], v[58:61]
	v_mfma_f32_16x16x32_bf16 v[50:53], v[106:109], v[162:165], v[50:53]
	v_mfma_f32_16x16x32_bf16 v[42:45], v[98:101], v[170:173], v[42:45]
	v_mfma_f32_16x16x32_bf16 v[34:37], v[106:109], v[170:173], v[34:37]
	v_mfma_f32_16x16x32_bf16 v[26:29], v[98:101], v[194:197], v[26:29]
	v_mfma_f32_16x16x32_bf16 v[18:21], v[106:109], v[194:197], v[18:21]
	v_mfma_f32_16x16x32_bf16 v[14:17], v[98:101], v[230:233], v[14:17]
	v_mfma_f32_16x16x32_bf16 v[10:13], v[106:109], v[230:233], v[10:13]
	v_mfma_f32_16x16x32_bf16 v[58:61], v[102:105], v[166:169], v[58:61]
	v_mfma_f32_16x16x32_bf16 v[50:53], v[110:113], v[166:169], v[50:53]
	v_mfma_f32_16x16x32_bf16 v[42:45], v[102:105], v[174:177], v[42:45]
	v_mfma_f32_16x16x32_bf16 v[34:37], v[110:113], v[174:177], v[34:37]
	v_mfma_f32_16x16x32_bf16 v[26:29], v[102:105], v[220:223], v[26:29]
	v_mfma_f32_16x16x32_bf16 v[18:21], v[110:113], v[220:223], v[18:21]
	v_mfma_f32_16x16x32_bf16 v[14:17], v[102:105], v[234:237], v[14:17]
	v_mfma_f32_16x16x32_bf16 v[10:13], v[110:113], v[234:237], v[10:13]
	s_barrier
	s_add_u32 s9, s9, 0x100
	s_addc_u32 s34, s34, 0
	s_add_u32 s4, s4, 0x100
	s_addc_u32 s5, s5, 0
	s_cmp_ge_i32 s35, s76
	s_mov_b32 s6, s35
	s_cbranch_scc0 .LBB0_1274

.LBB0_1289:
	s_mov_b32 s0, s45
	s_add_i32 s0, s0, 0x200e8
	v_mov_b32_e32 v0, s0
	ds_read_b64 v[2:3], v0
	s_mov_b32 s44, 0
	s_setprio 0
	s_getreg_b32 s0, hwreg(HW_REG_XCC_ID, 0, 4)
	s_waitcnt vmcnt(0)
	s_waitcnt lgkmcnt(0)
	v_readfirstlane_b32 s71, v3
	v_readfirstlane_b32 s70, v2
	s_barrier
	s_mov_b64 s[68:69], exec
	v_readlane_b32 s2, v252, 1
	v_readlane_b32 s3, v252, 2
	v_readlane_b32 s88, v252, 7
	s_and_b64 s[2:3], s[68:69], s[2:3]
	v_readlane_b32 s89, v252, 8
	s_mov_b64 exec, s[2:3]
	s_cbranch_execz .LBB0_1333
	s_add_i32 s37, s44, 0x20200
	v_mov_b32_e32 v0, s37
	s_waitcnt vmcnt(0) expcnt(0) lgkmcnt(0)
	ds_read_b32 v2, v0
	s_add_i32 s44, s44, 0x20204
	v_mov_b32_e32 v0, s44
	ds_read_b32 v0, v0
	s_and_b32 s33, s0, 15
	s_waitcnt lgkmcnt(1)
	v_cmp_ne_u32_e32 vcc, 0, v2
	s_cbranch_vccnz .LBB0_1304
	s_add_u32 s0, s70, 0x1000
	s_addc_u32 s1, s71, 0
	s_add_u32 s2, s70, 0x1100
	s_addc_u32 s3, s71, 0
	s_add_u32 s4, s70, 0x1200
	s_addc_u32 s5, s71, 0
	s_add_u32 s6, s70, 0x1300
	s_addc_u32 s7, s71, 0
	s_mov_b32 s30, 1
	s_mov_b64 s[8:9], 0
	s_branch .LBB0_1294

.LBB0_1346:
	s_or_b64 exec, exec, s[0:1]
	s_mov_b32 s0, s45
	s_add_i32 s0, s0, 0x200e8
	v_mov_b32_e32 v0, s0
	ds_read_b64 v[2:3], v0
	s_mov_b32 s33, 0
	s_setprio 0
	s_getreg_b32 s0, hwreg(HW_REG_XCC_ID, 0, 4)
	s_waitcnt vmcnt(0)
	s_waitcnt lgkmcnt(0)
	v_readfirstlane_b32 s71, v3
	v_readfirstlane_b32 s70, v2
	s_barrier
	s_mov_b64 s[68:69], exec
	v_readlane_b32 s2, v252, 1
	v_readlane_b32 s3, v252, 2
	s_and_b64 s[2:3], s[68:69], s[2:3]
	s_mov_b64 exec, s[2:3]
	s_cbranch_execz .LBB0_1390
	s_add_i32 s16, s33, 0x20200
	v_mov_b32_e32 v0, s16
	s_waitcnt vmcnt(0) expcnt(0) lgkmcnt(0)
	ds_read_b32 v2, v0
	s_add_i32 s33, s33, 0x20204
	v_mov_b32_e32 v0, s33
	ds_read_b32 v0, v0
	s_and_b32 s14, s0, 15
	s_waitcnt lgkmcnt(1)
	v_cmp_ne_u32_e32 vcc, 0, v2
	s_cbranch_vccnz .LBB0_1361
	s_add_u32 s0, s70, 0x1000
	s_addc_u32 s1, s71, 0
	s_add_u32 s2, s70, 0x1100
	s_addc_u32 s3, s71, 0
	s_add_u32 s4, s70, 0x1200
	s_addc_u32 s5, s71, 0
	s_add_u32 s6, s70, 0x1300
	s_addc_u32 s7, s71, 0
	s_mov_b32 s30, 1
	s_mov_b64 s[8:9], 0
	s_branch .LBB0_1351

.LBB0_1390:
	s_or_b64 exec, exec, s[68:69]
	s_mov_b32 s33, s45
	s_mov_b32 s16, 0
	s_mov_b32 s0, 0
	s_waitcnt lgkmcnt(0)
	s_barrier
	s_add_i32 s0, s0, 0x200e8
	v_mov_b32_e32 v0, s0
	s_mov_b32 s0, 0
	ds_read_b64 v[2:3], v0
	s_add_i32 s0, s0, 0x200e8
	v_mov_b32_e32 v0, s0
	s_movk_i32 s0, 0xb00
	s_movk_i32 s2, 0xb00
	s_movk_i32 s5, 0x400
	ds_read_b64 v[4:5], v0
	s_ashr_i32 s7, s5, 31
	s_lshr_b32 s7, s7, 24
	s_add_i32 s5, s5, s7
	s_ashr_i32 s5, s5, 8
	s_or_b32 s14, s15, 1
	v_readlane_b32 s50, v252, 0
	s_lshl_b32 s8, s5, 6
	v_mov_b32_e32 v172, v200
	s_waitcnt lgkmcnt(0)
	v_readfirstlane_b32 s1, v3
	v_readfirstlane_b32 s3, v2
	v_readfirstlane_b32 s4, v5
	v_readfirstlane_b32 s6, v4
	s_cmp_ge_i32 s50, s8
	v_readfirstlane_b32 s37, v172
	s_cbranch_scc1 .LBB0_1512
	v_lshlrev_b32_e32 v2, 4, v172
	v_add_u32_e32 v3, 0x2000, v2
	v_ashrrev_i32_e32 v0, 31, v3
	v_lshrrev_b32_e32 v0, 22, v0
	v_add_u32_e32 v0, v3, v0
	v_ashrrev_i32_e32 v4, 10, v0
	v_mul_i32_i24_e32 v5, 0x400, v4
	v_sub_u32_e32 v3, v3, v5
	v_lshrrev_b32_e32 v5, 4, v3
	v_bitop3_b32 v3, v5, v3, 32 bitop3:0x6c
	v_ashrrev_i32_e32 v5, 31, v3
	v_lshrrev_b32_e32 v5, 26, v5
	v_add_u32_e32 v5, v3, v5
	v_ashrrev_i32_e32 v6, 6, v5
	v_and_b32_e32 v5, 0xc0, v5
	v_lshlrev_b32_e32 v0, 5, v4
	v_sub_u32_e32 v3, v3, v5
	v_lshlrev_b32_e32 v4, 3, v4
	v_ashrrev_i16_sdwa v3, v201, sext(v3) dst_sel:DWORD dst_unused:UNUSED_PAD src0_sel:DWORD src1_sel:BYTE_0
	v_and_b32_e32 v4, -16, v4
	v_and_b32_e32 v0, 32, v0
	v_bfe_i32 v14, v3, 0, 16
	v_add_u32_e32 v4, v6, v4
	v_add_u32_e32 v3, v0, v14
	v_mul_lo_u32 v5, v4, s0
	v_mul_lo_u32 v15, v4, s2
	v_add_lshl_u32 v74, v3, v5, 1
	v_add_lshl_u32 v76, v3, v15, 1
	v_ashrrev_i32_e32 v3, 31, v172
	v_lshrrev_b32_e32 v3, 26, v3
	v_add_u32_e32 v3, v172, v3
	v_ashrrev_i32_e32 v3, 6, v3
	v_lshlrev_b32_e32 v4, 5, v3
	v_and_b32_e32 v16, 32, v4
	v_bfe_i32 v4, v172, 27, 1
	v_lshrrev_b32_e32 v4, 22, v4
	v_add_u32_e32 v4, v2, v4
	v_and_b32_e32 v4, 0xfffffc00, v4
	v_sub_u32_e32 v2, v2, v4
	s_add_u32 s51, s3, 0x8bf0000
	v_lshrrev_b32_e32 v4, 4, v2
	s_addc_u32 s52, s1, 0
	v_bitop3_b32 v2, v4, v2, 32 bitop3:0x6c
	s_add_u32 s53, s6, 0x2670000
	v_ashrrev_i32_e32 v4, 31, v2
	s_addc_u32 s54, s4, 0
	v_lshrrev_b32_e32 v4, 26, v4
	s_ashr_i32 s58, s50, 31
	v_add_u32_e32 v4, v2, v4
	s_lshr_b32 s6, s58, 29
	v_ashrrev_i32_e32 v5, 6, v4
	v_and_b32_e32 v4, 0xc0, v4
	s_add_i32 s6, s50, s6
	s_ashr_i32 s7, s37, 6
	s_ashr_i32 s3, s2, 31
	s_ashr_i32 s1, s0, 31
	v_sub_u32_e32 v2, v2, v4
	v_lshlrev_b32_e32 v3, 3, v3
	s_lshl_b32 s55, s5, 3
	s_ashr_i32 s9, s6, 3
	s_and_b32 s6, s6, -8
	s_ashr_i32 s44, s37, 8
	s_lshl_b64 s[10:11], s[2:3], 8
	s_lshl_b64 s[12:13], s[0:1], 8
	s_lshl_b64 s[18:19], s[2:3], 9
	s_lshl_b64 s[20:21], s[0:1], 9
	s_lshl_b32 s4, s7, 10
	v_ashrrev_i16_sdwa v2, v201, sext(v2) dst_sel:DWORD dst_unused:UNUSED_PAD src0_sel:DWORD src1_sel:BYTE_0
	v_and_b32_e32 v3, -16, v3
	s_sub_i32 s6, s50, s6
	s_or_b32 s59, s55, 1
	v_bfe_i32 v17, v2, 0, 16
	v_add_u32_e32 v3, v5, v3
	s_cmp_lt_i32 s6, 0
	v_add_u32_e32 v2, v16, v17
	v_mul_lo_u32 v4, v3, s0
	v_mul_lo_u32 v18, v3, s2
	s_cselect_b32 s22, s59, s55
	s_abs_i32 s61, s55
	v_add_lshl_u32 v134, v2, v4, 1
	v_add_lshl_u32 v136, v2, v18, 1
	v_cvt_f32_u32_e32 v2, s61
	s_mul_i32 s6, s22, s6
	s_sub_i32 s22, 0, s61
	s_add_i32 s6, s6, s9
	v_rcp_iflag_f32_e32 v2, v2
	s_ashr_i32 s9, s6, 31
	s_bfe_i32 s60, s5, 0x1001c
	s_xor_b32 s5, s9, s60
	v_mul_f32_e32 v2, 0x4f7ffffe, v2
	v_cvt_u32_f32_e32 v2, v2
	s_abs_i32 s9, s6
	v_mov_b32_e32 v135, v1
	v_mov_b32_e32 v75, v1
	v_readfirstlane_b32 s62, v2
	s_mul_i32 s22, s22, s62
	s_mul_hi_u32 s22, s62, s22
	s_add_i32 s62, s62, s22
	s_mul_hi_u32 s22, s9, s62
	s_mul_i32 s23, s22, s61
	s_sub_i32 s9, s9, s23
	s_add_i32 s23, s22, 1
	s_sub_i32 s24, s9, s61
	s_cmp_ge_u32 s9, s61
	s_cselect_b32 s22, s23, s22
	s_cselect_b32 s9, s24, s9
	s_add_i32 s23, s22, 1
	s_cmp_ge_u32 s9, s61
	s_cselect_b32 s9, s23, s22
	s_xor_b32 s9, s9, s5
	s_sub_i32 s5, s9, s5
	s_lshl_b32 s9, s5, 3
	s_sub_i32 s22, 64, s9
	s_min_i32 s22, s22, 8
	s_abs_i32 s24, s22
	v_cvt_f32_u32_e32 v2, s24
	s_sub_i32 s25, 0, s24
	s_mul_i32 s5, s5, s55
	s_sub_i32 s5, s6, s5
	v_rcp_iflag_f32_e32 v2, v2
	s_abs_i32 s23, s5
	s_xor_b32 s6, s5, s22
	s_ashr_i32 s6, s6, 31
	v_mul_f32_e32 v2, 0x4f7ffffe, v2
	v_cvt_u32_f32_e32 v2, v2
	v_mov_b32_e32 v137, v1
	v_mov_b32_e32 v77, v1
	v_readfirstlane_b32 s26, v2
	s_mul_i32 s25, s25, s26
	s_mul_hi_u32 s25, s26, s25
	s_add_i32 s26, s26, s25
	s_mul_hi_u32 s25, s23, s26
	s_mul_i32 s26, s25, s24
	s_sub_i32 s23, s23, s26
	s_add_i32 s26, s25, 1
	s_sub_i32 s27, s23, s24
	s_cmp_ge_u32 s23, s24
	s_cselect_b32 s25, s26, s25
	s_cselect_b32 s23, s27, s23
	s_add_i32 s26, s25, 1
	s_cmp_ge_u32 s23, s24
	s_cselect_b32 s23, s26, s25
	s_xor_b32 s23, s23, s6
	s_sub_i32 s6, s23, s6
	s_mul_i32 s22, s6, s22
	s_sub_i32 s5, s5, s22
	s_add_i32 s46, s5, s9
	s_ashr_i32 s5, s46, 31
	s_mul_i32 s5, s18, s5
	s_mul_hi_u32 s9, s18, s46
	s_lshr_b64 s[2:3], s[2:3], 23
	s_add_i32 s5, s9, s5
	s_mul_i32 s2, s2, s46
	s_add_i32 s5, s5, s2
	s_ashr_i32 s2, s6, 31
	s_mul_i32 s2, s20, s2
	s_mul_hi_u32 s3, s20, s6
	s_add_i32 s22, s3, s2
	s_lshr_b64 s[2:3], s[0:1], 23
	s_mul_i32 s2, s2, s6
	s_add_i32 s2, s22, s2
	s_mul_i32 s3, s20, s6
	s_add_u32 s22, s53, s3
	s_addc_u32 s23, s54, s2
	s_add_i32 s63, s16, 0x10000
	s_add_i32 s64, s63, s4
	s_add_i32 s65, s64, 0x2000
	s_add_u32 s2, s22, s12
	s_addc_u32 s3, s23, s13
	s_add_i32 s66, s16, 0x14000
	s_add_i32 s67, s66, s4
	s_mul_i32 s9, s18, s46
	s_mov_b32 m0, s64
	s_add_i32 s68, s67, 0x2000
	global_load_lds_dwordx4 v134, s[22:23]
	s_mov_b32 m0, s65
	s_add_u32 s24, s51, s9
	global_load_lds_dwordx4 v74, s[22:23]
	s_mov_b32 m0, s67
	s_addc_u32 s25, s52, s5
	s_add_i32 s69, s16, s4
	global_load_lds_dwordx4 v134, s[2:3]
	s_mov_b32 m0, s68
	s_add_i32 s70, s69, 0x2000
	v_lshl_add_u64 v[6:7], s[2:3], 0, v[134:135]
	v_lshl_add_u64 v[8:9], s[2:3], 0, v[74:75]
	global_load_lds_dwordx4 v74, s[2:3]
	s_mov_b32 m0, s69
	s_add_u32 s2, s24, s10
	global_load_lds_dwordx4 v136, s[24:25]
	s_mov_b32 m0, s70
	s_addc_u32 s3, s25, s11
	s_add_i32 s71, s69, 0x4000
	global_load_lds_dwordx4 v76, s[24:25]
	s_mov_b32 m0, s71
	s_add_i32 s72, s69, 0x6000
	global_load_lds_dwordx4 v136, s[2:3]
	s_mov_b32 m0, s72
	v_lshl_add_u64 v[2:3], s[22:23], 0, v[134:135]
	global_load_lds_dwordx4 v76, s[2:3]
	v_lshl_add_u64 v[4:5], s[22:23], 0, v[74:75]
	v_lshl_add_u64 v[10:11], s[24:25], 0, v[136:137]
	v_lshl_add_u64 v[12:13], s[24:25], 0, v[76:77]
	s_cmp_lg_u32 s44, 1
	s_cbranch_scc1 .LBB0_1393
	s_barrier
	s_setprio 1

.LBB0_1401:
	v_add_u32_e32 v0, s63, v142
	ds_read_b128 v[144:147], v0
	ds_read_b128 v[148:151], v0 offset:1024
	ds_read_b128 v[152:155], v0 offset:2048
	ds_read_b128 v[156:159], v0 offset:3072
	v_add_u32_e32 v0, s66, v142
	ds_read_b128 v[160:163], v0
	ds_read_b128 v[164:167], v0 offset:1024
	ds_read_b128 v[168:171], v0 offset:2048
	ds_read_b128 v[182:185], v0 offset:3072
	s_add_i32 s89, s34, 2
	s_add_u32 s90, s30, 0x80
	s_addc_u32 s35, s31, 0
	s_cmp_eq_u32 s82, s34
	s_cselect_b32 s34, s0, s90
	s_cselect_b32 s35, s1, s35
	s_cselect_b32 s91, s29, s88
	s_cselect_b32 s90, s28, s87
	v_lshl_add_u64 v[176:177], s[30:31], 0, v[140:141]
	s_add_i32 m0, s69, 0xc000
	ds_read_b128 v[186:189], v143
	ds_read_b128 v[190:193], v143 offset:1024
	ds_read_b128 v[194:197], v143 offset:2048
	ds_read_b128 v[218:221], v143 offset:3072
	ds_read_b128 v[222:225], v143 offset:4096
	ds_read_b128 v[230:233], v143 offset:5120
	ds_read_b128 v[234:237], v143 offset:6144
	ds_read_b128 v[238:241], v143 offset:7168
	global_load_lds_dwordx4 v[176:177], off
	v_lshl_add_u64 v[176:177], s[30:31], 0, v[138:139]
	s_add_i32 m0, s69, 0xe000
	s_nop 0
	global_load_lds_dwordx4 v[176:177], off
	s_waitcnt vmcnt(8)
	s_waitcnt lgkmcnt(0)
	s_barrier
	s_waitcnt lgkmcnt(0)
	v_mfma_f32_16x16x32_bf16 v[2:5], v[144:147], v[186:189], v[2:5]
	v_mfma_f32_16x16x32_bf16 v[42:45], v[152:155], v[186:189], v[42:45]
	v_mfma_f32_16x16x32_bf16 v[86:89], v[144:147], v[194:197], v[86:89]
	v_mfma_f32_16x16x32_bf16 v[54:57], v[152:155], v[194:197], v[54:57]
	v_mfma_f32_16x16x32_bf16 v[94:97], v[144:147], v[222:225], v[94:97]
	v_mfma_f32_16x16x32_bf16 v[62:65], v[152:155], v[222:225], v[62:65]
	v_mfma_f32_16x16x32_bf16 v[98:101], v[144:147], v[234:237], v[98:101]
	v_mfma_f32_16x16x32_bf16 v[66:69], v[152:155], v[234:237], v[66:69]
	v_mfma_f32_16x16x32_bf16 v[2:5], v[148:151], v[190:193], v[2:5]
	v_mfma_f32_16x16x32_bf16 v[42:45], v[156:159], v[190:193], v[42:45]
	v_mfma_f32_16x16x32_bf16 v[86:89], v[148:151], v[218:221], v[86:89]
	v_mfma_f32_16x16x32_bf16 v[54:57], v[156:159], v[218:221], v[54:57]
	v_mfma_f32_16x16x32_bf16 v[94:97], v[148:151], v[230:233], v[94:97]
	v_mfma_f32_16x16x32_bf16 v[62:65], v[156:159], v[230:233], v[62:65]
	v_mfma_f32_16x16x32_bf16 v[98:101], v[148:151], v[238:241], v[98:101]
	v_mfma_f32_16x16x32_bf16 v[66:69], v[156:159], v[238:241], v[66:69]
	v_mfma_f32_16x16x32_bf16 v[18:21], v[160:163], v[186:189], v[18:21]
	v_mfma_f32_16x16x32_bf16 v[130:133], v[168:171], v[186:189], v[130:133]
	v_mfma_f32_16x16x32_bf16 v[26:29], v[160:163], v[194:197], v[26:29]
	v_mfma_f32_16x16x32_bf16 v[6:9], v[168:171], v[194:197], v[6:9]
	v_mfma_f32_16x16x32_bf16 v[34:37], v[160:163], v[222:225], v[34:37]
	v_mfma_f32_16x16x32_bf16 v[10:13], v[168:171], v[222:225], v[10:13]
	v_mfma_f32_16x16x32_bf16 v[38:41], v[160:163], v[234:237], v[38:41]
	v_mfma_f32_16x16x32_bf16 v[14:17], v[168:171], v[234:237], v[14:17]
	v_mfma_f32_16x16x32_bf16 v[18:21], v[164:167], v[190:193], v[18:21]
	v_mfma_f32_16x16x32_bf16 v[130:133], v[182:185], v[190:193], v[130:133]
	v_mfma_f32_16x16x32_bf16 v[26:29], v[164:167], v[218:221], v[26:29]
	v_mfma_f32_16x16x32_bf16 v[6:9], v[182:185], v[218:221], v[6:9]
	v_mfma_f32_16x16x32_bf16 v[34:37], v[164:167], v[230:233], v[34:37]
	v_mfma_f32_16x16x32_bf16 v[10:13], v[182:185], v[230:233], v[10:13]
	v_mfma_f32_16x16x32_bf16 v[38:41], v[164:167], v[238:241], v[38:41]
	v_mfma_f32_16x16x32_bf16 v[14:17], v[182:185], v[238:241], v[14:17]
	s_barrier
	s_mov_b32 m0, s64
	v_lshl_add_u64 v[176:177], s[90:91], 0, v[134:135]
	v_lshl_add_u64 v[198:199], s[90:91], 0, v[74:75]
	s_add_u32 s90, s90, s12
	ds_read_b128 v[186:189], v143 offset:16384
	ds_read_b128 v[190:193], v143 offset:17408
	ds_read_b128 v[194:197], v143 offset:18432
	ds_read_b128 v[218:221], v143 offset:19456
	ds_read_b128 v[222:225], v143 offset:20480
	ds_read_b128 v[230:233], v143 offset:21504
	ds_read_b128 v[234:237], v143 offset:22528
	ds_read_b128 v[238:241], v143 offset:23552
	global_load_lds_dwordx4 v[176:177], off
	s_mov_b32 m0, s65
	s_addc_u32 s91, s91, s13
	global_load_lds_dwordx4 v[198:199], off
	v_lshl_add_u64 v[242:243], s[90:91], 0, v[134:135]
	s_mov_b32 m0, s67
	v_lshl_add_u64 v[244:245], s[90:91], 0, v[74:75]
	global_load_lds_dwordx4 v[242:243], off
	s_mov_b32 m0, s68
	v_lshl_add_u64 v[246:247], s[34:35], 0, v[136:137]
	global_load_lds_dwordx4 v[244:245], off
	s_mov_b32 m0, s69
	v_lshl_add_u64 v[248:249], s[34:35], 0, v[76:77]
	global_load_lds_dwordx4 v[246:247], off
	s_mov_b32 m0, s70
	s_nop 0
	global_load_lds_dwordx4 v[248:249], off
	s_waitcnt vmcnt(8)
	s_waitcnt lgkmcnt(0)
	s_barrier
	s_waitcnt lgkmcnt(0)
	v_mfma_f32_16x16x32_bf16 v[102:105], v[144:147], v[186:189], v[102:105]
	v_mfma_f32_16x16x32_bf16 v[70:73], v[152:155], v[186:189], v[70:73]
	v_mfma_f32_16x16x32_bf16 v[114:117], v[144:147], v[194:197], v[114:117]
	v_mfma_f32_16x16x32_bf16 v[90:93], v[152:155], v[194:197], v[90:93]
	v_mfma_f32_16x16x32_bf16 v[126:129], v[144:147], v[222:225], v[126:129]
	v_mfma_f32_16x16x32_bf16 v[110:113], v[152:155], v[222:225], v[110:113]
	v_mfma_f32_16x16x32_bf16 v[122:125], v[144:147], v[234:237], v[122:125]
	v_mfma_f32_16x16x32_bf16 v[118:121], v[152:155], v[234:237], v[118:121]
	v_mfma_f32_16x16x32_bf16 v[102:105], v[148:151], v[190:193], v[102:105]
	v_mfma_f32_16x16x32_bf16 v[70:73], v[156:159], v[190:193], v[70:73]
	v_mfma_f32_16x16x32_bf16 v[114:117], v[148:151], v[218:221], v[114:117]
	v_mfma_f32_16x16x32_bf16 v[90:93], v[156:159], v[218:221], v[90:93]
	v_mfma_f32_16x16x32_bf16 v[126:129], v[148:151], v[230:233], v[126:129]
	v_mfma_f32_16x16x32_bf16 v[110:113], v[156:159], v[230:233], v[110:113]
	v_mfma_f32_16x16x32_bf16 v[122:125], v[148:151], v[238:241], v[122:125]
	v_mfma_f32_16x16x32_bf16 v[118:121], v[156:159], v[238:241], v[118:121]
	v_mfma_f32_16x16x32_bf16 v[46:49], v[160:163], v[186:189], v[46:49]
	v_mfma_f32_16x16x32_bf16 v[22:25], v[168:171], v[186:189], v[22:25]
	v_mfma_f32_16x16x32_bf16 v[58:61], v[160:163], v[194:197], v[58:61]
	v_mfma_f32_16x16x32_bf16 v[30:33], v[168:171], v[194:197], v[30:33]
	v_mfma_f32_16x16x32_bf16 v[82:85], v[160:163], v[222:225], v[82:85]
	v_mfma_f32_16x16x32_bf16 v[50:53], v[168:171], v[222:225], v[50:53]
	v_mfma_f32_16x16x32_bf16 v[106:109], v[160:163], v[234:237], v[106:109]
	v_mfma_f32_16x16x32_bf16 v[78:81], v[168:171], v[234:237], v[78:81]
	v_mfma_f32_16x16x32_bf16 v[46:49], v[164:167], v[190:193], v[46:49]
	v_mfma_f32_16x16x32_bf16 v[22:25], v[182:185], v[190:193], v[22:25]
	v_mfma_f32_16x16x32_bf16 v[58:61], v[164:167], v[218:221], v[58:61]
	v_mfma_f32_16x16x32_bf16 v[30:33], v[182:185], v[218:221], v[30:33]
	v_mfma_f32_16x16x32_bf16 v[82:85], v[164:167], v[230:233], v[82:85]
	v_mfma_f32_16x16x32_bf16 v[50:53], v[182:185], v[230:233], v[50:53]
	v_mfma_f32_16x16x32_bf16 v[106:109], v[164:167], v[238:241], v[106:109]
	v_mfma_f32_16x16x32_bf16 v[78:81], v[182:185], v[238:241], v[78:81]
	s_barrier
	v_add_u32_e32 v0, s73, v142
	ds_read_b128 v[144:147], v0
	ds_read_b128 v[148:151], v0 offset:1024
	ds_read_b128 v[152:155], v0 offset:2048
	ds_read_b128 v[156:159], v0 offset:3072
	v_add_u32_e32 v0, s78, v142
	ds_read_b128 v[160:163], v0
	ds_read_b128 v[164:167], v0 offset:1024
	ds_read_b128 v[168:171], v0 offset:2048
	ds_read_b128 v[182:185], v0 offset:3072
	s_add_u32 s34, s34, s10
	s_addc_u32 s35, s35, s11
	s_mov_b32 m0, s71
	v_lshl_add_u64 v[250:251], s[34:35], 0, v[136:137]
	ds_read_b128 v[186:189], v143 offset:32768
	ds_read_b128 v[190:193], v143 offset:33792
	ds_read_b128 v[194:197], v143 offset:34816
	ds_read_b128 v[218:221], v143 offset:35840
	ds_read_b128 v[222:225], v143 offset:36864
	ds_read_b128 v[230:233], v143 offset:37888
	ds_read_b128 v[234:237], v143 offset:38912
	ds_read_b128 v[238:241], v143 offset:39936
	global_load_lds_dwordx4 v[250:251], off
	v_lshl_add_u64 v[250:251], s[34:35], 0, v[76:77]
	s_mov_b32 m0, s72
	s_nop 0
	global_load_lds_dwordx4 v[250:251], off
	s_waitcnt vmcnt(8)
	s_waitcnt lgkmcnt(0)
	s_barrier
	s_waitcnt lgkmcnt(0)
	v_mfma_f32_16x16x32_bf16 v[2:5], v[144:147], v[186:189], v[2:5]
	v_mfma_f32_16x16x32_bf16 v[42:45], v[152:155], v[186:189], v[42:45]
	v_mfma_f32_16x16x32_bf16 v[86:89], v[144:147], v[194:197], v[86:89]
	v_mfma_f32_16x16x32_bf16 v[54:57], v[152:155], v[194:197], v[54:57]
	v_mfma_f32_16x16x32_bf16 v[94:97], v[144:147], v[222:225], v[94:97]
	v_mfma_f32_16x16x32_bf16 v[62:65], v[152:155], v[222:225], v[62:65]
	v_mfma_f32_16x16x32_bf16 v[98:101], v[144:147], v[234:237], v[98:101]
	v_mfma_f32_16x16x32_bf16 v[66:69], v[152:155], v[234:237], v[66:69]
	v_mfma_f32_16x16x32_bf16 v[2:5], v[148:151], v[190:193], v[2:5]
	v_mfma_f32_16x16x32_bf16 v[42:45], v[156:159], v[190:193], v[42:45]
	v_mfma_f32_16x16x32_bf16 v[86:89], v[148:151], v[218:221], v[86:89]
	v_mfma_f32_16x16x32_bf16 v[54:57], v[156:159], v[218:221], v[54:57]
	v_mfma_f32_16x16x32_bf16 v[94:97], v[148:151], v[230:233], v[94:97]
	v_mfma_f32_16x16x32_bf16 v[62:65], v[156:159], v[230:233], v[62:65]
	v_mfma_f32_16x16x32_bf16 v[98:101], v[148:151], v[238:241], v[98:101]
	v_mfma_f32_16x16x32_bf16 v[66:69], v[156:159], v[238:241], v[66:69]
	v_mfma_f32_16x16x32_bf16 v[18:21], v[160:163], v[186:189], v[18:21]
	v_mfma_f32_16x16x32_bf16 v[130:133], v[168:171], v[186:189], v[130:133]
	v_mfma_f32_16x16x32_bf16 v[26:29], v[160:163], v[194:197], v[26:29]
	v_mfma_f32_16x16x32_bf16 v[6:9], v[168:171], v[194:197], v[6:9]
	v_mfma_f32_16x16x32_bf16 v[34:37], v[160:163], v[222:225], v[34:37]
	v_mfma_f32_16x16x32_bf16 v[10:13], v[168:171], v[222:225], v[10:13]
	v_mfma_f32_16x16x32_bf16 v[38:41], v[160:163], v[234:237], v[38:41]
	v_mfma_f32_16x16x32_bf16 v[14:17], v[168:171], v[234:237], v[14:17]
	v_mfma_f32_16x16x32_bf16 v[18:21], v[164:167], v[190:193], v[18:21]
	v_mfma_f32_16x16x32_bf16 v[130:133], v[182:185], v[190:193], v[130:133]
	v_mfma_f32_16x16x32_bf16 v[26:29], v[164:167], v[218:221], v[26:29]
	v_mfma_f32_16x16x32_bf16 v[6:9], v[182:185], v[218:221], v[6:9]
	v_mfma_f32_16x16x32_bf16 v[34:37], v[164:167], v[230:233], v[34:37]
	v_mfma_f32_16x16x32_bf16 v[10:13], v[182:185], v[230:233], v[10:13]
	v_mfma_f32_16x16x32_bf16 v[38:41], v[164:167], v[238:241], v[38:41]
	v_mfma_f32_16x16x32_bf16 v[14:17], v[182:185], v[238:241], v[14:17]
	s_barrier
	s_mov_b32 m0, s74
	v_lshl_add_u64 v[176:177], v[176:177], 0, s[48:49]
	ds_read_b128 v[186:189], v143 offset:49152
	ds_read_b128 v[190:193], v143 offset:50176
	ds_read_b128 v[194:197], v143 offset:51200
	ds_read_b128 v[218:221], v143 offset:52224
	ds_read_b128 v[222:225], v143 offset:53248
	ds_read_b128 v[230:233], v143 offset:54272
	ds_read_b128 v[234:237], v143 offset:55296
	ds_read_b128 v[238:241], v143 offset:56320
	global_load_lds_dwordx4 v[176:177], off
	v_lshl_add_u64 v[176:177], v[198:199], 0, s[48:49]
	s_mov_b32 m0, s75
	s_nop 0
	global_load_lds_dwordx4 v[176:177], off
	v_lshl_add_u64 v[176:177], v[242:243], 0, s[48:49]
	s_mov_b32 m0, s79
	s_nop 0
	global_load_lds_dwordx4 v[176:177], off
	v_lshl_add_u64 v[176:177], v[244:245], 0, s[48:49]
	s_mov_b32 m0, s80
	s_nop 0
	global_load_lds_dwordx4 v[176:177], off
	v_lshl_add_u64 v[176:177], v[246:247], 0, s[48:49]
	s_mov_b32 m0, s76
	s_nop 0
	global_load_lds_dwordx4 v[176:177], off
	v_lshl_add_u64 v[176:177], v[248:249], 0, s[48:49]
	s_mov_b32 m0, s77
	s_nop 0
	global_load_lds_dwordx4 v[176:177], off
	s_waitcnt vmcnt(8)
	s_waitcnt lgkmcnt(0)
	s_barrier
	s_waitcnt lgkmcnt(0)
	v_mfma_f32_16x16x32_bf16 v[102:105], v[144:147], v[186:189], v[102:105]
	v_mfma_f32_16x16x32_bf16 v[70:73], v[152:155], v[186:189], v[70:73]
	v_mfma_f32_16x16x32_bf16 v[114:117], v[144:147], v[194:197], v[114:117]
	v_mfma_f32_16x16x32_bf16 v[90:93], v[152:155], v[194:197], v[90:93]
	v_mfma_f32_16x16x32_bf16 v[126:129], v[144:147], v[222:225], v[126:129]
	v_mfma_f32_16x16x32_bf16 v[110:113], v[152:155], v[222:225], v[110:113]
	v_mfma_f32_16x16x32_bf16 v[122:125], v[144:147], v[234:237], v[122:125]
	v_mfma_f32_16x16x32_bf16 v[118:121], v[152:155], v[234:237], v[118:121]
	v_mfma_f32_16x16x32_bf16 v[102:105], v[148:151], v[190:193], v[102:105]
	v_mfma_f32_16x16x32_bf16 v[70:73], v[156:159], v[190:193], v[70:73]
	v_mfma_f32_16x16x32_bf16 v[114:117], v[148:151], v[218:221], v[114:117]
	v_mfma_f32_16x16x32_bf16 v[90:93], v[156:159], v[218:221], v[90:93]
	v_mfma_f32_16x16x32_bf16 v[126:129], v[148:151], v[230:233], v[126:129]
	v_mfma_f32_16x16x32_bf16 v[110:113], v[156:159], v[230:233], v[110:113]
	v_mfma_f32_16x16x32_bf16 v[122:125], v[148:151], v[238:241], v[122:125]
	v_mfma_f32_16x16x32_bf16 v[118:121], v[156:159], v[238:241], v[118:121]
	v_mfma_f32_16x16x32_bf16 v[46:49], v[160:163], v[186:189], v[46:49]
	v_mfma_f32_16x16x32_bf16 v[22:25], v[168:171], v[186:189], v[22:25]
	v_mfma_f32_16x16x32_bf16 v[58:61], v[160:163], v[194:197], v[58:61]
	v_mfma_f32_16x16x32_bf16 v[30:33], v[168:171], v[194:197], v[30:33]
	v_mfma_f32_16x16x32_bf16 v[82:85], v[160:163], v[222:225], v[82:85]
	v_mfma_f32_16x16x32_bf16 v[50:53], v[168:171], v[222:225], v[50:53]
	v_mfma_f32_16x16x32_bf16 v[106:109], v[160:163], v[234:237], v[106:109]
	v_mfma_f32_16x16x32_bf16 v[78:81], v[168:171], v[234:237], v[78:81]
	v_mfma_f32_16x16x32_bf16 v[46:49], v[164:167], v[190:193], v[46:49]
	v_mfma_f32_16x16x32_bf16 v[22:25], v[182:185], v[190:193], v[22:25]
	v_mfma_f32_16x16x32_bf16 v[58:61], v[164:167], v[218:221], v[58:61]
	v_mfma_f32_16x16x32_bf16 v[30:33], v[182:185], v[218:221], v[30:33]
	v_mfma_f32_16x16x32_bf16 v[82:85], v[164:167], v[230:233], v[82:85]
	v_mfma_f32_16x16x32_bf16 v[50:53], v[182:185], v[230:233], v[50:53]
	v_mfma_f32_16x16x32_bf16 v[106:109], v[164:167], v[238:241], v[106:109]
	v_mfma_f32_16x16x32_bf16 v[78:81], v[182:185], v[238:241], v[78:81]
	s_barrier
	s_add_u32 s87, s87, 0x100
	s_addc_u32 s88, s88, 0
	s_add_u32 s30, s30, 0x100
	s_addc_u32 s31, s31, 0
	s_cmp_ge_i32 s89, s81
	s_mov_b32 s34, s89
	s_cbranch_scc0 .LBB0_1401
	v_readlane_b32 s88, v252, 7
	v_readlane_b32 s89, v252, 8
	s_and_b64 vcc, exec, s[4:5]
	s_cbranch_vccnz .LBB0_1394
	s_branch .LBB0_1406

.LBB0_1512:
	s_mov_b32 s33, s45
	s_mov_b32 s16, 0
	s_mov_b32 s0, 0
	s_waitcnt lgkmcnt(0)
	s_barrier
	s_add_i32 s0, s0, 0x200e8
	v_mov_b32_e32 v0, s0
	s_mov_b32 s0, 0
	ds_read_b64 v[2:3], v0
	s_add_i32 s0, s0, 0x200e8
	v_mov_b32_e32 v0, s0
	s_movk_i32 s0, 0xb00
	s_movk_i32 s2, 0xb00
	s_movk_i32 s5, 0x400
	ds_read_b64 v[4:5], v0
	s_ashr_i32 s7, s5, 31
	s_lshr_b32 s7, s7, 24
	s_add_i32 s5, s5, s7
	s_ashr_i32 s5, s5, 8
	v_readlane_b32 s47, v252, 0
	s_lshl_b32 s8, s5, 6
	v_mov_b32_e32 v172, v200
	s_waitcnt lgkmcnt(0)
	v_readfirstlane_b32 s1, v3
	v_readfirstlane_b32 s3, v2
	v_readfirstlane_b32 s4, v5
	v_readfirstlane_b32 s6, v4
	s_cmp_ge_i32 s47, s8
	v_readfirstlane_b32 s37, v172
	s_cbranch_scc1 .LBB0_1634
	v_lshlrev_b32_e32 v2, 4, v172
	v_add_u32_e32 v3, 0x2000, v2
	v_ashrrev_i32_e32 v0, 31, v3
	v_lshrrev_b32_e32 v0, 22, v0
	v_add_u32_e32 v0, v3, v0
	v_ashrrev_i32_e32 v4, 10, v0
	v_mul_i32_i24_e32 v5, 0x400, v4
	v_sub_u32_e32 v3, v3, v5
	v_lshrrev_b32_e32 v5, 4, v3
	v_bitop3_b32 v3, v5, v3, 32 bitop3:0x6c
	v_ashrrev_i32_e32 v5, 31, v3
	v_lshrrev_b32_e32 v5, 26, v5
	v_add_u32_e32 v5, v3, v5
	v_ashrrev_i32_e32 v6, 6, v5
	v_and_b32_e32 v5, 0xc0, v5
	v_lshlrev_b32_e32 v0, 5, v4
	v_sub_u32_e32 v3, v3, v5
	v_lshlrev_b32_e32 v4, 3, v4
	v_ashrrev_i16_sdwa v3, v201, sext(v3) dst_sel:DWORD dst_unused:UNUSED_PAD src0_sel:DWORD src1_sel:BYTE_0
	v_and_b32_e32 v4, -16, v4
	v_and_b32_e32 v0, 32, v0
	v_bfe_i32 v14, v3, 0, 16
	v_add_u32_e32 v4, v6, v4
	v_add_u32_e32 v3, v0, v14
	v_mul_lo_u32 v5, v4, s0
	v_mul_lo_u32 v15, v4, s2
	v_add_lshl_u32 v74, v3, v5, 1
	v_add_lshl_u32 v76, v3, v15, 1
	v_ashrrev_i32_e32 v3, 31, v172
	v_lshrrev_b32_e32 v3, 26, v3
	v_add_u32_e32 v3, v172, v3
	v_ashrrev_i32_e32 v3, 6, v3
	v_lshlrev_b32_e32 v4, 5, v3
	v_and_b32_e32 v16, 32, v4
	v_bfe_i32 v4, v172, 27, 1
	v_lshrrev_b32_e32 v4, 22, v4
	v_add_u32_e32 v4, v2, v4
	v_and_b32_e32 v4, 0xfffffc00, v4
	v_sub_u32_e32 v2, v2, v4
	s_add_u32 s50, s3, 0xe3f0000
	v_lshrrev_b32_e32 v4, 4, v2
	s_addc_u32 s51, s1, 0
	v_bitop3_b32 v2, v4, v2, 32 bitop3:0x6c
	s_add_u32 s52, s6, 0x2670000
	v_ashrrev_i32_e32 v4, 31, v2
	s_addc_u32 s53, s4, 0
	v_lshrrev_b32_e32 v4, 26, v4
	s_ashr_i32 s55, s47, 31
	v_add_u32_e32 v4, v2, v4
	s_lshr_b32 s6, s55, 29
	v_ashrrev_i32_e32 v5, 6, v4
	v_and_b32_e32 v4, 0xc0, v4
	s_add_i32 s6, s47, s6
	s_ashr_i32 s7, s37, 6
	s_ashr_i32 s3, s2, 31
	s_ashr_i32 s1, s0, 31
	v_sub_u32_e32 v2, v2, v4
	v_lshlrev_b32_e32 v3, 3, v3
	s_lshl_b32 s54, s5, 3
	s_ashr_i32 s9, s6, 3
	s_and_b32 s6, s6, -8
	s_ashr_i32 s44, s37, 8
	s_lshl_b64 s[10:11], s[2:3], 8
	s_lshl_b64 s[12:13], s[0:1], 8
	s_lshl_b64 s[18:19], s[2:3], 9
	s_lshl_b64 s[20:21], s[0:1], 9
	s_lshl_b32 s4, s7, 10
	v_ashrrev_i16_sdwa v2, v201, sext(v2) dst_sel:DWORD dst_unused:UNUSED_PAD src0_sel:DWORD src1_sel:BYTE_0
	v_and_b32_e32 v3, -16, v3
	s_sub_i32 s6, s47, s6
	s_or_b32 s58, s54, 1
	v_bfe_i32 v17, v2, 0, 16
	v_add_u32_e32 v3, v5, v3
	s_cmp_lt_i32 s6, 0
	v_add_u32_e32 v2, v16, v17
	v_mul_lo_u32 v4, v3, s0
	v_mul_lo_u32 v18, v3, s2
	s_cselect_b32 s22, s58, s54
	s_abs_i32 s60, s54
	v_add_lshl_u32 v134, v2, v4, 1
	v_add_lshl_u32 v136, v2, v18, 1
	v_cvt_f32_u32_e32 v2, s60
	s_mul_i32 s6, s22, s6
	s_sub_i32 s22, 0, s60
	s_add_i32 s6, s6, s9
	v_rcp_iflag_f32_e32 v2, v2
	s_ashr_i32 s9, s6, 31
	s_bfe_i32 s59, s5, 0x1001c
	s_xor_b32 s5, s9, s59
	v_mul_f32_e32 v2, 0x4f7ffffe, v2
	v_cvt_u32_f32_e32 v2, v2
	s_abs_i32 s9, s6
	v_mov_b32_e32 v135, v1
	v_mov_b32_e32 v75, v1
	v_readfirstlane_b32 s61, v2
	s_mul_i32 s22, s22, s61
	s_mul_hi_u32 s22, s61, s22
	s_add_i32 s61, s61, s22
	s_mul_hi_u32 s22, s9, s61
	s_mul_i32 s23, s22, s60
	s_sub_i32 s9, s9, s23
	s_add_i32 s23, s22, 1
	s_sub_i32 s24, s9, s60
	s_cmp_ge_u32 s9, s60
	s_cselect_b32 s22, s23, s22
	s_cselect_b32 s9, s24, s9
	s_add_i32 s23, s22, 1
	s_cmp_ge_u32 s9, s60
	s_cselect_b32 s9, s23, s22
	s_xor_b32 s9, s9, s5
	s_sub_i32 s5, s9, s5
	s_lshl_b32 s9, s5, 3
	s_sub_i32 s22, 64, s9
	s_min_i32 s22, s22, 8
	s_abs_i32 s24, s22
	v_cvt_f32_u32_e32 v2, s24
	s_sub_i32 s25, 0, s24
	s_mul_i32 s5, s5, s54
	s_sub_i32 s5, s6, s5
	v_rcp_iflag_f32_e32 v2, v2
	s_abs_i32 s23, s5
	s_xor_b32 s6, s5, s22
	s_ashr_i32 s6, s6, 31
	v_mul_f32_e32 v2, 0x4f7ffffe, v2
	v_cvt_u32_f32_e32 v2, v2
	v_mov_b32_e32 v137, v1
	v_mov_b32_e32 v77, v1
	v_readfirstlane_b32 s26, v2
	s_mul_i32 s25, s25, s26
	s_mul_hi_u32 s25, s26, s25
	s_add_i32 s26, s26, s25
	s_mul_hi_u32 s25, s23, s26
	s_mul_i32 s26, s25, s24
	s_sub_i32 s23, s23, s26
	s_add_i32 s26, s25, 1
	s_sub_i32 s27, s23, s24
	s_cmp_ge_u32 s23, s24
	s_cselect_b32 s25, s26, s25
	s_cselect_b32 s23, s27, s23
	s_add_i32 s26, s25, 1
	s_cmp_ge_u32 s23, s24
	s_cselect_b32 s23, s26, s25
	s_xor_b32 s23, s23, s6
	s_sub_i32 s6, s23, s6
	s_mul_i32 s22, s6, s22
	s_sub_i32 s5, s5, s22
	s_add_i32 s62, s5, s9
	s_ashr_i32 s5, s62, 31
	s_mul_i32 s5, s18, s5
	s_mul_hi_u32 s9, s18, s62
	s_lshr_b64 s[2:3], s[2:3], 23
	s_add_i32 s5, s9, s5
	s_mul_i32 s2, s2, s62
	s_add_i32 s5, s5, s2
	s_ashr_i32 s2, s6, 31
	s_mul_i32 s2, s20, s2
	s_mul_hi_u32 s3, s20, s6
	s_add_i32 s22, s3, s2
	s_lshr_b64 s[2:3], s[0:1], 23
	s_mul_i32 s2, s2, s6
	s_add_i32 s2, s22, s2
	s_mul_i32 s3, s20, s6
	s_add_u32 s22, s52, s3
	s_addc_u32 s23, s53, s2
	s_add_i32 s63, s16, 0x10000
	s_add_i32 s64, s63, s4
	s_add_i32 s65, s64, 0x2000
	s_add_u32 s2, s22, s12
	s_addc_u32 s3, s23, s13
	s_add_i32 s66, s16, 0x14000
	s_add_i32 s67, s66, s4
	s_mul_i32 s9, s18, s62
	s_mov_b32 m0, s64
	s_add_i32 s68, s67, 0x2000
	global_load_lds_dwordx4 v134, s[22:23]
	s_mov_b32 m0, s65
	s_add_u32 s24, s50, s9
	global_load_lds_dwordx4 v74, s[22:23]
	s_mov_b32 m0, s67
	s_addc_u32 s25, s51, s5
	s_add_i32 s69, s16, s4
	global_load_lds_dwordx4 v134, s[2:3]
	s_mov_b32 m0, s68
	s_add_i32 s70, s69, 0x2000
	v_lshl_add_u64 v[6:7], s[2:3], 0, v[134:135]
	v_lshl_add_u64 v[8:9], s[2:3], 0, v[74:75]
	global_load_lds_dwordx4 v74, s[2:3]
	s_mov_b32 m0, s69
	s_add_u32 s2, s24, s10
	global_load_lds_dwordx4 v136, s[24:25]
	s_mov_b32 m0, s70
	s_addc_u32 s3, s25, s11
	s_add_i32 s71, s69, 0x4000
	global_load_lds_dwordx4 v76, s[24:25]
	s_mov_b32 m0, s71
	s_add_i32 s72, s69, 0x6000
	global_load_lds_dwordx4 v136, s[2:3]
	s_mov_b32 m0, s72
	v_lshl_add_u64 v[2:3], s[22:23], 0, v[134:135]
	global_load_lds_dwordx4 v76, s[2:3]
	v_lshl_add_u64 v[4:5], s[22:23], 0, v[74:75]
	v_lshl_add_u64 v[10:11], s[24:25], 0, v[136:137]
	v_lshl_add_u64 v[12:13], s[24:25], 0, v[76:77]
	s_cmp_lg_u32 s44, 1
	s_cbranch_scc1 .LBB0_1515
	s_barrier
	s_setprio 1

.LBB0_1635:
	s_mov_b32 s0, s45
	s_add_i32 s0, s0, 0x200e8
	v_mov_b32_e32 v0, s0
	ds_read_b64 v[2:3], v0
	s_mov_b32 s16, 0
	s_setprio 0
	s_getreg_b32 s0, hwreg(HW_REG_XCC_ID, 0, 4)
	s_waitcnt vmcnt(0)
	s_waitcnt lgkmcnt(0)
	v_readfirstlane_b32 s69, v3
	v_readfirstlane_b32 s68, v2
	s_barrier
	s_mov_b64 s[64:65], exec
	v_readlane_b32 s2, v252, 1
	v_readlane_b32 s3, v252, 2
	s_and_b64 s[2:3], s[64:65], s[2:3]
	s_mov_b64 exec, s[2:3]
	s_cbranch_execz .LBB0_1679
	s_add_i32 s15, s16, 0x20200
	v_mov_b32_e32 v0, s15
	s_waitcnt vmcnt(0) expcnt(0) lgkmcnt(0)
	ds_read_b32 v2, v0
	s_add_i32 s16, s16, 0x20204
	v_mov_b32_e32 v0, s16
	ds_read_b32 v0, v0
	s_and_b32 s14, s0, 15
	s_waitcnt lgkmcnt(1)
	v_cmp_ne_u32_e32 vcc, 0, v2
	s_cbranch_vccnz .LBB0_1650
	s_add_u32 s0, s68, 0x1000
	s_addc_u32 s1, s69, 0
	s_add_u32 s2, s68, 0x1100
	s_addc_u32 s3, s69, 0
	s_add_u32 s4, s68, 0x1200
	s_addc_u32 s5, s69, 0
	s_add_u32 s6, s68, 0x1300
	s_addc_u32 s7, s69, 0
	s_mov_b32 s30, 1
	s_mov_b64 s[8:9], 0
	s_branch .LBB0_1640

.LBB0_1810:
	s_or_b64 exec, exec, s[0:1]
	s_mov_b32 s0, s45
	s_add_i32 s0, s0, 0x200e8
	v_mov_b32_e32 v0, s0
	ds_read_b64 v[2:3], v0
	s_mov_b32 s16, 0
	s_setprio 0
	s_getreg_b32 s0, hwreg(HW_REG_XCC_ID, 0, 4)
	s_waitcnt vmcnt(0)
	s_waitcnt lgkmcnt(0)
	v_readfirstlane_b32 s69, v3
	v_readfirstlane_b32 s68, v2
	s_barrier
	s_mov_b64 s[64:65], exec
	v_readlane_b32 s2, v252, 1
	v_readlane_b32 s3, v252, 2
	s_and_b64 s[2:3], s[64:65], s[2:3]
	s_mov_b64 exec, s[2:3]
	s_cbranch_execnz .LBB0_1811
	s_getpc_b64 s[98:99]
